# the two waits in front of each phase barrier merged into one s_waitcnt vmcnt(8) lgkmcnt(0)
# baseline (speedup 1.0000x reference)
; #define PG8_STAGE(bufoff, gbase, voff) do { _Pragma("unroll") for (int _i = 0; _i < 2; ++_i) \
;         __builtin_amdgcn_global_load_lds((const unsigned*)((const char*)(gbase) + (voff)[_i]), (PG8_LAS unsigned*)(lds + (bufoff) + ldsw + _i * 8192), 16, 0, 0); } while (0)
; #define PG8_LDA(dst, b, h) do { _Pragma("unroll") for (int m = 0; m < 4; ++m) _Pragma("unroll") for (int k = 0; k < 2; ++k) dst[m][k] = *(const PG8_LAS bf16x8*)(lds + PG8_SA(b, h) + aoff + m * 2048 + k * 1024); } while (0)
; #define PG8_LDB(dst, b, h) do { _Pragma("unroll") for (int n = 0; n < 2; ++n) _Pragma("unroll") for (int k = 0; k < 2; ++k) dst[n][k] = *(const PG8_LAS bf16x8*)(lds + PG8_SB(b, h) + boff + n * 2048 + k * 1024); } while (0)
; #define PG8_MMA(ai, bj, At, Bt) do { __builtin_amdgcn_s_setprio(1); _Pragma("unroll") for (int m = 0; m < 4; ++m) _Pragma("unroll") for (int n = 0; n < 2; ++n) _Pragma("unroll") for (int k = 0; k < 2; ++k) \
;         acc[ai][bj][m][n] = __builtin_amdgcn_mfma_f32_16x16x32_bf16(Bt[n][k], At[m][k], acc[ai][bj][m][n], 0, 0, 0); __builtin_amdgcn_s_setprio(0); } while (0)
; #define PG8_WAIT_V(n) asm volatile("s_waitcnt vmcnt(" #n ")" ::: "memory")
; #define PG8_WAIT_L(n) asm volatile("s_waitcnt lgkmcnt(" #n ")" ::: "memory")
; #define PG8_BAR __builtin_amdgcn_s_barrier()
; #define PG8_SCHED __builtin_amdgcn_sched_barrier(0)
; template <class Epi, class Sched, bool ALIGN_EPI = false, bool SP2 = false>
; __device__ __forceinline__ void gemm_phase(PG8_LAS unsigned char* lds, const Gemm g, const Sched& S, const Epi& E) {
;     ...
;             PG8_LDB(B0, 0, 0); PG8_LDB(B1, 0, 1); PG8_SCHED; PG8_LDA(At, 0, 0); PG8_STAGE(PG8_SA(1, 1), a1 + hstep, voffA);
;             PG8_WAIT_V(8); PG8_WAIT_L(0); PG8_BAR; PG8_MMA(0, 0, At, B0); PG8_MMA(0, 1, At, B1); PG8_BAR; PG8_SCHED;
;             PG8_LDA(At, 0, 1); PG8_STAGE(PG8_SB(0, 0), b2, voffB); PG8_STAGE(PG8_SB(0, 1), b2 + hstep, voffB); PG8_STAGE(PG8_SA(0, 0), a2, voffA);
;             PG8_WAIT_V(8); PG8_WAIT_L(0); PG8_BAR; PG8_MMA(1, 0, At, B0); PG8_MMA(1, 1, At, B1); PG8_BAR; PG8_SCHED;
.LBB0_96:
	ds_read_b128 v[128:131], v178
	ds_read_b128 v[132:135], v178 offset:1024
	ds_read_b128 v[136:139], v178 offset:2048
	ds_read_b128 v[140:143], v178 offset:3072
	ds_read_b128 v[166:169], v179
	ds_read_b128 v[170:173], v179 offset:1024
	ds_read_b128 v[190:193], v179 offset:2048
	ds_read_b128 v[194:197], v179 offset:3072
	s_add_u32 s36, s80, 0xfffc0080
	s_addc_u32 s37, s81, -1
	s_cmp_eq_u32 s35, 12
	s_cselect_b32 s87, s8, s37
	s_cselect_b32 s86, s55, s36
	s_cselect_b32 s83, s49, s34
	s_cselect_b32 s82, vcc_lo, vcc_hi
	s_add_i32 m0, s93, 0xc000
	ds_read_b128 v[198:201], v181
	ds_read_b128 v[202:205], v181 offset:1024
	ds_read_b128 v[206:209], v181 offset:2048
	ds_read_b128 v[210:213], v181 offset:3072
	ds_read_b128 v[214:217], v181 offset:4096
	ds_read_b128 v[218:221], v181 offset:5120
	ds_read_b128 v[222:225], v181 offset:6144
	ds_read_b128 v[226:229], v181 offset:7168
	global_load_lds_dwordx4 v158, s[80:81]
	s_add_i32 m0, s93, 0xe000
	s_nop 0
	global_load_lds_dwordx4 v160, s[80:81]
	s_waitcnt vmcnt(8) lgkmcnt(0)
	s_barrier
	s_setprio 1
	v_mfma_f32_16x16x32_bf16 v[124:127], v[128:131], v[198:201], v[124:127]
	v_mfma_f32_16x16x32_bf16 v[120:123], v[136:139], v[198:201], v[120:123]
	v_mfma_f32_16x16x32_bf16 v[108:111], v[128:131], v[206:209], v[108:111]
	v_mfma_f32_16x16x32_bf16 v[104:107], v[136:139], v[206:209], v[104:107]
	v_mfma_f32_16x16x32_bf16 v[92:95], v[128:131], v[214:217], v[92:95]
	v_mfma_f32_16x16x32_bf16 v[88:91], v[136:139], v[214:217], v[88:91]
	v_mfma_f32_16x16x32_bf16 v[76:79], v[128:131], v[222:225], v[76:79]
	v_mfma_f32_16x16x32_bf16 v[72:75], v[136:139], v[222:225], v[72:75]
	v_mfma_f32_16x16x32_bf16 v[124:127], v[132:135], v[202:205], v[124:127]
	v_mfma_f32_16x16x32_bf16 v[120:123], v[140:143], v[202:205], v[120:123]
	v_mfma_f32_16x16x32_bf16 v[108:111], v[132:135], v[210:213], v[108:111]
	v_mfma_f32_16x16x32_bf16 v[104:107], v[140:143], v[210:213], v[104:107]
	v_mfma_f32_16x16x32_bf16 v[92:95], v[132:135], v[218:221], v[92:95]
	v_mfma_f32_16x16x32_bf16 v[88:91], v[140:143], v[218:221], v[88:91]
	v_mfma_f32_16x16x32_bf16 v[76:79], v[132:135], v[226:229], v[76:79]
	v_mfma_f32_16x16x32_bf16 v[72:75], v[140:143], v[226:229], v[72:75]
	v_mfma_f32_16x16x32_bf16 v[116:119], v[166:169], v[198:201], v[116:119]
	v_mfma_f32_16x16x32_bf16 v[112:115], v[190:193], v[198:201], v[112:115]
	v_mfma_f32_16x16x32_bf16 v[100:103], v[166:169], v[206:209], v[100:103]
	v_mfma_f32_16x16x32_bf16 v[96:99], v[190:193], v[206:209], v[96:99]
	v_mfma_f32_16x16x32_bf16 v[84:87], v[166:169], v[214:217], v[84:87]
	v_mfma_f32_16x16x32_bf16 v[80:83], v[190:193], v[214:217], v[80:83]
	v_mfma_f32_16x16x32_bf16 v[68:71], v[166:169], v[222:225], v[68:71]
	v_mfma_f32_16x16x32_bf16 v[64:67], v[190:193], v[222:225], v[64:67]
	v_mfma_f32_16x16x32_bf16 v[116:119], v[170:173], v[202:205], v[116:119]
	v_mfma_f32_16x16x32_bf16 v[112:115], v[194:197], v[202:205], v[112:115]
	v_mfma_f32_16x16x32_bf16 v[100:103], v[170:173], v[210:213], v[100:103]
	v_mfma_f32_16x16x32_bf16 v[96:99], v[194:197], v[210:213], v[96:99]
	v_mfma_f32_16x16x32_bf16 v[84:87], v[170:173], v[218:221], v[84:87]
	v_mfma_f32_16x16x32_bf16 v[80:83], v[194:197], v[218:221], v[80:83]
	v_mfma_f32_16x16x32_bf16 v[68:71], v[170:173], v[226:229], v[68:71]
	v_mfma_f32_16x16x32_bf16 v[64:67], v[194:197], v[226:229], v[64:67]
	s_setprio 0
	s_barrier
	s_add_i32 s36, s23, s90
	v_lshl_add_u64 v[174:175], s[82:83], 0, v[148:149]
	s_mov_b32 m0, s36
	ds_read_b128 v[198:201], v181 offset:16384
	ds_read_b128 v[202:205], v181 offset:17408
	ds_read_b128 v[206:209], v181 offset:18432
	ds_read_b128 v[210:213], v181 offset:19456
	ds_read_b128 v[214:217], v181 offset:20480
	ds_read_b128 v[218:221], v181 offset:21504
	ds_read_b128 v[222:225], v181 offset:22528
	ds_read_b128 v[226:229], v181 offset:23552
	global_load_lds_dwordx4 v[174:175], off
	s_add_i32 m0, s36, 0x2000
	s_add_u32 s36, s82, 0x40000
	v_lshl_add_u64 v[186:187], s[82:83], 0, v[144:145]
	s_addc_u32 s37, s83, 0
	s_add_i32 s20, s41, s90
	global_load_lds_dwordx4 v[186:187], off
	s_mov_b32 m0, s20
	v_lshl_add_u64 v[232:233], s[86:87], 0, v[146:147]
	global_load_lds_dwordx4 v148, s[36:37]
	s_add_i32 m0, s20, 0x2000
	s_nop 0
	global_load_lds_dwordx4 v144, s[36:37]
	v_lshl_add_u64 v[230:231], s[86:87], 0, v[150:151]
	s_mov_b32 m0, s93
	s_nop 0
	global_load_lds_dwordx4 v[230:231], off
	s_mov_b32 m0, s94
	s_nop 0
	global_load_lds_dwordx4 v[232:233], off
	s_waitcnt vmcnt(8) lgkmcnt(0)
	s_barrier
	s_setprio 1
	v_mfma_f32_16x16x32_bf16 v[60:63], v[128:131], v[198:201], v[60:63]
	v_mfma_f32_16x16x32_bf16 v[56:59], v[136:139], v[198:201], v[56:59]
	v_mfma_f32_16x16x32_bf16 v[44:47], v[128:131], v[206:209], v[44:47]
	v_mfma_f32_16x16x32_bf16 v[40:43], v[136:139], v[206:209], v[40:43]
	v_mfma_f32_16x16x32_bf16 v[28:31], v[128:131], v[214:217], v[28:31]
	v_mfma_f32_16x16x32_bf16 v[24:27], v[136:139], v[214:217], v[24:27]
	v_mfma_f32_16x16x32_bf16 v[12:15], v[128:131], v[222:225], v[12:15]
	v_mfma_f32_16x16x32_bf16 v[8:11], v[136:139], v[222:225], v[8:11]
	v_mfma_f32_16x16x32_bf16 v[60:63], v[132:135], v[202:205], v[60:63]
	v_mfma_f32_16x16x32_bf16 v[56:59], v[140:143], v[202:205], v[56:59]
	v_mfma_f32_16x16x32_bf16 v[44:47], v[132:135], v[210:213], v[44:47]
	v_mfma_f32_16x16x32_bf16 v[40:43], v[140:143], v[210:213], v[40:43]
	v_mfma_f32_16x16x32_bf16 v[28:31], v[132:135], v[218:221], v[28:31]
	v_mfma_f32_16x16x32_bf16 v[24:27], v[140:143], v[218:221], v[24:27]
	v_mfma_f32_16x16x32_bf16 v[12:15], v[132:135], v[226:229], v[12:15]
	v_mfma_f32_16x16x32_bf16 v[8:11], v[140:143], v[226:229], v[8:11]
	v_mfma_f32_16x16x32_bf16 v[52:55], v[166:169], v[198:201], v[52:55]
	v_mfma_f32_16x16x32_bf16 v[48:51], v[190:193], v[198:201], v[48:51]
	v_mfma_f32_16x16x32_bf16 v[36:39], v[166:169], v[206:209], v[36:39]
	v_mfma_f32_16x16x32_bf16 v[32:35], v[190:193], v[206:209], v[32:35]
	v_mfma_f32_16x16x32_bf16 v[20:23], v[166:169], v[214:217], v[20:23]
	v_mfma_f32_16x16x32_bf16 v[16:19], v[190:193], v[214:217], v[16:19]
	v_mfma_f32_16x16x32_bf16 v[4:7], v[166:169], v[222:225], v[4:7]
	v_mfma_f32_16x16x32_bf16 v[0:3], v[190:193], v[222:225], v[0:3]
	v_mfma_f32_16x16x32_bf16 v[52:55], v[170:173], v[202:205], v[52:55]
	v_mfma_f32_16x16x32_bf16 v[48:51], v[194:197], v[202:205], v[48:51]
	v_mfma_f32_16x16x32_bf16 v[36:39], v[170:173], v[210:213], v[36:39]
	v_mfma_f32_16x16x32_bf16 v[32:35], v[194:197], v[210:213], v[32:35]
	v_mfma_f32_16x16x32_bf16 v[20:23], v[170:173], v[218:221], v[20:23]
	v_mfma_f32_16x16x32_bf16 v[16:19], v[194:197], v[218:221], v[16:19]
	v_mfma_f32_16x16x32_bf16 v[4:7], v[170:173], v[226:229], v[4:7]
	v_mfma_f32_16x16x32_bf16 v[0:3], v[194:197], v[226:229], v[0:3]
	s_setprio 0
	s_barrier
; #define PG8_STAGE(bufoff, gbase, voff) do { _Pragma("unroll") for (int _i = 0; _i < 2; ++_i) \
;         __builtin_amdgcn_global_load_lds((const unsigned*)((const char*)(gbase) + (voff)[_i]), (PG8_LAS unsigned*)(lds + (bufoff) + ldsw + _i * 8192), 16, 0, 0); } while (0)
; #define PG8_LDA(dst, b, h) do { _Pragma("unroll") for (int m = 0; m < 4; ++m) _Pragma("unroll") for (int k = 0; k < 2; ++k) dst[m][k] = *(const PG8_LAS bf16x8*)(lds + PG8_SA(b, h) + aoff + m * 2048 + k * 1024); } while (0)
; #define PG8_LDB(dst, b, h) do { _Pragma("unroll") for (int n = 0; n < 2; ++n) _Pragma("unroll") for (int k = 0; k < 2; ++k) dst[n][k] = *(const PG8_LAS bf16x8*)(lds + PG8_SB(b, h) + boff + n * 2048 + k * 1024); } while (0)
; #define PG8_MMA(ai, bj, At, Bt) do { __builtin_amdgcn_s_setprio(1); _Pragma("unroll") for (int m = 0; m < 4; ++m) _Pragma("unroll") for (int n = 0; n < 2; ++n) _Pragma("unroll") for (int k = 0; k < 2; ++k) \
;         acc[ai][bj][m][n] = __builtin_amdgcn_mfma_f32_16x16x32_bf16(Bt[n][k], At[m][k], acc[ai][bj][m][n], 0, 0, 0); __builtin_amdgcn_s_setprio(0); } while (0)
; #define PG8_WAIT_V(n) asm volatile("s_waitcnt vmcnt(" #n ")" ::: "memory")
; #define PG8_WAIT_L(n) asm volatile("s_waitcnt lgkmcnt(" #n ")" ::: "memory")
; #define PG8_BAR __builtin_amdgcn_s_barrier()
; #define PG8_SCHED __builtin_amdgcn_sched_barrier(0)
; template <class Epi, class Sched, bool ALIGN_EPI = false, bool SP2 = false>
; __device__ __forceinline__ void gemm_phase(PG8_LAS unsigned char* lds, const Gemm g, const Sched& S, const Epi& E) {
;     ...
;             PG8_LDB(B0, 1, 0); PG8_LDB(B1, 1, 1); PG8_SCHED; PG8_LDA(At, 1, 0); PG8_STAGE(PG8_SA(0, 1), a2 + hstep, voffA);
;             PG8_WAIT_V(8); PG8_WAIT_L(0); PG8_BAR; PG8_MMA(0, 0, At, B0); PG8_MMA(0, 1, At, B1); PG8_BAR; PG8_SCHED;
;             PG8_LDA(At, 1, 1); PG8_STAGE(PG8_SB(1, 0), b3, voffB); PG8_STAGE(PG8_SB(1, 1), b3 + hstep, voffB); PG8_STAGE(PG8_SA(1, 0), a3, voffA);
;             PG8_WAIT_V(8); PG8_WAIT_L(0); PG8_BAR; PG8_MMA(1, 0, At, B0); PG8_MMA(1, 1, At, B1); PG8_BAR; PG8_SCHED;
	s_add_i32 s20, 0, 0x18000
	s_add_i32 s21, 0, 0x1c000
	v_add_u32_e32 v140, s20, v176
	v_add_u32_e32 v152, s21, v176
	ds_read_b128 v[128:131], v140
	ds_read_b128 v[132:135], v140 offset:1024
	ds_read_b128 v[136:139], v140 offset:2048
	ds_read_b128 v[140:143], v140 offset:3072
	ds_read_b128 v[166:169], v152
	ds_read_b128 v[170:173], v152 offset:1024
	ds_read_b128 v[190:193], v152 offset:2048
	ds_read_b128 v[194:197], v152 offset:3072
	s_add_u32 s36, s86, 0x40000
	s_addc_u32 s37, s87, 0
	s_mov_b32 m0, s95
	ds_read_b128 v[198:201], v181 offset:32768
	ds_read_b128 v[202:205], v181 offset:33792
	ds_read_b128 v[206:209], v181 offset:34816
	ds_read_b128 v[210:213], v181 offset:35840
	ds_read_b128 v[214:217], v181 offset:36864
	ds_read_b128 v[218:221], v181 offset:37888
	ds_read_b128 v[222:225], v181 offset:38912
	ds_read_b128 v[226:229], v181 offset:39936
	global_load_lds_dwordx4 v150, s[36:37]
	s_mov_b32 m0, s97
	s_nop 0
	global_load_lds_dwordx4 v146, s[36:37]
	s_waitcnt vmcnt(8) lgkmcnt(0)
	s_barrier
	s_setprio 1
	v_mfma_f32_16x16x32_bf16 v[124:127], v[128:131], v[198:201], v[124:127]
	v_mfma_f32_16x16x32_bf16 v[120:123], v[136:139], v[198:201], v[120:123]
	v_mfma_f32_16x16x32_bf16 v[108:111], v[128:131], v[206:209], v[108:111]
	v_mfma_f32_16x16x32_bf16 v[104:107], v[136:139], v[206:209], v[104:107]
	v_mfma_f32_16x16x32_bf16 v[92:95], v[128:131], v[214:217], v[92:95]
	v_mfma_f32_16x16x32_bf16 v[88:91], v[136:139], v[214:217], v[88:91]
	v_mfma_f32_16x16x32_bf16 v[76:79], v[128:131], v[222:225], v[76:79]
	v_mfma_f32_16x16x32_bf16 v[72:75], v[136:139], v[222:225], v[72:75]
	v_mfma_f32_16x16x32_bf16 v[124:127], v[132:135], v[202:205], v[124:127]
	v_mfma_f32_16x16x32_bf16 v[120:123], v[140:143], v[202:205], v[120:123]
	v_mfma_f32_16x16x32_bf16 v[108:111], v[132:135], v[210:213], v[108:111]
	v_mfma_f32_16x16x32_bf16 v[104:107], v[140:143], v[210:213], v[104:107]
	v_mfma_f32_16x16x32_bf16 v[92:95], v[132:135], v[218:221], v[92:95]
	v_mfma_f32_16x16x32_bf16 v[88:91], v[140:143], v[218:221], v[88:91]
	v_mfma_f32_16x16x32_bf16 v[76:79], v[132:135], v[226:229], v[76:79]
	v_mfma_f32_16x16x32_bf16 v[72:75], v[140:143], v[226:229], v[72:75]
	v_mfma_f32_16x16x32_bf16 v[116:119], v[166:169], v[198:201], v[116:119]
	v_mfma_f32_16x16x32_bf16 v[112:115], v[190:193], v[198:201], v[112:115]
	v_mfma_f32_16x16x32_bf16 v[100:103], v[166:169], v[206:209], v[100:103]
	v_mfma_f32_16x16x32_bf16 v[96:99], v[190:193], v[206:209], v[96:99]
	v_mfma_f32_16x16x32_bf16 v[84:87], v[166:169], v[214:217], v[84:87]
	v_mfma_f32_16x16x32_bf16 v[80:83], v[190:193], v[214:217], v[80:83]
	v_mfma_f32_16x16x32_bf16 v[68:71], v[166:169], v[222:225], v[68:71]
	v_mfma_f32_16x16x32_bf16 v[64:67], v[190:193], v[222:225], v[64:67]
	v_mfma_f32_16x16x32_bf16 v[116:119], v[170:173], v[202:205], v[116:119]
	v_mfma_f32_16x16x32_bf16 v[112:115], v[194:197], v[202:205], v[112:115]
	v_mfma_f32_16x16x32_bf16 v[100:103], v[170:173], v[210:213], v[100:103]
	v_mfma_f32_16x16x32_bf16 v[96:99], v[194:197], v[210:213], v[96:99]
	v_mfma_f32_16x16x32_bf16 v[84:87], v[170:173], v[218:221], v[84:87]
	v_mfma_f32_16x16x32_bf16 v[80:83], v[194:197], v[218:221], v[80:83]
	v_mfma_f32_16x16x32_bf16 v[68:71], v[170:173], v[226:229], v[68:71]
	v_mfma_f32_16x16x32_bf16 v[64:67], v[194:197], v[226:229], v[64:67]
	s_setprio 0
	s_barrier
	s_add_i32 s20, s20, s90
	v_lshl_add_u64 v[174:175], v[174:175], 0, s[26:27]
	s_mov_b32 m0, s20
	ds_read_b128 v[198:201], v181 offset:49152
	ds_read_b128 v[202:205], v181 offset:50176
	ds_read_b128 v[206:209], v181 offset:51200
	ds_read_b128 v[210:213], v181 offset:52224
	ds_read_b128 v[214:217], v181 offset:53248
	ds_read_b128 v[218:221], v181 offset:54272
	ds_read_b128 v[222:225], v181 offset:55296
	ds_read_b128 v[226:229], v181 offset:56320
	global_load_lds_dwordx4 v[174:175], off
	s_add_i32 m0, s20, 0x2000
	s_add_u32 s36, s82, 0x40080
	v_lshl_add_u64 v[174:175], v[186:187], 0, s[26:27]
	s_addc_u32 s37, s83, 0
	s_add_i32 s20, s21, s90
	global_load_lds_dwordx4 v[174:175], off
	s_mov_b32 m0, s20
	s_nop 0
	global_load_lds_dwordx4 v148, s[36:37]
	s_add_i32 m0, s20, 0x2000
	s_nop 0
	global_load_lds_dwordx4 v144, s[36:37]
	v_lshl_add_u64 v[174:175], v[230:231], 0, s[26:27]
	s_mov_b32 m0, s42
	s_nop 0
	global_load_lds_dwordx4 v[174:175], off
	v_lshl_add_u64 v[174:175], v[232:233], 0, s[26:27]
	s_mov_b32 m0, s43
	s_nop 0
	global_load_lds_dwordx4 v[174:175], off
	s_waitcnt vmcnt(8) lgkmcnt(0)
	s_barrier
	s_setprio 1
	v_mfma_f32_16x16x32_bf16 v[60:63], v[128:131], v[198:201], v[60:63]
	v_mfma_f32_16x16x32_bf16 v[56:59], v[136:139], v[198:201], v[56:59]
	v_mfma_f32_16x16x32_bf16 v[44:47], v[128:131], v[206:209], v[44:47]
	v_mfma_f32_16x16x32_bf16 v[40:43], v[136:139], v[206:209], v[40:43]
	v_mfma_f32_16x16x32_bf16 v[28:31], v[128:131], v[214:217], v[28:31]
	v_mfma_f32_16x16x32_bf16 v[24:27], v[136:139], v[214:217], v[24:27]
	v_mfma_f32_16x16x32_bf16 v[12:15], v[128:131], v[222:225], v[12:15]
	v_mfma_f32_16x16x32_bf16 v[8:11], v[136:139], v[222:225], v[8:11]
	v_mfma_f32_16x16x32_bf16 v[60:63], v[132:135], v[202:205], v[60:63]
	v_mfma_f32_16x16x32_bf16 v[56:59], v[140:143], v[202:205], v[56:59]
	v_mfma_f32_16x16x32_bf16 v[44:47], v[132:135], v[210:213], v[44:47]
	v_mfma_f32_16x16x32_bf16 v[40:43], v[140:143], v[210:213], v[40:43]
	v_mfma_f32_16x16x32_bf16 v[28:31], v[132:135], v[218:221], v[28:31]
	v_mfma_f32_16x16x32_bf16 v[24:27], v[140:143], v[218:221], v[24:27]
	v_mfma_f32_16x16x32_bf16 v[12:15], v[132:135], v[226:229], v[12:15]
	v_mfma_f32_16x16x32_bf16 v[8:11], v[140:143], v[226:229], v[8:11]
	v_mfma_f32_16x16x32_bf16 v[52:55], v[166:169], v[198:201], v[52:55]
	v_mfma_f32_16x16x32_bf16 v[48:51], v[190:193], v[198:201], v[48:51]
	v_mfma_f32_16x16x32_bf16 v[36:39], v[166:169], v[206:209], v[36:39]
	v_mfma_f32_16x16x32_bf16 v[32:35], v[190:193], v[206:209], v[32:35]
	v_mfma_f32_16x16x32_bf16 v[20:23], v[166:169], v[214:217], v[20:23]
	v_mfma_f32_16x16x32_bf16 v[16:19], v[190:193], v[214:217], v[16:19]
	v_mfma_f32_16x16x32_bf16 v[4:7], v[166:169], v[222:225], v[4:7]
	v_mfma_f32_16x16x32_bf16 v[0:3], v[190:193], v[222:225], v[0:3]
	v_mfma_f32_16x16x32_bf16 v[52:55], v[170:173], v[202:205], v[52:55]
	v_mfma_f32_16x16x32_bf16 v[48:51], v[194:197], v[202:205], v[48:51]
	v_mfma_f32_16x16x32_bf16 v[36:39], v[170:173], v[210:213], v[36:39]
	v_mfma_f32_16x16x32_bf16 v[32:35], v[194:197], v[210:213], v[32:35]
	v_mfma_f32_16x16x32_bf16 v[20:23], v[170:173], v[218:221], v[20:23]
	v_mfma_f32_16x16x32_bf16 v[16:19], v[194:197], v[218:221], v[16:19]
	v_mfma_f32_16x16x32_bf16 v[4:7], v[170:173], v[226:229], v[4:7]
	v_mfma_f32_16x16x32_bf16 v[0:3], v[194:197], v[226:229], v[0:3]
	s_setprio 0
	s_barrier
	s_add_i32 s35, s35, 2
	s_add_u32 s80, s80, 0x100
	s_addc_u32 s81, s81, 0
	s_add_u32 vcc_hi, vcc_hi, 0x100
	s_addc_u32 s34, s34, 0
	s_cmp_gt_u32 s35, 13
	s_cbranch_scc0 .LBB0_96
	s_and_b64 vcc, exec, s[28:29]
	s_cbranch_vccz .LBB0_99
	s_barrier

; #define PG8_STAGE(bufoff, gbase, voff) do { _Pragma("unroll") for (int _i = 0; _i < 2; ++_i) \
;         __builtin_amdgcn_global_load_lds((const unsigned*)((const char*)(gbase) + (voff)[_i]), (PG8_LAS unsigned*)(lds + (bufoff) + ldsw + _i * 8192), 16, 0, 0); } while (0)
; #define PG8_LDA(dst, b, h) do { _Pragma("unroll") for (int m = 0; m < 4; ++m) _Pragma("unroll") for (int k = 0; k < 2; ++k) dst[m][k] = *(const PG8_LAS bf16x8*)(lds + PG8_SA(b, h) + aoff + m * 2048 + k * 1024); } while (0)
; #define PG8_LDB(dst, b, h) do { _Pragma("unroll") for (int n = 0; n < 2; ++n) _Pragma("unroll") for (int k = 0; k < 2; ++k) dst[n][k] = *(const PG8_LAS bf16x8*)(lds + PG8_SB(b, h) + boff + n * 2048 + k * 1024); } while (0)
; #define PG8_MMA(ai, bj, At, Bt) do { __builtin_amdgcn_s_setprio(1); _Pragma("unroll") for (int m = 0; m < 4; ++m) _Pragma("unroll") for (int n = 0; n < 2; ++n) _Pragma("unroll") for (int k = 0; k < 2; ++k) \
;         acc[ai][bj][m][n] = __builtin_amdgcn_mfma_f32_16x16x32_bf16(Bt[n][k], At[m][k], acc[ai][bj][m][n], 0, 0, 0); __builtin_amdgcn_s_setprio(0); } while (0)
; #define PG8_WAIT_V(n) asm volatile("s_waitcnt vmcnt(" #n ")" ::: "memory")
; #define PG8_WAIT_L(n) asm volatile("s_waitcnt lgkmcnt(" #n ")" ::: "memory")
; #define PG8_BAR __builtin_amdgcn_s_barrier()
; #define PG8_SCHED __builtin_amdgcn_sched_barrier(0)
; template <class Epi, class Sched, bool ALIGN_EPI = false, bool SP2 = false>
; __device__ __forceinline__ void gemm_phase(PG8_LAS unsigned char* lds, const Gemm g, const Sched& S, const Epi& E) {
;     ...
;             PG8_LDB(B0, 0, 0); PG8_LDB(B1, 0, 1); PG8_SCHED; PG8_LDA(At, 0, 0); PG8_STAGE(PG8_SA(1, 1), a1 + hstep, voffA);
;             PG8_WAIT_V(8); PG8_WAIT_L(0); PG8_BAR; PG8_MMA(0, 0, At, B0); PG8_MMA(0, 1, At, B1); PG8_BAR; PG8_SCHED;
;             PG8_LDA(At, 0, 1); PG8_STAGE(PG8_SB(0, 0), b2, voffB); PG8_STAGE(PG8_SB(0, 1), b2 + hstep, voffB); PG8_STAGE(PG8_SA(0, 0), a2, voffA);
;             PG8_WAIT_V(8); PG8_WAIT_L(0); PG8_BAR; PG8_MMA(1, 0, At, B0); PG8_MMA(1, 1, At, B1); PG8_BAR; PG8_SCHED;
.LBB0_150:
	s_add_u32 s24, s22, 0xfffc0080
	s_addc_u32 s25, s23, -1
	s_waitcnt lgkmcnt(0)
	s_add_i32 s54, 0, 0x10000
	v_add_u32_e32 v147, s54, v152
	ds_read_b128 v[156:159], v147
	ds_read_b128 v[160:163], v147 offset:1024
	ds_read_b128 v[164:167], v147 offset:2048
	ds_read_b128 v[168:171], v147 offset:3072
	ds_read_b128 v[172:175], v154
	ds_read_b128 v[176:179], v154 offset:1024
	ds_read_b128 v[182:185], v154 offset:2048
	ds_read_b128 v[190:193], v154 offset:3072
	s_cmp_eq_u32 s49, 12
	s_cselect_b32 s27, s17, s25
	s_cselect_b32 s26, s45, s24
	s_cselect_b32 s25, s15, s48
	s_cselect_b32 s24, s46, s47
	s_add_i32 m0, s13, 0xc000
	ds_read_b128 v[194:197], v155
	ds_read_b128 v[198:201], v155 offset:1024
	ds_read_b128 v[202:205], v155 offset:2048
	ds_read_b128 v[206:209], v155 offset:3072
	ds_read_b128 v[210:213], v155 offset:4096
	ds_read_b128 v[214:217], v155 offset:5120
	ds_read_b128 v[218:221], v155 offset:6144
	ds_read_b128 v[222:225], v155 offset:7168
	global_load_lds_dwordx4 v138, s[22:23]
	s_add_i32 m0, s13, 0xe000
	s_nop 0
	global_load_lds_dwordx4 v140, s[22:23]
	s_waitcnt vmcnt(8) lgkmcnt(0)
	s_barrier
	s_setprio 1
	v_mfma_f32_16x16x32_bf16 v[124:127], v[156:159], v[194:197], v[124:127]
	v_mfma_f32_16x16x32_bf16 v[120:123], v[164:167], v[194:197], v[120:123]
	v_mfma_f32_16x16x32_bf16 v[116:119], v[156:159], v[202:205], v[116:119]
	v_mfma_f32_16x16x32_bf16 v[112:115], v[164:167], v[202:205], v[112:115]
	v_mfma_f32_16x16x32_bf16 v[100:103], v[156:159], v[210:213], v[100:103]
	v_mfma_f32_16x16x32_bf16 v[96:99], v[164:167], v[210:213], v[96:99]
	v_mfma_f32_16x16x32_bf16 v[84:87], v[156:159], v[218:221], v[84:87]
	v_mfma_f32_16x16x32_bf16 v[80:83], v[164:167], v[218:221], v[80:83]
	v_mfma_f32_16x16x32_bf16 v[124:127], v[160:163], v[198:201], v[124:127]
	v_mfma_f32_16x16x32_bf16 v[120:123], v[168:171], v[198:201], v[120:123]
	v_mfma_f32_16x16x32_bf16 v[116:119], v[160:163], v[206:209], v[116:119]
	v_mfma_f32_16x16x32_bf16 v[112:115], v[168:171], v[206:209], v[112:115]
	v_mfma_f32_16x16x32_bf16 v[100:103], v[160:163], v[214:217], v[100:103]
	v_mfma_f32_16x16x32_bf16 v[96:99], v[168:171], v[214:217], v[96:99]
	v_mfma_f32_16x16x32_bf16 v[84:87], v[160:163], v[222:225], v[84:87]
	v_mfma_f32_16x16x32_bf16 v[80:83], v[168:171], v[222:225], v[80:83]
	v_mfma_f32_16x16x32_bf16 v[108:111], v[172:175], v[194:197], v[108:111]
	v_mfma_f32_16x16x32_bf16 v[104:107], v[182:185], v[194:197], v[104:107]
	v_mfma_f32_16x16x32_bf16 v[92:95], v[172:175], v[202:205], v[92:95]
	v_mfma_f32_16x16x32_bf16 v[88:91], v[182:185], v[202:205], v[88:91]
	v_mfma_f32_16x16x32_bf16 v[76:79], v[172:175], v[210:213], v[76:79]
	v_mfma_f32_16x16x32_bf16 v[72:75], v[182:185], v[210:213], v[72:75]
	v_mfma_f32_16x16x32_bf16 v[68:71], v[172:175], v[218:221], v[68:71]
	v_mfma_f32_16x16x32_bf16 v[64:67], v[182:185], v[218:221], v[64:67]
	v_mfma_f32_16x16x32_bf16 v[108:111], v[176:179], v[198:201], v[108:111]
	v_mfma_f32_16x16x32_bf16 v[104:107], v[190:193], v[198:201], v[104:107]
	v_mfma_f32_16x16x32_bf16 v[92:95], v[176:179], v[206:209], v[92:95]
	v_mfma_f32_16x16x32_bf16 v[88:91], v[190:193], v[206:209], v[88:91]
	v_mfma_f32_16x16x32_bf16 v[76:79], v[176:179], v[214:217], v[76:79]
	v_mfma_f32_16x16x32_bf16 v[72:75], v[190:193], v[214:217], v[72:75]
	v_mfma_f32_16x16x32_bf16 v[68:71], v[176:179], v[222:225], v[68:71]
	v_mfma_f32_16x16x32_bf16 v[64:67], v[190:193], v[222:225], v[64:67]
	s_setprio 0
	s_barrier
	s_add_i32 s54, s54, s31
	v_lshl_add_u64 v[186:187], s[24:25], 0, v[130:131]
	s_mov_b32 m0, s54
	ds_read_b128 v[194:197], v155 offset:16384
	ds_read_b128 v[198:201], v155 offset:17408
	ds_read_b128 v[202:205], v155 offset:18432
	ds_read_b128 v[206:209], v155 offset:19456
	ds_read_b128 v[210:213], v155 offset:20480
	ds_read_b128 v[214:217], v155 offset:21504
	ds_read_b128 v[218:221], v155 offset:22528
	ds_read_b128 v[222:225], v155 offset:23552
	global_load_lds_dwordx4 v[186:187], off
	s_add_i32 m0, s54, 0x2000
	s_add_u32 s54, s24, 0x40000
	v_lshl_add_u64 v[226:227], s[24:25], 0, v[134:135]
	s_addc_u32 s55, s25, 0
	s_add_i32 s76, s43, s31
	global_load_lds_dwordx4 v[226:227], off
	s_mov_b32 m0, s76
	v_lshl_add_u64 v[230:231], s[26:27], 0, v[132:133]
	global_load_lds_dwordx4 v130, s[54:55]
	s_add_i32 m0, s76, 0x2000
	s_nop 0
	global_load_lds_dwordx4 v134, s[54:55]
	v_lshl_add_u64 v[228:229], s[26:27], 0, v[128:129]
	s_mov_b32 m0, s13
	s_nop 0
	global_load_lds_dwordx4 v[228:229], off
	s_mov_b32 m0, s34
	s_nop 0
	global_load_lds_dwordx4 v[230:231], off
	s_waitcnt vmcnt(8) lgkmcnt(0)
	s_barrier
; #define PG8_STAGE(bufoff, gbase, voff) do { _Pragma("unroll") for (int _i = 0; _i < 2; ++_i) \
;         __builtin_amdgcn_global_load_lds((const unsigned*)((const char*)(gbase) + (voff)[_i]), (PG8_LAS unsigned*)(lds + (bufoff) + ldsw + _i * 8192), 16, 0, 0); } while (0)
; #define PG8_LDA(dst, b, h) do { _Pragma("unroll") for (int m = 0; m < 4; ++m) _Pragma("unroll") for (int k = 0; k < 2; ++k) dst[m][k] = *(const PG8_LAS bf16x8*)(lds + PG8_SA(b, h) + aoff + m * 2048 + k * 1024); } while (0)
; #define PG8_LDB(dst, b, h) do { _Pragma("unroll") for (int n = 0; n < 2; ++n) _Pragma("unroll") for (int k = 0; k < 2; ++k) dst[n][k] = *(const PG8_LAS bf16x8*)(lds + PG8_SB(b, h) + boff + n * 2048 + k * 1024); } while (0)
; #define PG8_MMA(ai, bj, At, Bt) do { __builtin_amdgcn_s_setprio(1); _Pragma("unroll") for (int m = 0; m < 4; ++m) _Pragma("unroll") for (int n = 0; n < 2; ++n) _Pragma("unroll") for (int k = 0; k < 2; ++k) \
;         acc[ai][bj][m][n] = __builtin_amdgcn_mfma_f32_16x16x32_bf16(Bt[n][k], At[m][k], acc[ai][bj][m][n], 0, 0, 0); __builtin_amdgcn_s_setprio(0); } while (0)
; #define PG8_WAIT_V(n) asm volatile("s_waitcnt vmcnt(" #n ")" ::: "memory")
; #define PG8_WAIT_L(n) asm volatile("s_waitcnt lgkmcnt(" #n ")" ::: "memory")
; #define PG8_BAR __builtin_amdgcn_s_barrier()
; #define PG8_SCHED __builtin_amdgcn_sched_barrier(0)
; template <class Epi, class Sched, bool ALIGN_EPI = false, bool SP2 = false>
; __device__ __forceinline__ void gemm_phase(PG8_LAS unsigned char* lds, const Gemm g, const Sched& S, const Epi& E) {
;     ...
;             PG8_WAIT_V(8); PG8_WAIT_L(0); PG8_BAR; PG8_MMA(0, 0, At, B0); PG8_MMA(0, 1, At, B1); PG8_BAR; PG8_SCHED;
;             PG8_LDA(At, 0, 1); PG8_STAGE(PG8_SB(0, 0), b2, voffB); PG8_STAGE(PG8_SB(0, 1), b2 + hstep, voffB); PG8_STAGE(PG8_SA(0, 0), a2, voffA);
;             PG8_WAIT_V(8); PG8_WAIT_L(0); PG8_BAR; PG8_MMA(1, 0, At, B0); PG8_MMA(1, 1, At, B1); PG8_BAR; PG8_SCHED;
;             PG8_LDB(B0, 1, 0); PG8_LDB(B1, 1, 1); PG8_SCHED; PG8_LDA(At, 1, 0); PG8_STAGE(PG8_SA(0, 1), a2 + hstep, voffA);
;             PG8_WAIT_V(8); PG8_WAIT_L(0); PG8_BAR; PG8_MMA(0, 0, At, B0); PG8_MMA(0, 1, At, B1); PG8_BAR; PG8_SCHED;
	s_setprio 1
	v_mfma_f32_16x16x32_bf16 v[60:63], v[156:159], v[194:197], v[60:63]
	v_mfma_f32_16x16x32_bf16 v[56:59], v[164:167], v[194:197], v[56:59]
	v_mfma_f32_16x16x32_bf16 v[52:55], v[156:159], v[202:205], v[52:55]
	v_mfma_f32_16x16x32_bf16 v[48:51], v[164:167], v[202:205], v[48:51]
	v_mfma_f32_16x16x32_bf16 v[36:39], v[156:159], v[210:213], v[36:39]
	v_mfma_f32_16x16x32_bf16 v[32:35], v[164:167], v[210:213], v[32:35]
	v_mfma_f32_16x16x32_bf16 v[20:23], v[156:159], v[218:221], v[20:23]
	v_mfma_f32_16x16x32_bf16 v[16:19], v[164:167], v[218:221], v[16:19]
	v_mfma_f32_16x16x32_bf16 v[60:63], v[160:163], v[198:201], v[60:63]
	v_mfma_f32_16x16x32_bf16 v[56:59], v[168:171], v[198:201], v[56:59]
	v_mfma_f32_16x16x32_bf16 v[52:55], v[160:163], v[206:209], v[52:55]
	v_mfma_f32_16x16x32_bf16 v[48:51], v[168:171], v[206:209], v[48:51]
	v_mfma_f32_16x16x32_bf16 v[36:39], v[160:163], v[214:217], v[36:39]
	v_mfma_f32_16x16x32_bf16 v[32:35], v[168:171], v[214:217], v[32:35]
	v_mfma_f32_16x16x32_bf16 v[20:23], v[160:163], v[222:225], v[20:23]
	v_mfma_f32_16x16x32_bf16 v[16:19], v[168:171], v[222:225], v[16:19]
	v_mfma_f32_16x16x32_bf16 v[44:47], v[172:175], v[194:197], v[44:47]
	v_mfma_f32_16x16x32_bf16 v[40:43], v[182:185], v[194:197], v[40:43]
	v_mfma_f32_16x16x32_bf16 v[28:31], v[172:175], v[202:205], v[28:31]
	v_mfma_f32_16x16x32_bf16 v[24:27], v[182:185], v[202:205], v[24:27]
	v_mfma_f32_16x16x32_bf16 v[12:15], v[172:175], v[210:213], v[12:15]
	v_mfma_f32_16x16x32_bf16 v[8:11], v[182:185], v[210:213], v[8:11]
	v_mfma_f32_16x16x32_bf16 v[4:7], v[172:175], v[218:221], v[4:7]
	v_mfma_f32_16x16x32_bf16 v[0:3], v[182:185], v[218:221], v[0:3]
	v_mfma_f32_16x16x32_bf16 v[44:47], v[176:179], v[198:201], v[44:47]
	v_mfma_f32_16x16x32_bf16 v[40:43], v[190:193], v[198:201], v[40:43]
	v_mfma_f32_16x16x32_bf16 v[28:31], v[176:179], v[206:209], v[28:31]
	v_mfma_f32_16x16x32_bf16 v[24:27], v[190:193], v[206:209], v[24:27]
	v_mfma_f32_16x16x32_bf16 v[12:15], v[176:179], v[214:217], v[12:15]
	v_mfma_f32_16x16x32_bf16 v[8:11], v[190:193], v[214:217], v[8:11]
	v_mfma_f32_16x16x32_bf16 v[4:7], v[176:179], v[222:225], v[4:7]
	v_mfma_f32_16x16x32_bf16 v[0:3], v[190:193], v[222:225], v[0:3]
	s_setprio 0
	s_barrier
	s_add_i32 s54, 0, 0x18000
	v_add_u32_e32 v147, s54, v152
	s_add_i32 s55, 0, 0x1c000
	ds_read_b128 v[156:159], v147
	ds_read_b128 v[160:163], v147 offset:1024
	ds_read_b128 v[164:167], v147 offset:2048
	ds_read_b128 v[168:171], v147 offset:3072
	v_add_u32_e32 v147, s55, v152
	ds_read_b128 v[172:175], v147
	ds_read_b128 v[176:179], v147 offset:1024
	ds_read_b128 v[182:185], v147 offset:2048
	ds_read_b128 v[190:193], v147 offset:3072
	s_add_u32 s26, s26, 0x40000
	s_addc_u32 s27, s27, 0
	s_mov_b32 m0, s35
	ds_read_b128 v[194:197], v155 offset:32768
	ds_read_b128 v[198:201], v155 offset:33792
	ds_read_b128 v[202:205], v155 offset:34816
	ds_read_b128 v[206:209], v155 offset:35840
	ds_read_b128 v[210:213], v155 offset:36864
	ds_read_b128 v[214:217], v155 offset:37888
	ds_read_b128 v[218:221], v155 offset:38912
	ds_read_b128 v[222:225], v155 offset:39936
	global_load_lds_dwordx4 v128, s[26:27]
	s_mov_b32 m0, s36
	s_nop 0
	global_load_lds_dwordx4 v132, s[26:27]
	s_waitcnt vmcnt(8) lgkmcnt(0)
	s_barrier
	s_setprio 1
	v_mfma_f32_16x16x32_bf16 v[124:127], v[156:159], v[194:197], v[124:127]
	v_mfma_f32_16x16x32_bf16 v[120:123], v[164:167], v[194:197], v[120:123]
	v_mfma_f32_16x16x32_bf16 v[116:119], v[156:159], v[202:205], v[116:119]
	v_mfma_f32_16x16x32_bf16 v[112:115], v[164:167], v[202:205], v[112:115]
	v_mfma_f32_16x16x32_bf16 v[100:103], v[156:159], v[210:213], v[100:103]
	v_mfma_f32_16x16x32_bf16 v[96:99], v[164:167], v[210:213], v[96:99]
	v_mfma_f32_16x16x32_bf16 v[84:87], v[156:159], v[218:221], v[84:87]
	v_mfma_f32_16x16x32_bf16 v[80:83], v[164:167], v[218:221], v[80:83]
	v_mfma_f32_16x16x32_bf16 v[124:127], v[160:163], v[198:201], v[124:127]
	v_mfma_f32_16x16x32_bf16 v[120:123], v[168:171], v[198:201], v[120:123]
	v_mfma_f32_16x16x32_bf16 v[116:119], v[160:163], v[206:209], v[116:119]
	v_mfma_f32_16x16x32_bf16 v[112:115], v[168:171], v[206:209], v[112:115]
	v_mfma_f32_16x16x32_bf16 v[100:103], v[160:163], v[214:217], v[100:103]
	v_mfma_f32_16x16x32_bf16 v[96:99], v[168:171], v[214:217], v[96:99]
	v_mfma_f32_16x16x32_bf16 v[84:87], v[160:163], v[222:225], v[84:87]
	v_mfma_f32_16x16x32_bf16 v[80:83], v[168:171], v[222:225], v[80:83]
	v_mfma_f32_16x16x32_bf16 v[108:111], v[172:175], v[194:197], v[108:111]
	v_mfma_f32_16x16x32_bf16 v[104:107], v[182:185], v[194:197], v[104:107]
	v_mfma_f32_16x16x32_bf16 v[92:95], v[172:175], v[202:205], v[92:95]
	v_mfma_f32_16x16x32_bf16 v[88:91], v[182:185], v[202:205], v[88:91]
	v_mfma_f32_16x16x32_bf16 v[76:79], v[172:175], v[210:213], v[76:79]
	v_mfma_f32_16x16x32_bf16 v[72:75], v[182:185], v[210:213], v[72:75]
	v_mfma_f32_16x16x32_bf16 v[68:71], v[172:175], v[218:221], v[68:71]
	v_mfma_f32_16x16x32_bf16 v[64:67], v[182:185], v[218:221], v[64:67]
	v_mfma_f32_16x16x32_bf16 v[108:111], v[176:179], v[198:201], v[108:111]
	v_mfma_f32_16x16x32_bf16 v[104:107], v[190:193], v[198:201], v[104:107]
	v_mfma_f32_16x16x32_bf16 v[92:95], v[176:179], v[206:209], v[92:95]
	v_mfma_f32_16x16x32_bf16 v[88:91], v[190:193], v[206:209], v[88:91]
	v_mfma_f32_16x16x32_bf16 v[76:79], v[176:179], v[214:217], v[76:79]
	v_mfma_f32_16x16x32_bf16 v[72:75], v[190:193], v[214:217], v[72:75]
	v_mfma_f32_16x16x32_bf16 v[68:71], v[176:179], v[222:225], v[68:71]
	v_mfma_f32_16x16x32_bf16 v[64:67], v[190:193], v[222:225], v[64:67]
	s_setprio 0
	s_barrier
; #define PG8_STAGE(bufoff, gbase, voff) do { _Pragma("unroll") for (int _i = 0; _i < 2; ++_i) \
;         __builtin_amdgcn_global_load_lds((const unsigned*)((const char*)(gbase) + (voff)[_i]), (PG8_LAS unsigned*)(lds + (bufoff) + ldsw + _i * 8192), 16, 0, 0); } while (0)
; #define PG8_LDA(dst, b, h) do { _Pragma("unroll") for (int m = 0; m < 4; ++m) _Pragma("unroll") for (int k = 0; k < 2; ++k) dst[m][k] = *(const PG8_LAS bf16x8*)(lds + PG8_SA(b, h) + aoff + m * 2048 + k * 1024); } while (0)
; #define PG8_MMA(ai, bj, At, Bt) do { __builtin_amdgcn_s_setprio(1); _Pragma("unroll") for (int m = 0; m < 4; ++m) _Pragma("unroll") for (int n = 0; n < 2; ++n) _Pragma("unroll") for (int k = 0; k < 2; ++k) \
;         acc[ai][bj][m][n] = __builtin_amdgcn_mfma_f32_16x16x32_bf16(Bt[n][k], At[m][k], acc[ai][bj][m][n], 0, 0, 0); __builtin_amdgcn_s_setprio(0); } while (0)
; #define PG8_WAIT_V(n) asm volatile("s_waitcnt vmcnt(" #n ")" ::: "memory")
; #define PG8_WAIT_L(n) asm volatile("s_waitcnt lgkmcnt(" #n ")" ::: "memory")
; #define PG8_BAR __builtin_amdgcn_s_barrier()
; #define PG8_SCHED __builtin_amdgcn_sched_barrier(0)
; template <class Epi, class Sched, bool ALIGN_EPI = false, bool SP2 = false>
; __device__ __forceinline__ void gemm_phase(PG8_LAS unsigned char* lds, const Gemm g, const Sched& S, const Epi& E) {
;     ...
;             PG8_LDA(At, 1, 1); PG8_STAGE(PG8_SB(1, 0), b3, voffB); PG8_STAGE(PG8_SB(1, 1), b3 + hstep, voffB); PG8_STAGE(PG8_SA(1, 0), a3, voffA);
;             PG8_WAIT_V(8); PG8_WAIT_L(0); PG8_BAR; PG8_MMA(1, 0, At, B0); PG8_MMA(1, 1, At, B1); PG8_BAR; PG8_SCHED;
	s_add_i32 s26, s54, s31
	v_lshl_add_u64 v[186:187], v[186:187], 0, s[8:9]
	s_mov_b32 m0, s26
	ds_read_b128 v[194:197], v155 offset:49152
	ds_read_b128 v[198:201], v155 offset:50176
	ds_read_b128 v[202:205], v155 offset:51200
	ds_read_b128 v[206:209], v155 offset:52224
	ds_read_b128 v[210:213], v155 offset:53248
	ds_read_b128 v[214:217], v155 offset:54272
	ds_read_b128 v[218:221], v155 offset:55296
	ds_read_b128 v[222:225], v155 offset:56320
	global_load_lds_dwordx4 v[186:187], off
	s_add_i32 m0, s26, 0x2000
	s_add_u32 s24, s24, 0x40080
	v_lshl_add_u64 v[186:187], v[226:227], 0, s[8:9]
	s_addc_u32 s25, s25, 0
	s_add_i32 s26, s55, s31
	global_load_lds_dwordx4 v[186:187], off
	s_mov_b32 m0, s26
	s_nop 0
	global_load_lds_dwordx4 v130, s[24:25]
	s_add_i32 m0, s26, 0x2000
	s_nop 0
	global_load_lds_dwordx4 v134, s[24:25]
	v_lshl_add_u64 v[186:187], v[228:229], 0, s[8:9]
	s_mov_b32 m0, s39
	s_nop 0
	global_load_lds_dwordx4 v[186:187], off
	v_lshl_add_u64 v[186:187], v[230:231], 0, s[8:9]
	s_mov_b32 m0, s40
	s_nop 0
	global_load_lds_dwordx4 v[186:187], off
	s_waitcnt vmcnt(8) lgkmcnt(0)
	s_barrier
	s_setprio 1
	v_mfma_f32_16x16x32_bf16 v[60:63], v[156:159], v[194:197], v[60:63]
	v_mfma_f32_16x16x32_bf16 v[56:59], v[164:167], v[194:197], v[56:59]
	v_mfma_f32_16x16x32_bf16 v[52:55], v[156:159], v[202:205], v[52:55]
	v_mfma_f32_16x16x32_bf16 v[48:51], v[164:167], v[202:205], v[48:51]
	v_mfma_f32_16x16x32_bf16 v[36:39], v[156:159], v[210:213], v[36:39]
	v_mfma_f32_16x16x32_bf16 v[32:35], v[164:167], v[210:213], v[32:35]
	v_mfma_f32_16x16x32_bf16 v[20:23], v[156:159], v[218:221], v[20:23]
	v_mfma_f32_16x16x32_bf16 v[16:19], v[164:167], v[218:221], v[16:19]
	v_mfma_f32_16x16x32_bf16 v[60:63], v[160:163], v[198:201], v[60:63]
	v_mfma_f32_16x16x32_bf16 v[56:59], v[168:171], v[198:201], v[56:59]
	v_mfma_f32_16x16x32_bf16 v[52:55], v[160:163], v[206:209], v[52:55]
	v_mfma_f32_16x16x32_bf16 v[48:51], v[168:171], v[206:209], v[48:51]
	v_mfma_f32_16x16x32_bf16 v[36:39], v[160:163], v[214:217], v[36:39]
	v_mfma_f32_16x16x32_bf16 v[32:35], v[168:171], v[214:217], v[32:35]
	v_mfma_f32_16x16x32_bf16 v[20:23], v[160:163], v[222:225], v[20:23]
	v_mfma_f32_16x16x32_bf16 v[16:19], v[168:171], v[222:225], v[16:19]
	v_mfma_f32_16x16x32_bf16 v[44:47], v[172:175], v[194:197], v[44:47]
	v_mfma_f32_16x16x32_bf16 v[40:43], v[182:185], v[194:197], v[40:43]
	v_mfma_f32_16x16x32_bf16 v[28:31], v[172:175], v[202:205], v[28:31]
	v_mfma_f32_16x16x32_bf16 v[24:27], v[182:185], v[202:205], v[24:27]
	v_mfma_f32_16x16x32_bf16 v[12:15], v[172:175], v[210:213], v[12:15]
	v_mfma_f32_16x16x32_bf16 v[8:11], v[182:185], v[210:213], v[8:11]
	v_mfma_f32_16x16x32_bf16 v[4:7], v[172:175], v[218:221], v[4:7]
	v_mfma_f32_16x16x32_bf16 v[0:3], v[182:185], v[218:221], v[0:3]
	v_mfma_f32_16x16x32_bf16 v[44:47], v[176:179], v[198:201], v[44:47]
	v_mfma_f32_16x16x32_bf16 v[40:43], v[190:193], v[198:201], v[40:43]
	v_mfma_f32_16x16x32_bf16 v[28:31], v[176:179], v[206:209], v[28:31]
	v_mfma_f32_16x16x32_bf16 v[24:27], v[190:193], v[206:209], v[24:27]
	v_mfma_f32_16x16x32_bf16 v[12:15], v[176:179], v[214:217], v[12:15]
	v_mfma_f32_16x16x32_bf16 v[8:11], v[190:193], v[214:217], v[8:11]
	v_mfma_f32_16x16x32_bf16 v[4:7], v[176:179], v[222:225], v[4:7]
	v_mfma_f32_16x16x32_bf16 v[0:3], v[190:193], v[222:225], v[0:3]
	s_setprio 0
	s_barrier
	s_add_i32 s49, s49, 2
	s_add_u32 s22, s22, 0x100
	s_addc_u32 s23, s23, 0
	s_add_u32 s47, s47, 0x100
	s_addc_u32 s48, s48, 0
	s_cmp_gt_u32 s49, 13
	s_cbranch_scc0 .LBB0_150
	s_and_b64 vcc, exec, s[10:11]
	s_cbranch_vccz .LBB0_153
	s_barrier

; #define PG8_STAGE(bufoff, gbase, voff) do { _Pragma("unroll") for (int _i = 0; _i < 2; ++_i) \
;         __builtin_amdgcn_global_load_lds((const unsigned*)((const char*)(gbase) + (voff)[_i]), (PG8_LAS unsigned*)(lds + (bufoff) + ldsw + _i * 8192), 16, 0, 0); } while (0)
; #define PG8_LDA(dst, b, h) do { _Pragma("unroll") for (int m = 0; m < 4; ++m) _Pragma("unroll") for (int k = 0; k < 2; ++k) dst[m][k] = *(const PG8_LAS bf16x8*)(lds + PG8_SA(b, h) + aoff + m * 2048 + k * 1024); } while (0)
; #define PG8_LDB(dst, b, h) do { _Pragma("unroll") for (int n = 0; n < 2; ++n) _Pragma("unroll") for (int k = 0; k < 2; ++k) dst[n][k] = *(const PG8_LAS bf16x8*)(lds + PG8_SB(b, h) + boff + n * 2048 + k * 1024); } while (0)
; #define PG8_MMA(ai, bj, At, Bt) do { __builtin_amdgcn_s_setprio(1); _Pragma("unroll") for (int m = 0; m < 4; ++m) _Pragma("unroll") for (int n = 0; n < 2; ++n) _Pragma("unroll") for (int k = 0; k < 2; ++k) \
;         acc[ai][bj][m][n] = __builtin_amdgcn_mfma_f32_16x16x32_bf16(Bt[n][k], At[m][k], acc[ai][bj][m][n], 0, 0, 0); __builtin_amdgcn_s_setprio(0); } while (0)
; #define PG8_WAIT_V(n) asm volatile("s_waitcnt vmcnt(" #n ")" ::: "memory")
; #define PG8_WAIT_L(n) asm volatile("s_waitcnt lgkmcnt(" #n ")" ::: "memory")
; #define PG8_BAR __builtin_amdgcn_s_barrier()
; #define PG8_SCHED __builtin_amdgcn_sched_barrier(0)
; template <class Epi, class Sched, bool ALIGN_EPI = false, bool SP2 = false>
; __device__ __forceinline__ void gemm_phase(PG8_LAS unsigned char* lds, const Gemm g, const Sched& S, const Epi& E) {
;     ...
;             PG8_LDB(B0, 0, 0); PG8_LDB(B1, 0, 1); PG8_SCHED; PG8_LDA(At, 0, 0); PG8_STAGE(PG8_SA(1, 1), a1 + hstep, voffA);
;             PG8_WAIT_V(8); PG8_WAIT_L(0); PG8_BAR; PG8_MMA(0, 0, At, B0); PG8_MMA(0, 1, At, B1); PG8_BAR; PG8_SCHED;
;             PG8_LDA(At, 0, 1); PG8_STAGE(PG8_SB(0, 0), b2, voffB); PG8_STAGE(PG8_SB(0, 1), b2 + hstep, voffB); PG8_STAGE(PG8_SA(0, 0), a2, voffA);
;             PG8_WAIT_V(8); PG8_WAIT_L(0); PG8_BAR; PG8_MMA(1, 0, At, B0); PG8_MMA(1, 1, At, B1); PG8_BAR; PG8_SCHED;
.LBB0_358:
	ds_read_b128 v[128:131], v178
	ds_read_b128 v[132:135], v178 offset:1024
	ds_read_b128 v[136:139], v178 offset:2048
	ds_read_b128 v[140:143], v178 offset:3072
	ds_read_b128 v[166:169], v179
	ds_read_b128 v[170:173], v179 offset:1024
	ds_read_b128 v[190:193], v179 offset:2048
	ds_read_b128 v[194:197], v179 offset:3072
	s_add_u32 s42, s40, 0xfffc0080
	s_addc_u32 s43, s41, -1
	s_cmp_eq_u32 s25, 12
	s_cselect_b32 s45, s1, s43
	s_cselect_b32 s44, s35, s42
	s_cselect_b32 s43, s31, s24
	s_cselect_b32 s42, vcc_lo, vcc_hi
	v_lshl_add_u64 v[174:175], s[40:41], 0, v[158:159]
	s_add_i32 m0, s47, 0xc000
	ds_read_b128 v[198:201], v181
	ds_read_b128 v[202:205], v181 offset:1024
	ds_read_b128 v[206:209], v181 offset:2048
	ds_read_b128 v[210:213], v181 offset:3072
	ds_read_b128 v[214:217], v181 offset:4096
	ds_read_b128 v[218:221], v181 offset:5120
	ds_read_b128 v[222:225], v181 offset:6144
	ds_read_b128 v[226:229], v181 offset:7168
	global_load_lds_dwordx4 v[174:175], off
	v_lshl_add_u64 v[174:175], s[40:41], 0, v[160:161]
	s_add_i32 m0, s47, 0xe000
	s_nop 0
	global_load_lds_dwordx4 v[174:175], off
	s_waitcnt vmcnt(8) lgkmcnt(0)
	s_barrier
	s_setprio 1
	v_mfma_f32_16x16x32_bf16 v[124:127], v[128:131], v[198:201], v[124:127]
	v_mfma_f32_16x16x32_bf16 v[120:123], v[136:139], v[198:201], v[120:123]
	v_mfma_f32_16x16x32_bf16 v[108:111], v[128:131], v[206:209], v[108:111]
	v_mfma_f32_16x16x32_bf16 v[104:107], v[136:139], v[206:209], v[104:107]
	v_mfma_f32_16x16x32_bf16 v[92:95], v[128:131], v[214:217], v[92:95]
	v_mfma_f32_16x16x32_bf16 v[88:91], v[136:139], v[214:217], v[88:91]
	v_mfma_f32_16x16x32_bf16 v[76:79], v[128:131], v[222:225], v[76:79]
	v_mfma_f32_16x16x32_bf16 v[72:75], v[136:139], v[222:225], v[72:75]
	v_mfma_f32_16x16x32_bf16 v[124:127], v[132:135], v[202:205], v[124:127]
	v_mfma_f32_16x16x32_bf16 v[120:123], v[140:143], v[202:205], v[120:123]
	v_mfma_f32_16x16x32_bf16 v[108:111], v[132:135], v[210:213], v[108:111]
	v_mfma_f32_16x16x32_bf16 v[104:107], v[140:143], v[210:213], v[104:107]
	v_mfma_f32_16x16x32_bf16 v[92:95], v[132:135], v[218:221], v[92:95]
	v_mfma_f32_16x16x32_bf16 v[88:91], v[140:143], v[218:221], v[88:91]
	v_mfma_f32_16x16x32_bf16 v[76:79], v[132:135], v[226:229], v[76:79]
	v_mfma_f32_16x16x32_bf16 v[72:75], v[140:143], v[226:229], v[72:75]
	v_mfma_f32_16x16x32_bf16 v[116:119], v[166:169], v[198:201], v[116:119]
	v_mfma_f32_16x16x32_bf16 v[112:115], v[190:193], v[198:201], v[112:115]
	v_mfma_f32_16x16x32_bf16 v[100:103], v[166:169], v[206:209], v[100:103]
	v_mfma_f32_16x16x32_bf16 v[96:99], v[190:193], v[206:209], v[96:99]
	v_mfma_f32_16x16x32_bf16 v[84:87], v[166:169], v[214:217], v[84:87]
	v_mfma_f32_16x16x32_bf16 v[80:83], v[190:193], v[214:217], v[80:83]
	v_mfma_f32_16x16x32_bf16 v[68:71], v[166:169], v[222:225], v[68:71]
	v_mfma_f32_16x16x32_bf16 v[64:67], v[190:193], v[222:225], v[64:67]
	v_mfma_f32_16x16x32_bf16 v[116:119], v[170:173], v[202:205], v[116:119]
	v_mfma_f32_16x16x32_bf16 v[112:115], v[194:197], v[202:205], v[112:115]
	v_mfma_f32_16x16x32_bf16 v[100:103], v[170:173], v[210:213], v[100:103]
	v_mfma_f32_16x16x32_bf16 v[96:99], v[194:197], v[210:213], v[96:99]
	v_mfma_f32_16x16x32_bf16 v[84:87], v[170:173], v[218:221], v[84:87]
	v_mfma_f32_16x16x32_bf16 v[80:83], v[194:197], v[218:221], v[80:83]
	v_mfma_f32_16x16x32_bf16 v[68:71], v[170:173], v[226:229], v[68:71]
	v_mfma_f32_16x16x32_bf16 v[64:67], v[194:197], v[226:229], v[64:67]
	s_setprio 0
	s_barrier
	s_add_i32 s54, s93, s46
	v_lshl_add_u64 v[174:175], s[42:43], 0, v[146:147]
	s_mov_b32 m0, s54
	ds_read_b128 v[198:201], v181 offset:16384
	ds_read_b128 v[202:205], v181 offset:17408
	ds_read_b128 v[206:209], v181 offset:18432
	ds_read_b128 v[210:213], v181 offset:19456
	ds_read_b128 v[214:217], v181 offset:20480
	ds_read_b128 v[218:221], v181 offset:21504
	ds_read_b128 v[222:225], v181 offset:22528
	ds_read_b128 v[226:229], v181 offset:23552
	global_load_lds_dwordx4 v[174:175], off
	s_add_i32 m0, s54, 0x2000
	s_add_u32 s54, s42, 0x40000
	v_lshl_add_u64 v[186:187], s[42:43], 0, v[150:151]
	s_addc_u32 s55, s43, 0
	s_add_i32 s23, s94, s46
	global_load_lds_dwordx4 v[186:187], off
	v_lshl_add_u64 v[230:231], s[54:55], 0, v[146:147]
	s_mov_b32 m0, s23
	v_lshl_add_u64 v[232:233], s[44:45], 0, v[148:149]
	global_load_lds_dwordx4 v[230:231], off
	v_lshl_add_u64 v[230:231], s[54:55], 0, v[150:151]
	s_add_i32 m0, s23, 0x2000
	s_nop 0
	global_load_lds_dwordx4 v[230:231], off
	v_lshl_add_u64 v[230:231], s[44:45], 0, v[144:145]
	s_mov_b32 m0, s47
	s_nop 0
	global_load_lds_dwordx4 v[230:231], off
	s_mov_b32 m0, s48
	s_nop 0
	global_load_lds_dwordx4 v[232:233], off
	s_waitcnt vmcnt(8) lgkmcnt(0)
	s_barrier
; #define PG8_STAGE(bufoff, gbase, voff) do { _Pragma("unroll") for (int _i = 0; _i < 2; ++_i) \
;         __builtin_amdgcn_global_load_lds((const unsigned*)((const char*)(gbase) + (voff)[_i]), (PG8_LAS unsigned*)(lds + (bufoff) + ldsw + _i * 8192), 16, 0, 0); } while (0)
; #define PG8_LDA(dst, b, h) do { _Pragma("unroll") for (int m = 0; m < 4; ++m) _Pragma("unroll") for (int k = 0; k < 2; ++k) dst[m][k] = *(const PG8_LAS bf16x8*)(lds + PG8_SA(b, h) + aoff + m * 2048 + k * 1024); } while (0)
; #define PG8_LDB(dst, b, h) do { _Pragma("unroll") for (int n = 0; n < 2; ++n) _Pragma("unroll") for (int k = 0; k < 2; ++k) dst[n][k] = *(const PG8_LAS bf16x8*)(lds + PG8_SB(b, h) + boff + n * 2048 + k * 1024); } while (0)
; #define PG8_MMA(ai, bj, At, Bt) do { __builtin_amdgcn_s_setprio(1); _Pragma("unroll") for (int m = 0; m < 4; ++m) _Pragma("unroll") for (int n = 0; n < 2; ++n) _Pragma("unroll") for (int k = 0; k < 2; ++k) \
;         acc[ai][bj][m][n] = __builtin_amdgcn_mfma_f32_16x16x32_bf16(Bt[n][k], At[m][k], acc[ai][bj][m][n], 0, 0, 0); __builtin_amdgcn_s_setprio(0); } while (0)
; #define PG8_WAIT_V(n) asm volatile("s_waitcnt vmcnt(" #n ")" ::: "memory")
; #define PG8_WAIT_L(n) asm volatile("s_waitcnt lgkmcnt(" #n ")" ::: "memory")
; #define PG8_BAR __builtin_amdgcn_s_barrier()
; #define PG8_SCHED __builtin_amdgcn_sched_barrier(0)
; template <class Epi, class Sched, bool ALIGN_EPI = false, bool SP2 = false>
; __device__ __forceinline__ void gemm_phase(PG8_LAS unsigned char* lds, const Gemm g, const Sched& S, const Epi& E) {
;     ...
;             PG8_WAIT_V(8); PG8_WAIT_L(0); PG8_BAR; PG8_MMA(0, 0, At, B0); PG8_MMA(0, 1, At, B1); PG8_BAR; PG8_SCHED;
;             PG8_LDA(At, 0, 1); PG8_STAGE(PG8_SB(0, 0), b2, voffB); PG8_STAGE(PG8_SB(0, 1), b2 + hstep, voffB); PG8_STAGE(PG8_SA(0, 0), a2, voffA);
;             PG8_WAIT_V(8); PG8_WAIT_L(0); PG8_BAR; PG8_MMA(1, 0, At, B0); PG8_MMA(1, 1, At, B1); PG8_BAR; PG8_SCHED;
;             PG8_LDB(B0, 1, 0); PG8_LDB(B1, 1, 1); PG8_SCHED; PG8_LDA(At, 1, 0); PG8_STAGE(PG8_SA(0, 1), a2 + hstep, voffA);
;             PG8_WAIT_V(8); PG8_WAIT_L(0); PG8_BAR; PG8_MMA(0, 0, At, B0); PG8_MMA(0, 1, At, B1); PG8_BAR; PG8_SCHED;
	s_setprio 1
	v_mfma_f32_16x16x32_bf16 v[60:63], v[128:131], v[198:201], v[60:63]
	v_mfma_f32_16x16x32_bf16 v[56:59], v[136:139], v[198:201], v[56:59]
	v_mfma_f32_16x16x32_bf16 v[44:47], v[128:131], v[206:209], v[44:47]
	v_mfma_f32_16x16x32_bf16 v[40:43], v[136:139], v[206:209], v[40:43]
	v_mfma_f32_16x16x32_bf16 v[28:31], v[128:131], v[214:217], v[28:31]
	v_mfma_f32_16x16x32_bf16 v[24:27], v[136:139], v[214:217], v[24:27]
	v_mfma_f32_16x16x32_bf16 v[12:15], v[128:131], v[222:225], v[12:15]
	v_mfma_f32_16x16x32_bf16 v[8:11], v[136:139], v[222:225], v[8:11]
	v_mfma_f32_16x16x32_bf16 v[60:63], v[132:135], v[202:205], v[60:63]
	v_mfma_f32_16x16x32_bf16 v[56:59], v[140:143], v[202:205], v[56:59]
	v_mfma_f32_16x16x32_bf16 v[44:47], v[132:135], v[210:213], v[44:47]
	v_mfma_f32_16x16x32_bf16 v[40:43], v[140:143], v[210:213], v[40:43]
	v_mfma_f32_16x16x32_bf16 v[28:31], v[132:135], v[218:221], v[28:31]
	v_mfma_f32_16x16x32_bf16 v[24:27], v[140:143], v[218:221], v[24:27]
	v_mfma_f32_16x16x32_bf16 v[12:15], v[132:135], v[226:229], v[12:15]
	v_mfma_f32_16x16x32_bf16 v[8:11], v[140:143], v[226:229], v[8:11]
	v_mfma_f32_16x16x32_bf16 v[52:55], v[166:169], v[198:201], v[52:55]
	v_mfma_f32_16x16x32_bf16 v[48:51], v[190:193], v[198:201], v[48:51]
	v_mfma_f32_16x16x32_bf16 v[36:39], v[166:169], v[206:209], v[36:39]
	v_mfma_f32_16x16x32_bf16 v[32:35], v[190:193], v[206:209], v[32:35]
	v_mfma_f32_16x16x32_bf16 v[20:23], v[166:169], v[214:217], v[20:23]
	v_mfma_f32_16x16x32_bf16 v[16:19], v[190:193], v[214:217], v[16:19]
	v_mfma_f32_16x16x32_bf16 v[4:7], v[166:169], v[222:225], v[4:7]
	v_mfma_f32_16x16x32_bf16 v[0:3], v[190:193], v[222:225], v[0:3]
	v_mfma_f32_16x16x32_bf16 v[52:55], v[170:173], v[202:205], v[52:55]
	v_mfma_f32_16x16x32_bf16 v[48:51], v[194:197], v[202:205], v[48:51]
	v_mfma_f32_16x16x32_bf16 v[36:39], v[170:173], v[210:213], v[36:39]
	v_mfma_f32_16x16x32_bf16 v[32:35], v[194:197], v[210:213], v[32:35]
	v_mfma_f32_16x16x32_bf16 v[20:23], v[170:173], v[218:221], v[20:23]
	v_mfma_f32_16x16x32_bf16 v[16:19], v[194:197], v[218:221], v[16:19]
	v_mfma_f32_16x16x32_bf16 v[4:7], v[170:173], v[226:229], v[4:7]
	v_mfma_f32_16x16x32_bf16 v[0:3], v[194:197], v[226:229], v[0:3]
	s_setprio 0
	s_barrier
	s_add_i32 s23, 0, 0x18000
	s_add_i32 s54, 0, 0x1c000
	v_add_u32_e32 v140, s23, v176
	v_add_u32_e32 v152, s54, v176
	ds_read_b128 v[128:131], v140
	ds_read_b128 v[132:135], v140 offset:1024
	ds_read_b128 v[136:139], v140 offset:2048
	ds_read_b128 v[140:143], v140 offset:3072
	ds_read_b128 v[166:169], v152
	ds_read_b128 v[170:173], v152 offset:1024
	ds_read_b128 v[190:193], v152 offset:2048
	ds_read_b128 v[194:197], v152 offset:3072
	s_add_u32 s44, s44, 0x40000
	s_addc_u32 s45, s45, 0
	s_mov_b32 m0, s49
	v_lshl_add_u64 v[234:235], s[44:45], 0, v[144:145]
	ds_read_b128 v[198:201], v181 offset:32768
	ds_read_b128 v[202:205], v181 offset:33792
	ds_read_b128 v[206:209], v181 offset:34816
	ds_read_b128 v[210:213], v181 offset:35840
	ds_read_b128 v[214:217], v181 offset:36864
	ds_read_b128 v[218:221], v181 offset:37888
	ds_read_b128 v[222:225], v181 offset:38912
	ds_read_b128 v[226:229], v181 offset:39936
	global_load_lds_dwordx4 v[234:235], off
	v_lshl_add_u64 v[234:235], s[44:45], 0, v[148:149]
	s_mov_b32 m0, s51
	s_nop 0
	global_load_lds_dwordx4 v[234:235], off
	s_waitcnt vmcnt(8) lgkmcnt(0)
	s_barrier
	s_setprio 1
	v_mfma_f32_16x16x32_bf16 v[124:127], v[128:131], v[198:201], v[124:127]
	v_mfma_f32_16x16x32_bf16 v[120:123], v[136:139], v[198:201], v[120:123]
	v_mfma_f32_16x16x32_bf16 v[108:111], v[128:131], v[206:209], v[108:111]
	v_mfma_f32_16x16x32_bf16 v[104:107], v[136:139], v[206:209], v[104:107]
	v_mfma_f32_16x16x32_bf16 v[92:95], v[128:131], v[214:217], v[92:95]
	v_mfma_f32_16x16x32_bf16 v[88:91], v[136:139], v[214:217], v[88:91]
	v_mfma_f32_16x16x32_bf16 v[76:79], v[128:131], v[222:225], v[76:79]
	v_mfma_f32_16x16x32_bf16 v[72:75], v[136:139], v[222:225], v[72:75]
	v_mfma_f32_16x16x32_bf16 v[124:127], v[132:135], v[202:205], v[124:127]
	v_mfma_f32_16x16x32_bf16 v[120:123], v[140:143], v[202:205], v[120:123]
	v_mfma_f32_16x16x32_bf16 v[108:111], v[132:135], v[210:213], v[108:111]
	v_mfma_f32_16x16x32_bf16 v[104:107], v[140:143], v[210:213], v[104:107]
	v_mfma_f32_16x16x32_bf16 v[92:95], v[132:135], v[218:221], v[92:95]
	v_mfma_f32_16x16x32_bf16 v[88:91], v[140:143], v[218:221], v[88:91]
	v_mfma_f32_16x16x32_bf16 v[76:79], v[132:135], v[226:229], v[76:79]
	v_mfma_f32_16x16x32_bf16 v[72:75], v[140:143], v[226:229], v[72:75]
	v_mfma_f32_16x16x32_bf16 v[116:119], v[166:169], v[198:201], v[116:119]
	v_mfma_f32_16x16x32_bf16 v[112:115], v[190:193], v[198:201], v[112:115]
	v_mfma_f32_16x16x32_bf16 v[100:103], v[166:169], v[206:209], v[100:103]
	v_mfma_f32_16x16x32_bf16 v[96:99], v[190:193], v[206:209], v[96:99]
	v_mfma_f32_16x16x32_bf16 v[84:87], v[166:169], v[214:217], v[84:87]
	v_mfma_f32_16x16x32_bf16 v[80:83], v[190:193], v[214:217], v[80:83]
	v_mfma_f32_16x16x32_bf16 v[68:71], v[166:169], v[222:225], v[68:71]
	v_mfma_f32_16x16x32_bf16 v[64:67], v[190:193], v[222:225], v[64:67]
	v_mfma_f32_16x16x32_bf16 v[116:119], v[170:173], v[202:205], v[116:119]
	v_mfma_f32_16x16x32_bf16 v[112:115], v[194:197], v[202:205], v[112:115]
	v_mfma_f32_16x16x32_bf16 v[100:103], v[170:173], v[210:213], v[100:103]
	v_mfma_f32_16x16x32_bf16 v[96:99], v[194:197], v[210:213], v[96:99]
	v_mfma_f32_16x16x32_bf16 v[84:87], v[170:173], v[218:221], v[84:87]
	v_mfma_f32_16x16x32_bf16 v[80:83], v[194:197], v[218:221], v[80:83]
	v_mfma_f32_16x16x32_bf16 v[68:71], v[170:173], v[226:229], v[68:71]
	v_mfma_f32_16x16x32_bf16 v[64:67], v[194:197], v[226:229], v[64:67]
	s_setprio 0
	s_barrier
; #define PG8_STAGE(bufoff, gbase, voff) do { _Pragma("unroll") for (int _i = 0; _i < 2; ++_i) \
;         __builtin_amdgcn_global_load_lds((const unsigned*)((const char*)(gbase) + (voff)[_i]), (PG8_LAS unsigned*)(lds + (bufoff) + ldsw + _i * 8192), 16, 0, 0); } while (0)
; #define PG8_LDA(dst, b, h) do { _Pragma("unroll") for (int m = 0; m < 4; ++m) _Pragma("unroll") for (int k = 0; k < 2; ++k) dst[m][k] = *(const PG8_LAS bf16x8*)(lds + PG8_SA(b, h) + aoff + m * 2048 + k * 1024); } while (0)
; #define PG8_MMA(ai, bj, At, Bt) do { __builtin_amdgcn_s_setprio(1); _Pragma("unroll") for (int m = 0; m < 4; ++m) _Pragma("unroll") for (int n = 0; n < 2; ++n) _Pragma("unroll") for (int k = 0; k < 2; ++k) \
;         acc[ai][bj][m][n] = __builtin_amdgcn_mfma_f32_16x16x32_bf16(Bt[n][k], At[m][k], acc[ai][bj][m][n], 0, 0, 0); __builtin_amdgcn_s_setprio(0); } while (0)
; #define PG8_WAIT_V(n) asm volatile("s_waitcnt vmcnt(" #n ")" ::: "memory")
; #define PG8_WAIT_L(n) asm volatile("s_waitcnt lgkmcnt(" #n ")" ::: "memory")
; #define PG8_BAR __builtin_amdgcn_s_barrier()
; #define PG8_SCHED __builtin_amdgcn_sched_barrier(0)
; template <class Epi, class Sched, bool ALIGN_EPI = false, bool SP2 = false>
; __device__ __forceinline__ void gemm_phase(PG8_LAS unsigned char* lds, const Gemm g, const Sched& S, const Epi& E) {
;     ...
;             PG8_LDA(At, 1, 1); PG8_STAGE(PG8_SB(1, 0), b3, voffB); PG8_STAGE(PG8_SB(1, 1), b3 + hstep, voffB); PG8_STAGE(PG8_SA(1, 0), a3, voffA);
;             PG8_WAIT_V(8); PG8_WAIT_L(0); PG8_BAR; PG8_MMA(1, 0, At, B0); PG8_MMA(1, 1, At, B1); PG8_BAR; PG8_SCHED;
	s_add_i32 s23, s23, s46
	v_lshl_add_u64 v[174:175], v[174:175], 0, s[10:11]
	s_mov_b32 m0, s23
	ds_read_b128 v[198:201], v181 offset:49152
	ds_read_b128 v[202:205], v181 offset:50176
	ds_read_b128 v[206:209], v181 offset:51200
	ds_read_b128 v[210:213], v181 offset:52224
	ds_read_b128 v[214:217], v181 offset:53248
	ds_read_b128 v[218:221], v181 offset:54272
	ds_read_b128 v[222:225], v181 offset:55296
	ds_read_b128 v[226:229], v181 offset:56320
	global_load_lds_dwordx4 v[174:175], off
	s_add_i32 m0, s23, 0x2000
	s_add_u32 s42, s42, 0x40080
	v_lshl_add_u64 v[174:175], v[186:187], 0, s[10:11]
	s_addc_u32 s43, s43, 0
	s_add_i32 s23, s54, s46
	global_load_lds_dwordx4 v[174:175], off
	v_lshl_add_u64 v[174:175], s[42:43], 0, v[146:147]
	s_mov_b32 m0, s23
	s_nop 0
	global_load_lds_dwordx4 v[174:175], off
	v_lshl_add_u64 v[174:175], s[42:43], 0, v[150:151]
	s_add_i32 m0, s23, 0x2000
	s_nop 0
	global_load_lds_dwordx4 v[174:175], off
	v_lshl_add_u64 v[174:175], v[230:231], 0, s[10:11]
	s_mov_b32 m0, s80
	s_nop 0
	global_load_lds_dwordx4 v[174:175], off
	v_lshl_add_u64 v[174:175], v[232:233], 0, s[10:11]
	s_mov_b32 m0, s81
	s_nop 0
	global_load_lds_dwordx4 v[174:175], off
	s_waitcnt vmcnt(8) lgkmcnt(0)
	s_barrier
	s_setprio 1
	v_mfma_f32_16x16x32_bf16 v[60:63], v[128:131], v[198:201], v[60:63]
	v_mfma_f32_16x16x32_bf16 v[56:59], v[136:139], v[198:201], v[56:59]
	v_mfma_f32_16x16x32_bf16 v[44:47], v[128:131], v[206:209], v[44:47]
	v_mfma_f32_16x16x32_bf16 v[40:43], v[136:139], v[206:209], v[40:43]
	v_mfma_f32_16x16x32_bf16 v[28:31], v[128:131], v[214:217], v[28:31]
	v_mfma_f32_16x16x32_bf16 v[24:27], v[136:139], v[214:217], v[24:27]
	v_mfma_f32_16x16x32_bf16 v[12:15], v[128:131], v[222:225], v[12:15]
	v_mfma_f32_16x16x32_bf16 v[8:11], v[136:139], v[222:225], v[8:11]
	v_mfma_f32_16x16x32_bf16 v[60:63], v[132:135], v[202:205], v[60:63]
	v_mfma_f32_16x16x32_bf16 v[56:59], v[140:143], v[202:205], v[56:59]
	v_mfma_f32_16x16x32_bf16 v[44:47], v[132:135], v[210:213], v[44:47]
	v_mfma_f32_16x16x32_bf16 v[40:43], v[140:143], v[210:213], v[40:43]
	v_mfma_f32_16x16x32_bf16 v[28:31], v[132:135], v[218:221], v[28:31]
	v_mfma_f32_16x16x32_bf16 v[24:27], v[140:143], v[218:221], v[24:27]
	v_mfma_f32_16x16x32_bf16 v[12:15], v[132:135], v[226:229], v[12:15]
	v_mfma_f32_16x16x32_bf16 v[8:11], v[140:143], v[226:229], v[8:11]
	v_mfma_f32_16x16x32_bf16 v[52:55], v[166:169], v[198:201], v[52:55]
	v_mfma_f32_16x16x32_bf16 v[48:51], v[190:193], v[198:201], v[48:51]
	v_mfma_f32_16x16x32_bf16 v[36:39], v[166:169], v[206:209], v[36:39]
	v_mfma_f32_16x16x32_bf16 v[32:35], v[190:193], v[206:209], v[32:35]
	v_mfma_f32_16x16x32_bf16 v[20:23], v[166:169], v[214:217], v[20:23]
	v_mfma_f32_16x16x32_bf16 v[16:19], v[190:193], v[214:217], v[16:19]
	v_mfma_f32_16x16x32_bf16 v[4:7], v[166:169], v[222:225], v[4:7]
	v_mfma_f32_16x16x32_bf16 v[0:3], v[190:193], v[222:225], v[0:3]
	v_mfma_f32_16x16x32_bf16 v[52:55], v[170:173], v[202:205], v[52:55]
	v_mfma_f32_16x16x32_bf16 v[48:51], v[194:197], v[202:205], v[48:51]
	v_mfma_f32_16x16x32_bf16 v[36:39], v[170:173], v[210:213], v[36:39]
	v_mfma_f32_16x16x32_bf16 v[32:35], v[194:197], v[210:213], v[32:35]
	v_mfma_f32_16x16x32_bf16 v[20:23], v[170:173], v[218:221], v[20:23]
	v_mfma_f32_16x16x32_bf16 v[16:19], v[194:197], v[218:221], v[16:19]
	v_mfma_f32_16x16x32_bf16 v[4:7], v[170:173], v[226:229], v[4:7]
	v_mfma_f32_16x16x32_bf16 v[0:3], v[194:197], v[226:229], v[0:3]
	s_setprio 0
	s_barrier
	s_add_i32 s25, s25, 2
	s_add_u32 s40, s40, 0x100
	s_addc_u32 s41, s41, 0
	s_add_u32 vcc_hi, vcc_hi, 0x100
	s_addc_u32 s24, s24, 0
	s_cmp_gt_u32 s25, 13
	s_cbranch_scc0 .LBB0_358
	s_and_b64 vcc, exec, s[12:13]
	s_cbranch_vccz .LBB0_361
	s_barrier

; #define PG8_STAGE(bufoff, gbase, voff) do { _Pragma("unroll") for (int _i = 0; _i < 2; ++_i) \
;         __builtin_amdgcn_global_load_lds((const unsigned*)((const char*)(gbase) + (voff)[_i]), (PG8_LAS unsigned*)(lds + (bufoff) + ldsw + _i * 8192), 16, 0, 0); } while (0)
; #define PG8_LDA(dst, b, h) do { _Pragma("unroll") for (int m = 0; m < 4; ++m) _Pragma("unroll") for (int k = 0; k < 2; ++k) dst[m][k] = *(const PG8_LAS bf16x8*)(lds + PG8_SA(b, h) + aoff + m * 2048 + k * 1024); } while (0)
; #define PG8_LDB(dst, b, h) do { _Pragma("unroll") for (int n = 0; n < 2; ++n) _Pragma("unroll") for (int k = 0; k < 2; ++k) dst[n][k] = *(const PG8_LAS bf16x8*)(lds + PG8_SB(b, h) + boff + n * 2048 + k * 1024); } while (0)
; #define PG8_MMA(ai, bj, At, Bt) do { __builtin_amdgcn_s_setprio(1); _Pragma("unroll") for (int m = 0; m < 4; ++m) _Pragma("unroll") for (int n = 0; n < 2; ++n) _Pragma("unroll") for (int k = 0; k < 2; ++k) \
;         acc[ai][bj][m][n] = __builtin_amdgcn_mfma_f32_16x16x32_bf16(Bt[n][k], At[m][k], acc[ai][bj][m][n], 0, 0, 0); __builtin_amdgcn_s_setprio(0); } while (0)
; #define PG8_WAIT_V(n) asm volatile("s_waitcnt vmcnt(" #n ")" ::: "memory")
; #define PG8_WAIT_L(n) asm volatile("s_waitcnt lgkmcnt(" #n ")" ::: "memory")
; #define PG8_BAR __builtin_amdgcn_s_barrier()
; #define PG8_SCHED __builtin_amdgcn_sched_barrier(0)
; template <class Epi, class Sched, bool ALIGN_EPI = false, bool SP2 = false>
; __device__ __forceinline__ void gemm_phase(PG8_LAS unsigned char* lds, const Gemm g, const Sched& S, const Epi& E) {
;     ...
;             PG8_LDB(B0, 0, 0); PG8_LDB(B1, 0, 1); PG8_SCHED; PG8_LDA(At, 0, 0); PG8_STAGE(PG8_SA(1, 1), a1 + hstep, voffA);
;             PG8_WAIT_V(8); PG8_WAIT_L(0); PG8_BAR; PG8_MMA(0, 0, At, B0); PG8_MMA(0, 1, At, B1); PG8_BAR; PG8_SCHED;
;             PG8_LDA(At, 0, 1); PG8_STAGE(PG8_SB(0, 0), b2, voffB); PG8_STAGE(PG8_SB(0, 1), b2 + hstep, voffB); PG8_STAGE(PG8_SA(0, 0), a2, voffA);
;             PG8_WAIT_V(8); PG8_WAIT_L(0); PG8_BAR; PG8_MMA(1, 0, At, B0); PG8_MMA(1, 1, At, B1); PG8_BAR; PG8_SCHED;
.LBB0_684:
	ds_read_b128 v[128:131], v174
	ds_read_b128 v[132:135], v174 offset:1024
	ds_read_b128 v[136:139], v174 offset:2048
	ds_read_b128 v[140:143], v174 offset:3072
	ds_read_b128 v[162:165], v175
	ds_read_b128 v[166:169], v175 offset:1024
	ds_read_b128 v[180:183], v175 offset:2048
	ds_read_b128 v[184:187], v175 offset:3072
	s_add_u32 s8, s0, 0xfffc0080
	s_addc_u32 s9, s1, -1
	s_cmp_eq_u32 vcc_lo, 12
	s_cselect_b32 s43, s3, s9
	s_cselect_b32 s42, s94, s8
	s_cselect_b32 s41, s5, s97
	s_cselect_b32 s40, s95, s96
	s_add_i32 m0, s47, 0xc000
	ds_read_b128 v[190:193], v176
	ds_read_b128 v[194:197], v176 offset:1024
	ds_read_b128 v[198:201], v176 offset:2048
	ds_read_b128 v[202:205], v176 offset:3072
	ds_read_b128 v[206:209], v176 offset:4096
	ds_read_b128 v[210:213], v176 offset:5120
	ds_read_b128 v[214:217], v176 offset:6144
	ds_read_b128 v[218:221], v176 offset:7168
	global_load_lds_dwordx4 v158, s[0:1]
	s_add_i32 m0, s47, 0xe000
	s_nop 0
	global_load_lds_dwordx4 v160, s[0:1]
	s_waitcnt vmcnt(8) lgkmcnt(0)
	s_barrier
	s_setprio 1
	v_mfma_f32_16x16x32_bf16 v[124:127], v[128:131], v[190:193], v[124:127]
	v_mfma_f32_16x16x32_bf16 v[120:123], v[136:139], v[190:193], v[120:123]
	v_mfma_f32_16x16x32_bf16 v[108:111], v[128:131], v[198:201], v[108:111]
	v_mfma_f32_16x16x32_bf16 v[104:107], v[136:139], v[198:201], v[104:107]
	v_mfma_f32_16x16x32_bf16 v[92:95], v[128:131], v[206:209], v[92:95]
	v_mfma_f32_16x16x32_bf16 v[88:91], v[136:139], v[206:209], v[88:91]
	v_mfma_f32_16x16x32_bf16 v[76:79], v[128:131], v[214:217], v[76:79]
	v_mfma_f32_16x16x32_bf16 v[72:75], v[136:139], v[214:217], v[72:75]
	v_mfma_f32_16x16x32_bf16 v[124:127], v[132:135], v[194:197], v[124:127]
	v_mfma_f32_16x16x32_bf16 v[120:123], v[140:143], v[194:197], v[120:123]
	v_mfma_f32_16x16x32_bf16 v[108:111], v[132:135], v[202:205], v[108:111]
	v_mfma_f32_16x16x32_bf16 v[104:107], v[140:143], v[202:205], v[104:107]
	v_mfma_f32_16x16x32_bf16 v[92:95], v[132:135], v[210:213], v[92:95]
	v_mfma_f32_16x16x32_bf16 v[88:91], v[140:143], v[210:213], v[88:91]
	v_mfma_f32_16x16x32_bf16 v[76:79], v[132:135], v[218:221], v[76:79]
	v_mfma_f32_16x16x32_bf16 v[72:75], v[140:143], v[218:221], v[72:75]
	v_mfma_f32_16x16x32_bf16 v[116:119], v[162:165], v[190:193], v[116:119]
	v_mfma_f32_16x16x32_bf16 v[112:115], v[180:183], v[190:193], v[112:115]
	v_mfma_f32_16x16x32_bf16 v[100:103], v[162:165], v[198:201], v[100:103]
	v_mfma_f32_16x16x32_bf16 v[96:99], v[180:183], v[198:201], v[96:99]
	v_mfma_f32_16x16x32_bf16 v[84:87], v[162:165], v[206:209], v[84:87]
	v_mfma_f32_16x16x32_bf16 v[80:83], v[180:183], v[206:209], v[80:83]
	v_mfma_f32_16x16x32_bf16 v[68:71], v[162:165], v[214:217], v[68:71]
	v_mfma_f32_16x16x32_bf16 v[64:67], v[180:183], v[214:217], v[64:67]
	v_mfma_f32_16x16x32_bf16 v[116:119], v[166:169], v[194:197], v[116:119]
	v_mfma_f32_16x16x32_bf16 v[112:115], v[184:187], v[194:197], v[112:115]
	v_mfma_f32_16x16x32_bf16 v[100:103], v[166:169], v[202:205], v[100:103]
	v_mfma_f32_16x16x32_bf16 v[96:99], v[184:187], v[202:205], v[96:99]
	v_mfma_f32_16x16x32_bf16 v[84:87], v[166:169], v[210:213], v[84:87]
	v_mfma_f32_16x16x32_bf16 v[80:83], v[184:187], v[210:213], v[80:83]
	v_mfma_f32_16x16x32_bf16 v[68:71], v[166:169], v[218:221], v[68:71]
	v_mfma_f32_16x16x32_bf16 v[64:67], v[184:187], v[218:221], v[64:67]
	s_setprio 0
	s_barrier
	s_add_i32 s8, s76, s46
	v_lshl_add_u64 v[170:171], s[40:41], 0, v[146:147]
	s_mov_b32 m0, s8
	ds_read_b128 v[190:193], v176 offset:16384
	ds_read_b128 v[194:197], v176 offset:17408
	ds_read_b128 v[198:201], v176 offset:18432
	ds_read_b128 v[202:205], v176 offset:19456
	ds_read_b128 v[206:209], v176 offset:20480
	ds_read_b128 v[210:213], v176 offset:21504
	ds_read_b128 v[214:217], v176 offset:22528
	ds_read_b128 v[218:221], v176 offset:23552
	global_load_lds_dwordx4 v[170:171], off
	s_add_i32 m0, s8, 0x2000
	s_add_u32 s8, s40, 0x40000
	v_lshl_add_u64 v[222:223], s[40:41], 0, v[150:151]
	s_addc_u32 s9, s41, 0
	s_add_i32 s54, s77, s46
	global_load_lds_dwordx4 v[222:223], off
	s_mov_b32 m0, s54
	v_lshl_add_u64 v[226:227], s[42:43], 0, v[148:149]
	global_load_lds_dwordx4 v146, s[8:9]
	s_add_i32 m0, s54, 0x2000
	s_nop 0
	global_load_lds_dwordx4 v150, s[8:9]
	v_lshl_add_u64 v[224:225], s[42:43], 0, v[144:145]
	s_mov_b32 m0, s47
	s_nop 0
	global_load_lds_dwordx4 v[224:225], off
	s_mov_b32 m0, s48
	s_nop 0
	global_load_lds_dwordx4 v[226:227], off
	s_waitcnt vmcnt(8) lgkmcnt(0)
	s_barrier
	s_setprio 1
	v_mfma_f32_16x16x32_bf16 v[60:63], v[128:131], v[190:193], v[60:63]
	v_mfma_f32_16x16x32_bf16 v[56:59], v[136:139], v[190:193], v[56:59]
	v_mfma_f32_16x16x32_bf16 v[44:47], v[128:131], v[198:201], v[44:47]
	v_mfma_f32_16x16x32_bf16 v[40:43], v[136:139], v[198:201], v[40:43]
	v_mfma_f32_16x16x32_bf16 v[28:31], v[128:131], v[206:209], v[28:31]
	v_mfma_f32_16x16x32_bf16 v[24:27], v[136:139], v[206:209], v[24:27]
	v_mfma_f32_16x16x32_bf16 v[12:15], v[128:131], v[214:217], v[12:15]
	v_mfma_f32_16x16x32_bf16 v[8:11], v[136:139], v[214:217], v[8:11]
	v_mfma_f32_16x16x32_bf16 v[60:63], v[132:135], v[194:197], v[60:63]
	v_mfma_f32_16x16x32_bf16 v[56:59], v[140:143], v[194:197], v[56:59]
	v_mfma_f32_16x16x32_bf16 v[44:47], v[132:135], v[202:205], v[44:47]
	v_mfma_f32_16x16x32_bf16 v[40:43], v[140:143], v[202:205], v[40:43]
	v_mfma_f32_16x16x32_bf16 v[28:31], v[132:135], v[210:213], v[28:31]
	v_mfma_f32_16x16x32_bf16 v[24:27], v[140:143], v[210:213], v[24:27]
	v_mfma_f32_16x16x32_bf16 v[12:15], v[132:135], v[218:221], v[12:15]
	v_mfma_f32_16x16x32_bf16 v[8:11], v[140:143], v[218:221], v[8:11]
	v_mfma_f32_16x16x32_bf16 v[52:55], v[162:165], v[190:193], v[52:55]
	v_mfma_f32_16x16x32_bf16 v[48:51], v[180:183], v[190:193], v[48:51]
	v_mfma_f32_16x16x32_bf16 v[36:39], v[162:165], v[198:201], v[36:39]
	v_mfma_f32_16x16x32_bf16 v[32:35], v[180:183], v[198:201], v[32:35]
	v_mfma_f32_16x16x32_bf16 v[20:23], v[162:165], v[206:209], v[20:23]
	v_mfma_f32_16x16x32_bf16 v[16:19], v[180:183], v[206:209], v[16:19]
	v_mfma_f32_16x16x32_bf16 v[4:7], v[162:165], v[214:217], v[4:7]
	v_mfma_f32_16x16x32_bf16 v[0:3], v[180:183], v[214:217], v[0:3]
	v_mfma_f32_16x16x32_bf16 v[52:55], v[166:169], v[194:197], v[52:55]
	v_mfma_f32_16x16x32_bf16 v[48:51], v[184:187], v[194:197], v[48:51]
	v_mfma_f32_16x16x32_bf16 v[36:39], v[166:169], v[202:205], v[36:39]
	v_mfma_f32_16x16x32_bf16 v[32:35], v[184:187], v[202:205], v[32:35]
	v_mfma_f32_16x16x32_bf16 v[20:23], v[166:169], v[210:213], v[20:23]
	v_mfma_f32_16x16x32_bf16 v[16:19], v[184:187], v[210:213], v[16:19]
	v_mfma_f32_16x16x32_bf16 v[4:7], v[166:169], v[218:221], v[4:7]
	v_mfma_f32_16x16x32_bf16 v[0:3], v[184:187], v[218:221], v[0:3]
	s_setprio 0
	s_barrier
; #define PG8_STAGE(bufoff, gbase, voff) do { _Pragma("unroll") for (int _i = 0; _i < 2; ++_i) \
;         __builtin_amdgcn_global_load_lds((const unsigned*)((const char*)(gbase) + (voff)[_i]), (PG8_LAS unsigned*)(lds + (bufoff) + ldsw + _i * 8192), 16, 0, 0); } while (0)
; #define PG8_LDA(dst, b, h) do { _Pragma("unroll") for (int m = 0; m < 4; ++m) _Pragma("unroll") for (int k = 0; k < 2; ++k) dst[m][k] = *(const PG8_LAS bf16x8*)(lds + PG8_SA(b, h) + aoff + m * 2048 + k * 1024); } while (0)
; #define PG8_LDB(dst, b, h) do { _Pragma("unroll") for (int n = 0; n < 2; ++n) _Pragma("unroll") for (int k = 0; k < 2; ++k) dst[n][k] = *(const PG8_LAS bf16x8*)(lds + PG8_SB(b, h) + boff + n * 2048 + k * 1024); } while (0)
; #define PG8_MMA(ai, bj, At, Bt) do { __builtin_amdgcn_s_setprio(1); _Pragma("unroll") for (int m = 0; m < 4; ++m) _Pragma("unroll") for (int n = 0; n < 2; ++n) _Pragma("unroll") for (int k = 0; k < 2; ++k) \
;         acc[ai][bj][m][n] = __builtin_amdgcn_mfma_f32_16x16x32_bf16(Bt[n][k], At[m][k], acc[ai][bj][m][n], 0, 0, 0); __builtin_amdgcn_s_setprio(0); } while (0)
; #define PG8_WAIT_V(n) asm volatile("s_waitcnt vmcnt(" #n ")" ::: "memory")
; #define PG8_WAIT_L(n) asm volatile("s_waitcnt lgkmcnt(" #n ")" ::: "memory")
; #define PG8_BAR __builtin_amdgcn_s_barrier()
; #define PG8_SCHED __builtin_amdgcn_sched_barrier(0)
; template <class Epi, class Sched, bool ALIGN_EPI = false, bool SP2 = false>
; __device__ __forceinline__ void gemm_phase(PG8_LAS unsigned char* lds, const Gemm g, const Sched& S, const Epi& E) {
;     ...
;             PG8_LDB(B0, 1, 0); PG8_LDB(B1, 1, 1); PG8_SCHED; PG8_LDA(At, 1, 0); PG8_STAGE(PG8_SA(0, 1), a2 + hstep, voffA);
;             PG8_WAIT_V(8); PG8_WAIT_L(0); PG8_BAR; PG8_MMA(0, 0, At, B0); PG8_MMA(0, 1, At, B1); PG8_BAR; PG8_SCHED;
;             PG8_LDA(At, 1, 1); PG8_STAGE(PG8_SB(1, 0), b3, voffB); PG8_STAGE(PG8_SB(1, 1), b3 + hstep, voffB); PG8_STAGE(PG8_SA(1, 0), a3, voffA);
;             PG8_WAIT_V(8); PG8_WAIT_L(0); PG8_BAR; PG8_MMA(1, 0, At, B0); PG8_MMA(1, 1, At, B1); PG8_BAR; PG8_SCHED;
	s_add_i32 s54, 0, 0x18000
	s_add_i32 s55, 0, 0x1c000
	v_add_u32_e32 v140, s54, v172
	v_add_u32_e32 v152, s55, v172
	ds_read_b128 v[128:131], v140
	ds_read_b128 v[132:135], v140 offset:1024
	ds_read_b128 v[136:139], v140 offset:2048
	ds_read_b128 v[140:143], v140 offset:3072
	ds_read_b128 v[162:165], v152
	ds_read_b128 v[166:169], v152 offset:1024
	ds_read_b128 v[180:183], v152 offset:2048
	ds_read_b128 v[184:187], v152 offset:3072
	s_add_u32 s8, s42, 0x40000
	s_addc_u32 s9, s43, 0
	s_mov_b32 m0, s49
	ds_read_b128 v[190:193], v176 offset:32768
	ds_read_b128 v[194:197], v176 offset:33792
	ds_read_b128 v[198:201], v176 offset:34816
	ds_read_b128 v[202:205], v176 offset:35840
	ds_read_b128 v[206:209], v176 offset:36864
	ds_read_b128 v[210:213], v176 offset:37888
	ds_read_b128 v[214:217], v176 offset:38912
	ds_read_b128 v[218:221], v176 offset:39936
	global_load_lds_dwordx4 v144, s[8:9]
	s_mov_b32 m0, s51
	s_nop 0
	global_load_lds_dwordx4 v148, s[8:9]
	s_waitcnt vmcnt(8) lgkmcnt(0)
	s_barrier
	s_setprio 1
	v_mfma_f32_16x16x32_bf16 v[124:127], v[128:131], v[190:193], v[124:127]
	v_mfma_f32_16x16x32_bf16 v[120:123], v[136:139], v[190:193], v[120:123]
	v_mfma_f32_16x16x32_bf16 v[108:111], v[128:131], v[198:201], v[108:111]
	v_mfma_f32_16x16x32_bf16 v[104:107], v[136:139], v[198:201], v[104:107]
	v_mfma_f32_16x16x32_bf16 v[92:95], v[128:131], v[206:209], v[92:95]
	v_mfma_f32_16x16x32_bf16 v[88:91], v[136:139], v[206:209], v[88:91]
	v_mfma_f32_16x16x32_bf16 v[76:79], v[128:131], v[214:217], v[76:79]
	v_mfma_f32_16x16x32_bf16 v[72:75], v[136:139], v[214:217], v[72:75]
	v_mfma_f32_16x16x32_bf16 v[124:127], v[132:135], v[194:197], v[124:127]
	v_mfma_f32_16x16x32_bf16 v[120:123], v[140:143], v[194:197], v[120:123]
	v_mfma_f32_16x16x32_bf16 v[108:111], v[132:135], v[202:205], v[108:111]
	v_mfma_f32_16x16x32_bf16 v[104:107], v[140:143], v[202:205], v[104:107]
	v_mfma_f32_16x16x32_bf16 v[92:95], v[132:135], v[210:213], v[92:95]
	v_mfma_f32_16x16x32_bf16 v[88:91], v[140:143], v[210:213], v[88:91]
	v_mfma_f32_16x16x32_bf16 v[76:79], v[132:135], v[218:221], v[76:79]
	v_mfma_f32_16x16x32_bf16 v[72:75], v[140:143], v[218:221], v[72:75]
	v_mfma_f32_16x16x32_bf16 v[116:119], v[162:165], v[190:193], v[116:119]
	v_mfma_f32_16x16x32_bf16 v[112:115], v[180:183], v[190:193], v[112:115]
	v_mfma_f32_16x16x32_bf16 v[100:103], v[162:165], v[198:201], v[100:103]
	v_mfma_f32_16x16x32_bf16 v[96:99], v[180:183], v[198:201], v[96:99]
	v_mfma_f32_16x16x32_bf16 v[84:87], v[162:165], v[206:209], v[84:87]
	v_mfma_f32_16x16x32_bf16 v[80:83], v[180:183], v[206:209], v[80:83]
	v_mfma_f32_16x16x32_bf16 v[68:71], v[162:165], v[214:217], v[68:71]
	v_mfma_f32_16x16x32_bf16 v[64:67], v[180:183], v[214:217], v[64:67]
	v_mfma_f32_16x16x32_bf16 v[116:119], v[166:169], v[194:197], v[116:119]
	v_mfma_f32_16x16x32_bf16 v[112:115], v[184:187], v[194:197], v[112:115]
	v_mfma_f32_16x16x32_bf16 v[100:103], v[166:169], v[202:205], v[100:103]
	v_mfma_f32_16x16x32_bf16 v[96:99], v[184:187], v[202:205], v[96:99]
	v_mfma_f32_16x16x32_bf16 v[84:87], v[166:169], v[210:213], v[84:87]
	v_mfma_f32_16x16x32_bf16 v[80:83], v[184:187], v[210:213], v[80:83]
	v_mfma_f32_16x16x32_bf16 v[68:71], v[166:169], v[218:221], v[68:71]
	v_mfma_f32_16x16x32_bf16 v[64:67], v[184:187], v[218:221], v[64:67]
	s_setprio 0
	s_barrier
	s_add_i32 s8, s54, s46
	v_lshl_add_u64 v[170:171], v[170:171], 0, s[14:15]
	s_mov_b32 m0, s8
	ds_read_b128 v[190:193], v176 offset:49152
	ds_read_b128 v[194:197], v176 offset:50176
	ds_read_b128 v[198:201], v176 offset:51200
	ds_read_b128 v[202:205], v176 offset:52224
	ds_read_b128 v[206:209], v176 offset:53248
	ds_read_b128 v[210:213], v176 offset:54272
	ds_read_b128 v[214:217], v176 offset:55296
	ds_read_b128 v[218:221], v176 offset:56320
	global_load_lds_dwordx4 v[170:171], off
	s_add_i32 m0, s8, 0x2000
	s_add_u32 s8, s40, 0x40080
	v_lshl_add_u64 v[170:171], v[222:223], 0, s[14:15]
	s_addc_u32 s9, s41, 0
	s_add_i32 s40, s55, s46
	global_load_lds_dwordx4 v[170:171], off
	s_mov_b32 m0, s40
	s_nop 0
	global_load_lds_dwordx4 v146, s[8:9]
	s_add_i32 m0, s40, 0x2000
	s_nop 0
	global_load_lds_dwordx4 v150, s[8:9]
	v_lshl_add_u64 v[170:171], v[224:225], 0, s[14:15]
	s_mov_b32 m0, s66
	s_nop 0
	global_load_lds_dwordx4 v[170:171], off
	v_lshl_add_u64 v[170:171], v[226:227], 0, s[14:15]
	s_mov_b32 m0, s67
	s_nop 0
	global_load_lds_dwordx4 v[170:171], off
	s_waitcnt vmcnt(8) lgkmcnt(0)
	s_barrier
	s_setprio 1
	v_mfma_f32_16x16x32_bf16 v[60:63], v[128:131], v[190:193], v[60:63]
	v_mfma_f32_16x16x32_bf16 v[56:59], v[136:139], v[190:193], v[56:59]
	v_mfma_f32_16x16x32_bf16 v[44:47], v[128:131], v[198:201], v[44:47]
	v_mfma_f32_16x16x32_bf16 v[40:43], v[136:139], v[198:201], v[40:43]
	v_mfma_f32_16x16x32_bf16 v[28:31], v[128:131], v[206:209], v[28:31]
	v_mfma_f32_16x16x32_bf16 v[24:27], v[136:139], v[206:209], v[24:27]
	v_mfma_f32_16x16x32_bf16 v[12:15], v[128:131], v[214:217], v[12:15]
	v_mfma_f32_16x16x32_bf16 v[8:11], v[136:139], v[214:217], v[8:11]
	v_mfma_f32_16x16x32_bf16 v[60:63], v[132:135], v[194:197], v[60:63]
	v_mfma_f32_16x16x32_bf16 v[56:59], v[140:143], v[194:197], v[56:59]
	v_mfma_f32_16x16x32_bf16 v[44:47], v[132:135], v[202:205], v[44:47]
	v_mfma_f32_16x16x32_bf16 v[40:43], v[140:143], v[202:205], v[40:43]
	v_mfma_f32_16x16x32_bf16 v[28:31], v[132:135], v[210:213], v[28:31]
	v_mfma_f32_16x16x32_bf16 v[24:27], v[140:143], v[210:213], v[24:27]
	v_mfma_f32_16x16x32_bf16 v[12:15], v[132:135], v[218:221], v[12:15]
	v_mfma_f32_16x16x32_bf16 v[8:11], v[140:143], v[218:221], v[8:11]
	v_mfma_f32_16x16x32_bf16 v[52:55], v[162:165], v[190:193], v[52:55]
	v_mfma_f32_16x16x32_bf16 v[48:51], v[180:183], v[190:193], v[48:51]
	v_mfma_f32_16x16x32_bf16 v[36:39], v[162:165], v[198:201], v[36:39]
	v_mfma_f32_16x16x32_bf16 v[32:35], v[180:183], v[198:201], v[32:35]
	v_mfma_f32_16x16x32_bf16 v[20:23], v[162:165], v[206:209], v[20:23]
	v_mfma_f32_16x16x32_bf16 v[16:19], v[180:183], v[206:209], v[16:19]
	v_mfma_f32_16x16x32_bf16 v[4:7], v[162:165], v[214:217], v[4:7]
	v_mfma_f32_16x16x32_bf16 v[0:3], v[180:183], v[214:217], v[0:3]
	v_mfma_f32_16x16x32_bf16 v[52:55], v[166:169], v[194:197], v[52:55]
	v_mfma_f32_16x16x32_bf16 v[48:51], v[184:187], v[194:197], v[48:51]
	v_mfma_f32_16x16x32_bf16 v[36:39], v[166:169], v[202:205], v[36:39]
	v_mfma_f32_16x16x32_bf16 v[32:35], v[184:187], v[202:205], v[32:35]
	v_mfma_f32_16x16x32_bf16 v[20:23], v[166:169], v[210:213], v[20:23]
	v_mfma_f32_16x16x32_bf16 v[16:19], v[184:187], v[210:213], v[16:19]
	v_mfma_f32_16x16x32_bf16 v[4:7], v[166:169], v[218:221], v[4:7]
	v_mfma_f32_16x16x32_bf16 v[0:3], v[184:187], v[218:221], v[0:3]
	s_setprio 0
	s_barrier
	s_add_i32 vcc_lo, vcc_lo, 2
	s_add_u32 s0, s0, 0x100
	s_addc_u32 s1, s1, 0
	s_add_u32 s96, s96, 0x100
	s_addc_u32 s97, s97, 0
	s_cmp_gt_u32 vcc_lo, 13
	s_cbranch_scc0 .LBB0_684
	s_and_b64 vcc, exec, s[18:19]
	s_cbranch_vccz .LBB0_687
	s_barrier

; #define PG8_STAGE(bufoff, gbase, voff) do { _Pragma("unroll") for (int _i = 0; _i < 2; ++_i) \
;         __builtin_amdgcn_global_load_lds((const unsigned*)((const char*)(gbase) + (voff)[_i]), (PG8_LAS unsigned*)(lds + (bufoff) + ldsw + _i * 8192), 16, 0, 0); } while (0)
; #define PG8_LDA(dst, b, h) do { _Pragma("unroll") for (int m = 0; m < 4; ++m) _Pragma("unroll") for (int k = 0; k < 2; ++k) dst[m][k] = *(const PG8_LAS bf16x8*)(lds + PG8_SA(b, h) + aoff + m * 2048 + k * 1024); } while (0)
; #define PG8_LDB(dst, b, h) do { _Pragma("unroll") for (int n = 0; n < 2; ++n) _Pragma("unroll") for (int k = 0; k < 2; ++k) dst[n][k] = *(const PG8_LAS bf16x8*)(lds + PG8_SB(b, h) + boff + n * 2048 + k * 1024); } while (0)
; #define PG8_MMA(ai, bj, At, Bt) do { __builtin_amdgcn_s_setprio(1); _Pragma("unroll") for (int m = 0; m < 4; ++m) _Pragma("unroll") for (int n = 0; n < 2; ++n) _Pragma("unroll") for (int k = 0; k < 2; ++k) \
;         acc[ai][bj][m][n] = __builtin_amdgcn_mfma_f32_16x16x32_bf16(Bt[n][k], At[m][k], acc[ai][bj][m][n], 0, 0, 0); __builtin_amdgcn_s_setprio(0); } while (0)
; #define PG8_WAIT_V(n) asm volatile("s_waitcnt vmcnt(" #n ")" ::: "memory")
; #define PG8_WAIT_L(n) asm volatile("s_waitcnt lgkmcnt(" #n ")" ::: "memory")
; #define PG8_BAR __builtin_amdgcn_s_barrier()
; #define PG8_SCHED __builtin_amdgcn_sched_barrier(0)
; template <class Epi, class Sched, bool ALIGN_EPI = false, bool SP2 = false>
; __device__ __forceinline__ void gemm_phase(PG8_LAS unsigned char* lds, const Gemm g, const Sched& S, const Epi& E) {
;     ...
;             PG8_LDB(B0, 0, 0); PG8_LDB(B1, 0, 1); PG8_SCHED; PG8_LDA(At, 0, 0); PG8_STAGE(PG8_SA(1, 1), a1 + hstep, voffA);
;             PG8_WAIT_V(8); PG8_WAIT_L(0); PG8_BAR; PG8_MMA(0, 0, At, B0); PG8_MMA(0, 1, At, B1); PG8_BAR; PG8_SCHED;
;             PG8_LDA(At, 0, 1); PG8_STAGE(PG8_SB(0, 0), b2, voffB); PG8_STAGE(PG8_SB(0, 1), b2 + hstep, voffB); PG8_STAGE(PG8_SA(0, 0), a2, voffA);
;             PG8_WAIT_V(8); PG8_WAIT_L(0); PG8_BAR; PG8_MMA(1, 0, At, B0); PG8_MMA(1, 1, At, B1); PG8_BAR; PG8_SCHED;
.LBB0_795:
	v_add_u32_e32 v162, s67, v186
	v_add_u32_e32 v178, s68, v186
	ds_read_b128 v[150:153], v162
	ds_read_b128 v[154:157], v162 offset:1024
	ds_read_b128 v[158:161], v162 offset:2048
	ds_read_b128 v[162:165], v162 offset:3072
	ds_read_b128 v[166:169], v178
	ds_read_b128 v[170:173], v178 offset:1024
	ds_read_b128 v[174:177], v178 offset:2048
	ds_read_b128 v[178:181], v178 offset:3072
	s_add_u32 s54, s46, 0xfff80080
	s_addc_u32 s55, s47, -1
	s_cmp_eq_u32 s82, 12
	s_cselect_b32 s57, s41, s55
	s_cselect_b32 s56, s78, s54
	s_cselect_b32 s55, s39, s81
	s_cselect_b32 s54, s79, s80
	s_add_i32 m0, s61, 0xc000
	ds_read_b128 v[182:185], v187
	ds_read_b128 v[190:193], v187 offset:1024
	ds_read_b128 v[194:197], v187 offset:2048
	ds_read_b128 v[198:201], v187 offset:3072
	ds_read_b128 v[202:205], v187 offset:4096
	ds_read_b128 v[206:209], v187 offset:5120
	ds_read_b128 v[210:213], v187 offset:6144
	ds_read_b128 v[214:217], v187 offset:7168
	global_load_lds_dwordx4 v142, s[46:47]
	s_add_i32 m0, s61, 0xe000
	s_nop 0
	global_load_lds_dwordx4 v144, s[46:47]
	s_waitcnt vmcnt(8) lgkmcnt(0)
	s_barrier
	s_setprio 1
	v_mfma_f32_16x16x32_bf16 v[124:127], v[150:153], v[182:185], v[124:127]
	v_mfma_f32_16x16x32_bf16 v[120:123], v[158:161], v[182:185], v[120:123]
	v_mfma_f32_16x16x32_bf16 v[116:119], v[150:153], v[194:197], v[116:119]
	v_mfma_f32_16x16x32_bf16 v[112:115], v[158:161], v[194:197], v[112:115]
	v_mfma_f32_16x16x32_bf16 v[108:111], v[150:153], v[202:205], v[108:111]
	v_mfma_f32_16x16x32_bf16 v[104:107], v[158:161], v[202:205], v[104:107]
	v_mfma_f32_16x16x32_bf16 v[100:103], v[150:153], v[210:213], v[100:103]
	v_mfma_f32_16x16x32_bf16 v[96:99], v[158:161], v[210:213], v[96:99]
	v_mfma_f32_16x16x32_bf16 v[124:127], v[154:157], v[190:193], v[124:127]
	v_mfma_f32_16x16x32_bf16 v[120:123], v[162:165], v[190:193], v[120:123]
	v_mfma_f32_16x16x32_bf16 v[116:119], v[154:157], v[198:201], v[116:119]
	v_mfma_f32_16x16x32_bf16 v[112:115], v[162:165], v[198:201], v[112:115]
	v_mfma_f32_16x16x32_bf16 v[108:111], v[154:157], v[206:209], v[108:111]
	v_mfma_f32_16x16x32_bf16 v[104:107], v[162:165], v[206:209], v[104:107]
	v_mfma_f32_16x16x32_bf16 v[100:103], v[154:157], v[214:217], v[100:103]
	v_mfma_f32_16x16x32_bf16 v[96:99], v[162:165], v[214:217], v[96:99]
	v_mfma_f32_16x16x32_bf16 v[92:95], v[166:169], v[182:185], v[92:95]
	v_mfma_f32_16x16x32_bf16 v[88:91], v[174:177], v[182:185], v[88:91]
	v_mfma_f32_16x16x32_bf16 v[84:87], v[166:169], v[194:197], v[84:87]
	v_mfma_f32_16x16x32_bf16 v[80:83], v[174:177], v[194:197], v[80:83]
	v_mfma_f32_16x16x32_bf16 v[76:79], v[166:169], v[202:205], v[76:79]
	v_mfma_f32_16x16x32_bf16 v[72:75], v[174:177], v[202:205], v[72:75]
	v_mfma_f32_16x16x32_bf16 v[68:71], v[166:169], v[210:213], v[68:71]
	v_mfma_f32_16x16x32_bf16 v[64:67], v[174:177], v[210:213], v[64:67]
	v_mfma_f32_16x16x32_bf16 v[92:95], v[170:173], v[190:193], v[92:95]
	v_mfma_f32_16x16x32_bf16 v[88:91], v[178:181], v[190:193], v[88:91]
	v_mfma_f32_16x16x32_bf16 v[84:87], v[170:173], v[198:201], v[84:87]
	v_mfma_f32_16x16x32_bf16 v[80:83], v[178:181], v[198:201], v[80:83]
	v_mfma_f32_16x16x32_bf16 v[76:79], v[170:173], v[206:209], v[76:79]
	v_mfma_f32_16x16x32_bf16 v[72:75], v[178:181], v[206:209], v[72:75]
	v_mfma_f32_16x16x32_bf16 v[68:71], v[170:173], v[214:217], v[68:71]
	v_mfma_f32_16x16x32_bf16 v[64:67], v[178:181], v[214:217], v[64:67]
	s_setprio 0
	s_barrier
	s_add_i32 s83, s67, s60
	v_lshl_add_u64 v[218:219], s[54:55], 0, v[130:131]
	s_mov_b32 m0, s83
	ds_read_b128 v[182:185], v187 offset:16384
	ds_read_b128 v[190:193], v187 offset:17408
	ds_read_b128 v[194:197], v187 offset:18432
	ds_read_b128 v[198:201], v187 offset:19456
	ds_read_b128 v[202:205], v187 offset:20480
	ds_read_b128 v[206:209], v187 offset:21504
	ds_read_b128 v[210:213], v187 offset:22528
	ds_read_b128 v[214:217], v187 offset:23552
	global_load_lds_dwordx4 v[218:219], off
	s_add_i32 m0, s83, 0x2000
	s_add_u32 s86, s54, 0x80000
	v_lshl_add_u64 v[220:221], s[54:55], 0, v[134:135]
	s_addc_u32 s87, s55, 0
	s_add_i32 s83, s68, s60
	global_load_lds_dwordx4 v[220:221], off
	s_mov_b32 m0, s83
	v_lshl_add_u64 v[224:225], s[56:57], 0, v[132:133]
	global_load_lds_dwordx4 v130, s[86:87]
	s_add_i32 m0, s83, 0x2000
	s_nop 0
	global_load_lds_dwordx4 v134, s[86:87]
	v_lshl_add_u64 v[222:223], s[56:57], 0, v[128:129]
	s_mov_b32 m0, s61
	s_nop 0
	global_load_lds_dwordx4 v[222:223], off
	s_mov_b32 m0, s62
	s_nop 0
	global_load_lds_dwordx4 v[224:225], off
	s_waitcnt vmcnt(8) lgkmcnt(0)
	s_barrier
	s_setprio 1
	v_mfma_f32_16x16x32_bf16 v[60:63], v[150:153], v[182:185], v[60:63]
	v_mfma_f32_16x16x32_bf16 v[56:59], v[158:161], v[182:185], v[56:59]
	v_mfma_f32_16x16x32_bf16 v[52:55], v[150:153], v[194:197], v[52:55]
	v_mfma_f32_16x16x32_bf16 v[48:51], v[158:161], v[194:197], v[48:51]
	v_mfma_f32_16x16x32_bf16 v[44:47], v[150:153], v[202:205], v[44:47]
	v_mfma_f32_16x16x32_bf16 v[40:43], v[158:161], v[202:205], v[40:43]
	v_mfma_f32_16x16x32_bf16 v[36:39], v[150:153], v[210:213], v[36:39]
	v_mfma_f32_16x16x32_bf16 v[32:35], v[158:161], v[210:213], v[32:35]
	v_mfma_f32_16x16x32_bf16 v[60:63], v[154:157], v[190:193], v[60:63]
	v_mfma_f32_16x16x32_bf16 v[56:59], v[162:165], v[190:193], v[56:59]
	v_mfma_f32_16x16x32_bf16 v[52:55], v[154:157], v[198:201], v[52:55]
	v_mfma_f32_16x16x32_bf16 v[48:51], v[162:165], v[198:201], v[48:51]
	v_mfma_f32_16x16x32_bf16 v[44:47], v[154:157], v[206:209], v[44:47]
	v_mfma_f32_16x16x32_bf16 v[40:43], v[162:165], v[206:209], v[40:43]
	v_mfma_f32_16x16x32_bf16 v[36:39], v[154:157], v[214:217], v[36:39]
	v_mfma_f32_16x16x32_bf16 v[32:35], v[162:165], v[214:217], v[32:35]
	v_mfma_f32_16x16x32_bf16 v[28:31], v[166:169], v[182:185], v[28:31]
	v_mfma_f32_16x16x32_bf16 v[24:27], v[174:177], v[182:185], v[24:27]
	v_mfma_f32_16x16x32_bf16 v[20:23], v[166:169], v[194:197], v[20:23]
	v_mfma_f32_16x16x32_bf16 v[16:19], v[174:177], v[194:197], v[16:19]
	v_mfma_f32_16x16x32_bf16 v[12:15], v[166:169], v[202:205], v[12:15]
	v_mfma_f32_16x16x32_bf16 v[8:11], v[174:177], v[202:205], v[8:11]
	v_mfma_f32_16x16x32_bf16 v[4:7], v[166:169], v[210:213], v[4:7]
	v_mfma_f32_16x16x32_bf16 v[0:3], v[174:177], v[210:213], v[0:3]
	v_mfma_f32_16x16x32_bf16 v[28:31], v[170:173], v[190:193], v[28:31]
	v_mfma_f32_16x16x32_bf16 v[24:27], v[178:181], v[190:193], v[24:27]
	v_mfma_f32_16x16x32_bf16 v[20:23], v[170:173], v[198:201], v[20:23]
	v_mfma_f32_16x16x32_bf16 v[16:19], v[178:181], v[198:201], v[16:19]
	v_mfma_f32_16x16x32_bf16 v[12:15], v[170:173], v[206:209], v[12:15]
	v_mfma_f32_16x16x32_bf16 v[8:11], v[178:181], v[206:209], v[8:11]
	v_mfma_f32_16x16x32_bf16 v[4:7], v[170:173], v[214:217], v[4:7]
	v_mfma_f32_16x16x32_bf16 v[0:3], v[178:181], v[214:217], v[0:3]
	s_setprio 0
	s_barrier
; #define PG8_STAGE(bufoff, gbase, voff) do { _Pragma("unroll") for (int _i = 0; _i < 2; ++_i) \
;         __builtin_amdgcn_global_load_lds((const unsigned*)((const char*)(gbase) + (voff)[_i]), (PG8_LAS unsigned*)(lds + (bufoff) + ldsw + _i * 8192), 16, 0, 0); } while (0)
; #define PG8_LDA(dst, b, h) do { _Pragma("unroll") for (int m = 0; m < 4; ++m) _Pragma("unroll") for (int k = 0; k < 2; ++k) dst[m][k] = *(const PG8_LAS bf16x8*)(lds + PG8_SA(b, h) + aoff + m * 2048 + k * 1024); } while (0)
; #define PG8_LDB(dst, b, h) do { _Pragma("unroll") for (int n = 0; n < 2; ++n) _Pragma("unroll") for (int k = 0; k < 2; ++k) dst[n][k] = *(const PG8_LAS bf16x8*)(lds + PG8_SB(b, h) + boff + n * 2048 + k * 1024); } while (0)
; #define PG8_MMA(ai, bj, At, Bt) do { __builtin_amdgcn_s_setprio(1); _Pragma("unroll") for (int m = 0; m < 4; ++m) _Pragma("unroll") for (int n = 0; n < 2; ++n) _Pragma("unroll") for (int k = 0; k < 2; ++k) \
;         acc[ai][bj][m][n] = __builtin_amdgcn_mfma_f32_16x16x32_bf16(Bt[n][k], At[m][k], acc[ai][bj][m][n], 0, 0, 0); __builtin_amdgcn_s_setprio(0); } while (0)
; #define PG8_WAIT_V(n) asm volatile("s_waitcnt vmcnt(" #n ")" ::: "memory")
; #define PG8_WAIT_L(n) asm volatile("s_waitcnt lgkmcnt(" #n ")" ::: "memory")
; #define PG8_BAR __builtin_amdgcn_s_barrier()
; #define PG8_SCHED __builtin_amdgcn_sched_barrier(0)
; template <class Epi, class Sched, bool ALIGN_EPI = false, bool SP2 = false>
; __device__ __forceinline__ void gemm_phase(PG8_LAS unsigned char* lds, const Gemm g, const Sched& S, const Epi& E) {
;     ...
;             PG8_LDB(B0, 1, 0); PG8_LDB(B1, 1, 1); PG8_SCHED; PG8_LDA(At, 1, 0); PG8_STAGE(PG8_SA(0, 1), a2 + hstep, voffA);
;             PG8_WAIT_V(8); PG8_WAIT_L(0); PG8_BAR; PG8_MMA(0, 0, At, B0); PG8_MMA(0, 1, At, B1); PG8_BAR; PG8_SCHED;
;             PG8_LDA(At, 1, 1); PG8_STAGE(PG8_SB(1, 0), b3, voffB); PG8_STAGE(PG8_SB(1, 1), b3 + hstep, voffB); PG8_STAGE(PG8_SA(1, 0), a3, voffA);
;             PG8_WAIT_V(8); PG8_WAIT_L(0); PG8_BAR; PG8_MMA(1, 0, At, B0); PG8_MMA(1, 1, At, B1); PG8_BAR; PG8_SCHED;
;     ...
;         if constexpr (ALIGN_EPI) { if (wr == 0) PG8_BAR; }
	s_add_i32 s83, 0, 0x18000
	s_add_i32 s86, 0, 0x1c000
	v_add_u32_e32 v162, s83, v186
	v_add_u32_e32 v178, s86, v186
	ds_read_b128 v[150:153], v162
	ds_read_b128 v[154:157], v162 offset:1024
	ds_read_b128 v[158:161], v162 offset:2048
	ds_read_b128 v[162:165], v162 offset:3072
	ds_read_b128 v[166:169], v178
	ds_read_b128 v[170:173], v178 offset:1024
	ds_read_b128 v[174:177], v178 offset:2048
	ds_read_b128 v[178:181], v178 offset:3072
	s_add_u32 s56, s56, 0x80000
	s_addc_u32 s57, s57, 0
	s_mov_b32 m0, s63
	ds_read_b128 v[182:185], v187 offset:32768
	ds_read_b128 v[190:193], v187 offset:33792
	ds_read_b128 v[194:197], v187 offset:34816
	ds_read_b128 v[198:201], v187 offset:35840
	ds_read_b128 v[202:205], v187 offset:36864
	ds_read_b128 v[206:209], v187 offset:37888
	ds_read_b128 v[210:213], v187 offset:38912
	ds_read_b128 v[214:217], v187 offset:39936
	global_load_lds_dwordx4 v128, s[56:57]
	s_mov_b32 m0, s64
	s_nop 0
	global_load_lds_dwordx4 v132, s[56:57]
	s_waitcnt vmcnt(8) lgkmcnt(0)
	s_barrier
	s_setprio 1
	v_mfma_f32_16x16x32_bf16 v[124:127], v[150:153], v[182:185], v[124:127]
	v_mfma_f32_16x16x32_bf16 v[120:123], v[158:161], v[182:185], v[120:123]
	v_mfma_f32_16x16x32_bf16 v[116:119], v[150:153], v[194:197], v[116:119]
	v_mfma_f32_16x16x32_bf16 v[112:115], v[158:161], v[194:197], v[112:115]
	v_mfma_f32_16x16x32_bf16 v[108:111], v[150:153], v[202:205], v[108:111]
	v_mfma_f32_16x16x32_bf16 v[104:107], v[158:161], v[202:205], v[104:107]
	v_mfma_f32_16x16x32_bf16 v[100:103], v[150:153], v[210:213], v[100:103]
	v_mfma_f32_16x16x32_bf16 v[96:99], v[158:161], v[210:213], v[96:99]
	v_mfma_f32_16x16x32_bf16 v[124:127], v[154:157], v[190:193], v[124:127]
	v_mfma_f32_16x16x32_bf16 v[120:123], v[162:165], v[190:193], v[120:123]
	v_mfma_f32_16x16x32_bf16 v[116:119], v[154:157], v[198:201], v[116:119]
	v_mfma_f32_16x16x32_bf16 v[112:115], v[162:165], v[198:201], v[112:115]
	v_mfma_f32_16x16x32_bf16 v[108:111], v[154:157], v[206:209], v[108:111]
	v_mfma_f32_16x16x32_bf16 v[104:107], v[162:165], v[206:209], v[104:107]
	v_mfma_f32_16x16x32_bf16 v[100:103], v[154:157], v[214:217], v[100:103]
	v_mfma_f32_16x16x32_bf16 v[96:99], v[162:165], v[214:217], v[96:99]
	v_mfma_f32_16x16x32_bf16 v[92:95], v[166:169], v[182:185], v[92:95]
	v_mfma_f32_16x16x32_bf16 v[88:91], v[174:177], v[182:185], v[88:91]
	v_mfma_f32_16x16x32_bf16 v[84:87], v[166:169], v[194:197], v[84:87]
	v_mfma_f32_16x16x32_bf16 v[80:83], v[174:177], v[194:197], v[80:83]
	v_mfma_f32_16x16x32_bf16 v[76:79], v[166:169], v[202:205], v[76:79]
	v_mfma_f32_16x16x32_bf16 v[72:75], v[174:177], v[202:205], v[72:75]
	v_mfma_f32_16x16x32_bf16 v[68:71], v[166:169], v[210:213], v[68:71]
	v_mfma_f32_16x16x32_bf16 v[64:67], v[174:177], v[210:213], v[64:67]
	v_mfma_f32_16x16x32_bf16 v[92:95], v[170:173], v[190:193], v[92:95]
	v_mfma_f32_16x16x32_bf16 v[88:91], v[178:181], v[190:193], v[88:91]
	v_mfma_f32_16x16x32_bf16 v[84:87], v[170:173], v[198:201], v[84:87]
	v_mfma_f32_16x16x32_bf16 v[80:83], v[178:181], v[198:201], v[80:83]
	v_mfma_f32_16x16x32_bf16 v[76:79], v[170:173], v[206:209], v[76:79]
	v_mfma_f32_16x16x32_bf16 v[72:75], v[178:181], v[206:209], v[72:75]
	v_mfma_f32_16x16x32_bf16 v[68:71], v[170:173], v[214:217], v[68:71]
	v_mfma_f32_16x16x32_bf16 v[64:67], v[178:181], v[214:217], v[64:67]
	s_setprio 0
	s_barrier
	s_add_i32 s56, s83, s60
	v_lshl_add_u64 v[218:219], v[218:219], 0, s[14:15]
	s_mov_b32 m0, s56
	ds_read_b128 v[182:185], v187 offset:49152
	ds_read_b128 v[190:193], v187 offset:50176
	ds_read_b128 v[194:197], v187 offset:51200
	ds_read_b128 v[198:201], v187 offset:52224
	ds_read_b128 v[202:205], v187 offset:53248
	ds_read_b128 v[206:209], v187 offset:54272
	ds_read_b128 v[210:213], v187 offset:55296
	ds_read_b128 v[214:217], v187 offset:56320
	global_load_lds_dwordx4 v[218:219], off
	s_add_i32 m0, s56, 0x2000
	s_add_u32 s54, s54, 0x80080
	v_lshl_add_u64 v[218:219], v[220:221], 0, s[14:15]
	s_addc_u32 s55, s55, 0
	s_add_i32 s56, s86, s60
	global_load_lds_dwordx4 v[218:219], off
	s_mov_b32 m0, s56
	s_nop 0
	global_load_lds_dwordx4 v130, s[54:55]
	s_add_i32 m0, s56, 0x2000
	s_nop 0
	global_load_lds_dwordx4 v134, s[54:55]
	v_lshl_add_u64 v[218:219], v[222:223], 0, s[14:15]
	s_mov_b32 m0, s65
	s_nop 0
	global_load_lds_dwordx4 v[218:219], off
	v_lshl_add_u64 v[218:219], v[224:225], 0, s[14:15]
	s_mov_b32 m0, s66
	s_nop 0
	global_load_lds_dwordx4 v[218:219], off
	s_waitcnt vmcnt(8) lgkmcnt(0)
	s_barrier
	s_setprio 1
	v_mfma_f32_16x16x32_bf16 v[60:63], v[150:153], v[182:185], v[60:63]
	v_mfma_f32_16x16x32_bf16 v[56:59], v[158:161], v[182:185], v[56:59]
	v_mfma_f32_16x16x32_bf16 v[52:55], v[150:153], v[194:197], v[52:55]
	v_mfma_f32_16x16x32_bf16 v[48:51], v[158:161], v[194:197], v[48:51]
	v_mfma_f32_16x16x32_bf16 v[44:47], v[150:153], v[202:205], v[44:47]
	v_mfma_f32_16x16x32_bf16 v[40:43], v[158:161], v[202:205], v[40:43]
	v_mfma_f32_16x16x32_bf16 v[36:39], v[150:153], v[210:213], v[36:39]
	v_mfma_f32_16x16x32_bf16 v[32:35], v[158:161], v[210:213], v[32:35]
	v_mfma_f32_16x16x32_bf16 v[60:63], v[154:157], v[190:193], v[60:63]
	v_mfma_f32_16x16x32_bf16 v[56:59], v[162:165], v[190:193], v[56:59]
	v_mfma_f32_16x16x32_bf16 v[52:55], v[154:157], v[198:201], v[52:55]
	v_mfma_f32_16x16x32_bf16 v[48:51], v[162:165], v[198:201], v[48:51]
	v_mfma_f32_16x16x32_bf16 v[44:47], v[154:157], v[206:209], v[44:47]
	v_mfma_f32_16x16x32_bf16 v[40:43], v[162:165], v[206:209], v[40:43]
	v_mfma_f32_16x16x32_bf16 v[36:39], v[154:157], v[214:217], v[36:39]
	v_mfma_f32_16x16x32_bf16 v[32:35], v[162:165], v[214:217], v[32:35]
	v_mfma_f32_16x16x32_bf16 v[28:31], v[166:169], v[182:185], v[28:31]
	v_mfma_f32_16x16x32_bf16 v[24:27], v[174:177], v[182:185], v[24:27]
	v_mfma_f32_16x16x32_bf16 v[20:23], v[166:169], v[194:197], v[20:23]
	v_mfma_f32_16x16x32_bf16 v[16:19], v[174:177], v[194:197], v[16:19]
	v_mfma_f32_16x16x32_bf16 v[12:15], v[166:169], v[202:205], v[12:15]
	v_mfma_f32_16x16x32_bf16 v[8:11], v[174:177], v[202:205], v[8:11]
	v_mfma_f32_16x16x32_bf16 v[4:7], v[166:169], v[210:213], v[4:7]
	v_mfma_f32_16x16x32_bf16 v[0:3], v[174:177], v[210:213], v[0:3]
	v_mfma_f32_16x16x32_bf16 v[28:31], v[170:173], v[190:193], v[28:31]
	v_mfma_f32_16x16x32_bf16 v[24:27], v[178:181], v[190:193], v[24:27]
	v_mfma_f32_16x16x32_bf16 v[20:23], v[170:173], v[198:201], v[20:23]
	v_mfma_f32_16x16x32_bf16 v[16:19], v[178:181], v[198:201], v[16:19]
	v_mfma_f32_16x16x32_bf16 v[12:15], v[170:173], v[206:209], v[12:15]
	v_mfma_f32_16x16x32_bf16 v[8:11], v[178:181], v[206:209], v[8:11]
	v_mfma_f32_16x16x32_bf16 v[4:7], v[170:173], v[214:217], v[4:7]
	v_mfma_f32_16x16x32_bf16 v[0:3], v[178:181], v[214:217], v[0:3]
	s_setprio 0
	s_barrier
	s_add_i32 s82, s82, 2
	s_add_u32 s46, s46, 0x100
	s_addc_u32 s47, s47, 0
	s_add_u32 s80, s80, 0x100
	s_addc_u32 s81, s81, 0
	s_cmp_gt_u32 s82, 13
	s_cbranch_scc0 .LBB0_795
	s_and_b64 vcc, exec, s[16:17]
	s_cbranch_vccz .LBB0_798
	s_barrier

; #define PG8_STAGE(bufoff, gbase, voff) do { _Pragma("unroll") for (int _i = 0; _i < 2; ++_i) \
;         __builtin_amdgcn_global_load_lds((const unsigned*)((const char*)(gbase) + (voff)[_i]), (PG8_LAS unsigned*)(lds + (bufoff) + ldsw + _i * 8192), 16, 0, 0); } while (0)
; #define PG8_LDA(dst, b, h) do { _Pragma("unroll") for (int m = 0; m < 4; ++m) _Pragma("unroll") for (int k = 0; k < 2; ++k) dst[m][k] = *(const PG8_LAS bf16x8*)(lds + PG8_SA(b, h) + aoff + m * 2048 + k * 1024); } while (0)
; #define PG8_LDB(dst, b, h) do { _Pragma("unroll") for (int n = 0; n < 2; ++n) _Pragma("unroll") for (int k = 0; k < 2; ++k) dst[n][k] = *(const PG8_LAS bf16x8*)(lds + PG8_SB(b, h) + boff + n * 2048 + k * 1024); } while (0)
; #define PG8_MMA(ai, bj, At, Bt) do { __builtin_amdgcn_s_setprio(1); _Pragma("unroll") for (int m = 0; m < 4; ++m) _Pragma("unroll") for (int n = 0; n < 2; ++n) _Pragma("unroll") for (int k = 0; k < 2; ++k) \
;         acc[ai][bj][m][n] = __builtin_amdgcn_mfma_f32_16x16x32_bf16(Bt[n][k], At[m][k], acc[ai][bj][m][n], 0, 0, 0); __builtin_amdgcn_s_setprio(0); } while (0)
; #define PG8_WAIT_V(n) asm volatile("s_waitcnt vmcnt(" #n ")" ::: "memory")
; #define PG8_WAIT_L(n) asm volatile("s_waitcnt lgkmcnt(" #n ")" ::: "memory")
; #define PG8_BAR __builtin_amdgcn_s_barrier()
; #define PG8_SCHED __builtin_amdgcn_sched_barrier(0)
; template <class Epi, class Sched, bool ALIGN_EPI = false, bool SP2 = false>
; __device__ __forceinline__ void gemm_phase(PG8_LAS unsigned char* lds, const Gemm g, const Sched& S, const Epi& E) {
;     ...
;             PG8_LDB(B0, 0, 0); PG8_LDB(B1, 0, 1); PG8_SCHED; PG8_LDA(At, 0, 0); PG8_STAGE(PG8_SA(1, 1), a1 + hstep, voffA);
;             PG8_WAIT_V(8); PG8_WAIT_L(0); PG8_BAR; PG8_MMA(0, 0, At, B0); PG8_MMA(0, 1, At, B1); PG8_BAR; PG8_SCHED;
;             PG8_LDA(At, 0, 1); PG8_STAGE(PG8_SB(0, 0), b2, voffB); PG8_STAGE(PG8_SB(0, 1), b2 + hstep, voffB); PG8_STAGE(PG8_SA(0, 0), a2, voffA);
;             PG8_WAIT_V(8); PG8_WAIT_L(0); PG8_BAR; PG8_MMA(1, 0, At, B0); PG8_MMA(1, 1, At, B1); PG8_BAR; PG8_SCHED;
.LBB0_882:
	ds_read_b128 v[128:131], v173
	ds_read_b128 v[132:135], v173 offset:1024
	ds_read_b128 v[136:139], v173 offset:2048
	ds_read_b128 v[140:143], v173 offset:3072
	ds_read_b128 v[164:167], v174
	ds_read_b128 v[168:171], v174 offset:1024
	ds_read_b128 v[178:181], v174 offset:2048
	ds_read_b128 v[182:185], v174 offset:3072
	s_add_u32 s34, s30, 0xfffc0080
	s_addc_u32 s35, s31, -1
	s_cmp_eq_u32 s61, 12
	s_cselect_b32 s37, s23, s35
	s_cselect_b32 s36, s29, s34
	s_cselect_b32 s35, s21, s60
	s_cselect_b32 s34, s58, s59
	s_add_i32 m0, s43, 0xc000
	ds_read_b128 v[190:193], v175
	ds_read_b128 v[194:197], v175 offset:1024
	ds_read_b128 v[198:201], v175 offset:2048
	ds_read_b128 v[202:205], v175 offset:3072
	ds_read_b128 v[206:209], v175 offset:4096
	ds_read_b128 v[210:213], v175 offset:5120
	ds_read_b128 v[214:217], v175 offset:6144
	ds_read_b128 v[218:221], v175 offset:7168
	global_load_lds_dwordx4 v156, s[30:31]
	s_add_i32 m0, s43, 0xe000
	s_nop 0
	global_load_lds_dwordx4 v158, s[30:31]
	s_waitcnt vmcnt(8) lgkmcnt(0)
	s_barrier
	s_setprio 1
	v_mfma_f32_16x16x32_bf16 v[124:127], v[128:131], v[190:193], v[124:127]
	v_mfma_f32_16x16x32_bf16 v[120:123], v[136:139], v[190:193], v[120:123]
	v_mfma_f32_16x16x32_bf16 v[108:111], v[128:131], v[198:201], v[108:111]
	v_mfma_f32_16x16x32_bf16 v[104:107], v[136:139], v[198:201], v[104:107]
	v_mfma_f32_16x16x32_bf16 v[92:95], v[128:131], v[206:209], v[92:95]
	v_mfma_f32_16x16x32_bf16 v[88:91], v[136:139], v[206:209], v[88:91]
	v_mfma_f32_16x16x32_bf16 v[76:79], v[128:131], v[214:217], v[76:79]
	v_mfma_f32_16x16x32_bf16 v[72:75], v[136:139], v[214:217], v[72:75]
	v_mfma_f32_16x16x32_bf16 v[124:127], v[132:135], v[194:197], v[124:127]
	v_mfma_f32_16x16x32_bf16 v[120:123], v[140:143], v[194:197], v[120:123]
	v_mfma_f32_16x16x32_bf16 v[108:111], v[132:135], v[202:205], v[108:111]
	v_mfma_f32_16x16x32_bf16 v[104:107], v[140:143], v[202:205], v[104:107]
	v_mfma_f32_16x16x32_bf16 v[92:95], v[132:135], v[210:213], v[92:95]
	v_mfma_f32_16x16x32_bf16 v[88:91], v[140:143], v[210:213], v[88:91]
	v_mfma_f32_16x16x32_bf16 v[76:79], v[132:135], v[218:221], v[76:79]
	v_mfma_f32_16x16x32_bf16 v[72:75], v[140:143], v[218:221], v[72:75]
	v_mfma_f32_16x16x32_bf16 v[116:119], v[164:167], v[190:193], v[116:119]
	v_mfma_f32_16x16x32_bf16 v[112:115], v[178:181], v[190:193], v[112:115]
	v_mfma_f32_16x16x32_bf16 v[100:103], v[164:167], v[198:201], v[100:103]
	v_mfma_f32_16x16x32_bf16 v[96:99], v[178:181], v[198:201], v[96:99]
	v_mfma_f32_16x16x32_bf16 v[84:87], v[164:167], v[206:209], v[84:87]
	v_mfma_f32_16x16x32_bf16 v[80:83], v[178:181], v[206:209], v[80:83]
	v_mfma_f32_16x16x32_bf16 v[68:71], v[164:167], v[214:217], v[68:71]
	v_mfma_f32_16x16x32_bf16 v[64:67], v[178:181], v[214:217], v[64:67]
	v_mfma_f32_16x16x32_bf16 v[116:119], v[168:171], v[194:197], v[116:119]
	v_mfma_f32_16x16x32_bf16 v[112:115], v[182:185], v[194:197], v[112:115]
	v_mfma_f32_16x16x32_bf16 v[100:103], v[168:171], v[202:205], v[100:103]
	v_mfma_f32_16x16x32_bf16 v[96:99], v[182:185], v[202:205], v[96:99]
	v_mfma_f32_16x16x32_bf16 v[84:87], v[168:171], v[210:213], v[84:87]
	v_mfma_f32_16x16x32_bf16 v[80:83], v[182:185], v[210:213], v[80:83]
	v_mfma_f32_16x16x32_bf16 v[68:71], v[168:171], v[218:221], v[68:71]
	v_mfma_f32_16x16x32_bf16 v[64:67], v[182:185], v[218:221], v[64:67]
	s_setprio 0
	s_barrier
	s_add_i32 s62, s55, s42
	v_lshl_add_u64 v[186:187], s[34:35], 0, v[146:147]
	s_mov_b32 m0, s62
	ds_read_b128 v[190:193], v175 offset:16384
	ds_read_b128 v[194:197], v175 offset:17408
	ds_read_b128 v[198:201], v175 offset:18432
	ds_read_b128 v[202:205], v175 offset:19456
	ds_read_b128 v[206:209], v175 offset:20480
	ds_read_b128 v[210:213], v175 offset:21504
	ds_read_b128 v[214:217], v175 offset:22528
	ds_read_b128 v[218:221], v175 offset:23552
	global_load_lds_dwordx4 v[186:187], off
	s_add_i32 m0, s62, 0x2000
	s_add_u32 s62, s34, 0x40000
	v_lshl_add_u64 v[222:223], s[34:35], 0, v[150:151]
	s_addc_u32 s63, s35, 0
	s_add_i32 s64, s56, s42
	global_load_lds_dwordx4 v[222:223], off
	s_mov_b32 m0, s64
	v_lshl_add_u64 v[226:227], s[36:37], 0, v[148:149]
	global_load_lds_dwordx4 v146, s[62:63]
	s_add_i32 m0, s64, 0x2000
	s_nop 0
	global_load_lds_dwordx4 v150, s[62:63]
	v_lshl_add_u64 v[224:225], s[36:37], 0, v[144:145]
	s_mov_b32 m0, s43
	s_nop 0
	global_load_lds_dwordx4 v[224:225], off
	s_mov_b32 m0, s44
	s_nop 0
	global_load_lds_dwordx4 v[226:227], off
	s_waitcnt vmcnt(8) lgkmcnt(0)
	s_barrier
	s_setprio 1
	v_mfma_f32_16x16x32_bf16 v[60:63], v[128:131], v[190:193], v[60:63]
	v_mfma_f32_16x16x32_bf16 v[56:59], v[136:139], v[190:193], v[56:59]
	v_mfma_f32_16x16x32_bf16 v[44:47], v[128:131], v[198:201], v[44:47]
	v_mfma_f32_16x16x32_bf16 v[40:43], v[136:139], v[198:201], v[40:43]
	v_mfma_f32_16x16x32_bf16 v[28:31], v[128:131], v[206:209], v[28:31]
	v_mfma_f32_16x16x32_bf16 v[24:27], v[136:139], v[206:209], v[24:27]
	v_mfma_f32_16x16x32_bf16 v[12:15], v[128:131], v[214:217], v[12:15]
	v_mfma_f32_16x16x32_bf16 v[8:11], v[136:139], v[214:217], v[8:11]
	v_mfma_f32_16x16x32_bf16 v[60:63], v[132:135], v[194:197], v[60:63]
	v_mfma_f32_16x16x32_bf16 v[56:59], v[140:143], v[194:197], v[56:59]
	v_mfma_f32_16x16x32_bf16 v[44:47], v[132:135], v[202:205], v[44:47]
	v_mfma_f32_16x16x32_bf16 v[40:43], v[140:143], v[202:205], v[40:43]
	v_mfma_f32_16x16x32_bf16 v[28:31], v[132:135], v[210:213], v[28:31]
	v_mfma_f32_16x16x32_bf16 v[24:27], v[140:143], v[210:213], v[24:27]
	v_mfma_f32_16x16x32_bf16 v[12:15], v[132:135], v[218:221], v[12:15]
	v_mfma_f32_16x16x32_bf16 v[8:11], v[140:143], v[218:221], v[8:11]
	v_mfma_f32_16x16x32_bf16 v[52:55], v[164:167], v[190:193], v[52:55]
	v_mfma_f32_16x16x32_bf16 v[48:51], v[178:181], v[190:193], v[48:51]
	v_mfma_f32_16x16x32_bf16 v[36:39], v[164:167], v[198:201], v[36:39]
	v_mfma_f32_16x16x32_bf16 v[32:35], v[178:181], v[198:201], v[32:35]
	v_mfma_f32_16x16x32_bf16 v[20:23], v[164:167], v[206:209], v[20:23]
	v_mfma_f32_16x16x32_bf16 v[16:19], v[178:181], v[206:209], v[16:19]
	v_mfma_f32_16x16x32_bf16 v[4:7], v[164:167], v[214:217], v[4:7]
	v_mfma_f32_16x16x32_bf16 v[0:3], v[178:181], v[214:217], v[0:3]
	v_mfma_f32_16x16x32_bf16 v[52:55], v[168:171], v[194:197], v[52:55]
	v_mfma_f32_16x16x32_bf16 v[48:51], v[182:185], v[194:197], v[48:51]
	v_mfma_f32_16x16x32_bf16 v[36:39], v[168:171], v[202:205], v[36:39]
	v_mfma_f32_16x16x32_bf16 v[32:35], v[182:185], v[202:205], v[32:35]
	v_mfma_f32_16x16x32_bf16 v[20:23], v[168:171], v[210:213], v[20:23]
	v_mfma_f32_16x16x32_bf16 v[16:19], v[182:185], v[210:213], v[16:19]
	v_mfma_f32_16x16x32_bf16 v[4:7], v[168:171], v[218:221], v[4:7]
	v_mfma_f32_16x16x32_bf16 v[0:3], v[182:185], v[218:221], v[0:3]
	s_setprio 0
	s_barrier
; #define PG8_STAGE(bufoff, gbase, voff) do { _Pragma("unroll") for (int _i = 0; _i < 2; ++_i) \
;         __builtin_amdgcn_global_load_lds((const unsigned*)((const char*)(gbase) + (voff)[_i]), (PG8_LAS unsigned*)(lds + (bufoff) + ldsw + _i * 8192), 16, 0, 0); } while (0)
; #define PG8_LDA(dst, b, h) do { _Pragma("unroll") for (int m = 0; m < 4; ++m) _Pragma("unroll") for (int k = 0; k < 2; ++k) dst[m][k] = *(const PG8_LAS bf16x8*)(lds + PG8_SA(b, h) + aoff + m * 2048 + k * 1024); } while (0)
; #define PG8_LDB(dst, b, h) do { _Pragma("unroll") for (int n = 0; n < 2; ++n) _Pragma("unroll") for (int k = 0; k < 2; ++k) dst[n][k] = *(const PG8_LAS bf16x8*)(lds + PG8_SB(b, h) + boff + n * 2048 + k * 1024); } while (0)
; #define PG8_MMA(ai, bj, At, Bt) do { __builtin_amdgcn_s_setprio(1); _Pragma("unroll") for (int m = 0; m < 4; ++m) _Pragma("unroll") for (int n = 0; n < 2; ++n) _Pragma("unroll") for (int k = 0; k < 2; ++k) \
;         acc[ai][bj][m][n] = __builtin_amdgcn_mfma_f32_16x16x32_bf16(Bt[n][k], At[m][k], acc[ai][bj][m][n], 0, 0, 0); __builtin_amdgcn_s_setprio(0); } while (0)
; #define PG8_WAIT_V(n) asm volatile("s_waitcnt vmcnt(" #n ")" ::: "memory")
; #define PG8_WAIT_L(n) asm volatile("s_waitcnt lgkmcnt(" #n ")" ::: "memory")
; #define PG8_BAR __builtin_amdgcn_s_barrier()
; #define PG8_SCHED __builtin_amdgcn_sched_barrier(0)
; template <class Epi, class Sched, bool ALIGN_EPI = false, bool SP2 = false>
; __device__ __forceinline__ void gemm_phase(PG8_LAS unsigned char* lds, const Gemm g, const Sched& S, const Epi& E) {
;     ...
;             PG8_LDB(B0, 1, 0); PG8_LDB(B1, 1, 1); PG8_SCHED; PG8_LDA(At, 1, 0); PG8_STAGE(PG8_SA(0, 1), a2 + hstep, voffA);
;             PG8_WAIT_V(8); PG8_WAIT_L(0); PG8_BAR; PG8_MMA(0, 0, At, B0); PG8_MMA(0, 1, At, B1); PG8_BAR; PG8_SCHED;
;             PG8_LDA(At, 1, 1); PG8_STAGE(PG8_SB(1, 0), b3, voffB); PG8_STAGE(PG8_SB(1, 1), b3 + hstep, voffB); PG8_STAGE(PG8_SA(1, 0), a3, voffA);
;             PG8_WAIT_V(8); PG8_WAIT_L(0); PG8_BAR; PG8_MMA(1, 0, At, B0); PG8_MMA(1, 1, At, B1); PG8_BAR; PG8_SCHED;
;     ...
;         if constexpr (ALIGN_EPI) { if (wr == 0) PG8_BAR; }
	s_add_i32 s62, 0, 0x18000
	s_add_i32 s63, 0, 0x1c000
	v_add_u32_e32 v140, s62, v172
	v_add_u32_e32 v177, s63, v172
	ds_read_b128 v[128:131], v140
	ds_read_b128 v[132:135], v140 offset:1024
	ds_read_b128 v[136:139], v140 offset:2048
	ds_read_b128 v[140:143], v140 offset:3072
	ds_read_b128 v[164:167], v177
	ds_read_b128 v[168:171], v177 offset:1024
	ds_read_b128 v[178:181], v177 offset:2048
	ds_read_b128 v[182:185], v177 offset:3072
	s_add_u32 s36, s36, 0x40000
	s_addc_u32 s37, s37, 0
	s_mov_b32 m0, s45
	ds_read_b128 v[190:193], v175 offset:32768
	ds_read_b128 v[194:197], v175 offset:33792
	ds_read_b128 v[198:201], v175 offset:34816
	ds_read_b128 v[202:205], v175 offset:35840
	ds_read_b128 v[206:209], v175 offset:36864
	ds_read_b128 v[210:213], v175 offset:37888
	ds_read_b128 v[214:217], v175 offset:38912
	ds_read_b128 v[218:221], v175 offset:39936
	global_load_lds_dwordx4 v144, s[36:37]
	s_mov_b32 m0, s46
	s_nop 0
	global_load_lds_dwordx4 v148, s[36:37]
	s_waitcnt vmcnt(8) lgkmcnt(0)
	s_barrier
	s_setprio 1
	v_mfma_f32_16x16x32_bf16 v[124:127], v[128:131], v[190:193], v[124:127]
	v_mfma_f32_16x16x32_bf16 v[120:123], v[136:139], v[190:193], v[120:123]
	v_mfma_f32_16x16x32_bf16 v[108:111], v[128:131], v[198:201], v[108:111]
	v_mfma_f32_16x16x32_bf16 v[104:107], v[136:139], v[198:201], v[104:107]
	v_mfma_f32_16x16x32_bf16 v[92:95], v[128:131], v[206:209], v[92:95]
	v_mfma_f32_16x16x32_bf16 v[88:91], v[136:139], v[206:209], v[88:91]
	v_mfma_f32_16x16x32_bf16 v[76:79], v[128:131], v[214:217], v[76:79]
	v_mfma_f32_16x16x32_bf16 v[72:75], v[136:139], v[214:217], v[72:75]
	v_mfma_f32_16x16x32_bf16 v[124:127], v[132:135], v[194:197], v[124:127]
	v_mfma_f32_16x16x32_bf16 v[120:123], v[140:143], v[194:197], v[120:123]
	v_mfma_f32_16x16x32_bf16 v[108:111], v[132:135], v[202:205], v[108:111]
	v_mfma_f32_16x16x32_bf16 v[104:107], v[140:143], v[202:205], v[104:107]
	v_mfma_f32_16x16x32_bf16 v[92:95], v[132:135], v[210:213], v[92:95]
	v_mfma_f32_16x16x32_bf16 v[88:91], v[140:143], v[210:213], v[88:91]
	v_mfma_f32_16x16x32_bf16 v[76:79], v[132:135], v[218:221], v[76:79]
	v_mfma_f32_16x16x32_bf16 v[72:75], v[140:143], v[218:221], v[72:75]
	v_mfma_f32_16x16x32_bf16 v[116:119], v[164:167], v[190:193], v[116:119]
	v_mfma_f32_16x16x32_bf16 v[112:115], v[178:181], v[190:193], v[112:115]
	v_mfma_f32_16x16x32_bf16 v[100:103], v[164:167], v[198:201], v[100:103]
	v_mfma_f32_16x16x32_bf16 v[96:99], v[178:181], v[198:201], v[96:99]
	v_mfma_f32_16x16x32_bf16 v[84:87], v[164:167], v[206:209], v[84:87]
	v_mfma_f32_16x16x32_bf16 v[80:83], v[178:181], v[206:209], v[80:83]
	v_mfma_f32_16x16x32_bf16 v[68:71], v[164:167], v[214:217], v[68:71]
	v_mfma_f32_16x16x32_bf16 v[64:67], v[178:181], v[214:217], v[64:67]
	v_mfma_f32_16x16x32_bf16 v[116:119], v[168:171], v[194:197], v[116:119]
	v_mfma_f32_16x16x32_bf16 v[112:115], v[182:185], v[194:197], v[112:115]
	v_mfma_f32_16x16x32_bf16 v[100:103], v[168:171], v[202:205], v[100:103]
	v_mfma_f32_16x16x32_bf16 v[96:99], v[182:185], v[202:205], v[96:99]
	v_mfma_f32_16x16x32_bf16 v[84:87], v[168:171], v[210:213], v[84:87]
	v_mfma_f32_16x16x32_bf16 v[80:83], v[182:185], v[210:213], v[80:83]
	v_mfma_f32_16x16x32_bf16 v[68:71], v[168:171], v[218:221], v[68:71]
	v_mfma_f32_16x16x32_bf16 v[64:67], v[182:185], v[218:221], v[64:67]
	s_setprio 0
	s_barrier
	s_add_i32 s36, s62, s42
	v_lshl_add_u64 v[186:187], v[186:187], 0, s[16:17]
	s_mov_b32 m0, s36
	ds_read_b128 v[190:193], v175 offset:49152
	ds_read_b128 v[194:197], v175 offset:50176
	ds_read_b128 v[198:201], v175 offset:51200
	ds_read_b128 v[202:205], v175 offset:52224
	ds_read_b128 v[206:209], v175 offset:53248
	ds_read_b128 v[210:213], v175 offset:54272
	ds_read_b128 v[214:217], v175 offset:55296
	ds_read_b128 v[218:221], v175 offset:56320
	global_load_lds_dwordx4 v[186:187], off
	s_add_i32 m0, s36, 0x2000
	s_add_u32 s34, s34, 0x40080
	v_lshl_add_u64 v[186:187], v[222:223], 0, s[16:17]
	s_addc_u32 s35, s35, 0
	s_add_i32 s36, s63, s42
	global_load_lds_dwordx4 v[186:187], off
	s_mov_b32 m0, s36
	s_nop 0
	global_load_lds_dwordx4 v146, s[34:35]
	s_add_i32 m0, s36, 0x2000
	s_nop 0
	global_load_lds_dwordx4 v150, s[34:35]
	v_lshl_add_u64 v[186:187], v[224:225], 0, s[16:17]
	s_mov_b32 m0, s48
	s_nop 0
	global_load_lds_dwordx4 v[186:187], off
	v_lshl_add_u64 v[186:187], v[226:227], 0, s[16:17]
	s_mov_b32 m0, s49
	s_nop 0
	global_load_lds_dwordx4 v[186:187], off
	s_waitcnt vmcnt(8) lgkmcnt(0)
	s_barrier
	s_setprio 1
	v_mfma_f32_16x16x32_bf16 v[60:63], v[128:131], v[190:193], v[60:63]
	v_mfma_f32_16x16x32_bf16 v[56:59], v[136:139], v[190:193], v[56:59]
	v_mfma_f32_16x16x32_bf16 v[44:47], v[128:131], v[198:201], v[44:47]
	v_mfma_f32_16x16x32_bf16 v[40:43], v[136:139], v[198:201], v[40:43]
	v_mfma_f32_16x16x32_bf16 v[28:31], v[128:131], v[206:209], v[28:31]
	v_mfma_f32_16x16x32_bf16 v[24:27], v[136:139], v[206:209], v[24:27]
	v_mfma_f32_16x16x32_bf16 v[12:15], v[128:131], v[214:217], v[12:15]
	v_mfma_f32_16x16x32_bf16 v[8:11], v[136:139], v[214:217], v[8:11]
	v_mfma_f32_16x16x32_bf16 v[60:63], v[132:135], v[194:197], v[60:63]
	v_mfma_f32_16x16x32_bf16 v[56:59], v[140:143], v[194:197], v[56:59]
	v_mfma_f32_16x16x32_bf16 v[44:47], v[132:135], v[202:205], v[44:47]
	v_mfma_f32_16x16x32_bf16 v[40:43], v[140:143], v[202:205], v[40:43]
	v_mfma_f32_16x16x32_bf16 v[28:31], v[132:135], v[210:213], v[28:31]
	v_mfma_f32_16x16x32_bf16 v[24:27], v[140:143], v[210:213], v[24:27]
	v_mfma_f32_16x16x32_bf16 v[12:15], v[132:135], v[218:221], v[12:15]
	v_mfma_f32_16x16x32_bf16 v[8:11], v[140:143], v[218:221], v[8:11]
	v_mfma_f32_16x16x32_bf16 v[52:55], v[164:167], v[190:193], v[52:55]
	v_mfma_f32_16x16x32_bf16 v[48:51], v[178:181], v[190:193], v[48:51]
	v_mfma_f32_16x16x32_bf16 v[36:39], v[164:167], v[198:201], v[36:39]
	v_mfma_f32_16x16x32_bf16 v[32:35], v[178:181], v[198:201], v[32:35]
	v_mfma_f32_16x16x32_bf16 v[20:23], v[164:167], v[206:209], v[20:23]
	v_mfma_f32_16x16x32_bf16 v[16:19], v[178:181], v[206:209], v[16:19]
	v_mfma_f32_16x16x32_bf16 v[4:7], v[164:167], v[214:217], v[4:7]
	v_mfma_f32_16x16x32_bf16 v[0:3], v[178:181], v[214:217], v[0:3]
	v_mfma_f32_16x16x32_bf16 v[52:55], v[168:171], v[194:197], v[52:55]
	v_mfma_f32_16x16x32_bf16 v[48:51], v[182:185], v[194:197], v[48:51]
	v_mfma_f32_16x16x32_bf16 v[36:39], v[168:171], v[202:205], v[36:39]
	v_mfma_f32_16x16x32_bf16 v[32:35], v[182:185], v[202:205], v[32:35]
	v_mfma_f32_16x16x32_bf16 v[20:23], v[168:171], v[210:213], v[20:23]
	v_mfma_f32_16x16x32_bf16 v[16:19], v[182:185], v[210:213], v[16:19]
	v_mfma_f32_16x16x32_bf16 v[4:7], v[168:171], v[218:221], v[4:7]
	v_mfma_f32_16x16x32_bf16 v[0:3], v[182:185], v[218:221], v[0:3]
	s_setprio 0
	s_barrier
	s_add_i32 s61, s61, 2
	s_add_u32 s30, s30, 0x100
	s_addc_u32 s31, s31, 0
	s_add_u32 s59, s59, 0x100
	s_addc_u32 s60, s60, 0
	s_cmp_gt_u32 s61, 13
	s_cbranch_scc0 .LBB0_882
	s_and_b64 vcc, exec, s[18:19]
	s_cbranch_vccz .LBB0_885
	s_barrier

; #define PG8_STAGE(bufoff, gbase, voff) do { _Pragma("unroll") for (int _i = 0; _i < 2; ++_i) \
;         __builtin_amdgcn_global_load_lds((const unsigned*)((const char*)(gbase) + (voff)[_i]), (PG8_LAS unsigned*)(lds + (bufoff) + ldsw + _i * 8192), 16, 0, 0); } while (0)
; #define PG8_LDA(dst, b, h) do { _Pragma("unroll") for (int m = 0; m < 4; ++m) _Pragma("unroll") for (int k = 0; k < 2; ++k) dst[m][k] = *(const PG8_LAS bf16x8*)(lds + PG8_SA(b, h) + aoff + m * 2048 + k * 1024); } while (0)
; #define PG8_LDB(dst, b, h) do { _Pragma("unroll") for (int n = 0; n < 2; ++n) _Pragma("unroll") for (int k = 0; k < 2; ++k) dst[n][k] = *(const PG8_LAS bf16x8*)(lds + PG8_SB(b, h) + boff + n * 2048 + k * 1024); } while (0)
; #define PG8_MMA(ai, bj, At, Bt) do { __builtin_amdgcn_s_setprio(1); _Pragma("unroll") for (int m = 0; m < 4; ++m) _Pragma("unroll") for (int n = 0; n < 2; ++n) _Pragma("unroll") for (int k = 0; k < 2; ++k) \
;         acc[ai][bj][m][n] = __builtin_amdgcn_mfma_f32_16x16x32_bf16(Bt[n][k], At[m][k], acc[ai][bj][m][n], 0, 0, 0); __builtin_amdgcn_s_setprio(0); } while (0)
; #define PG8_WAIT_V(n) asm volatile("s_waitcnt vmcnt(" #n ")" ::: "memory")
; #define PG8_WAIT_L(n) asm volatile("s_waitcnt lgkmcnt(" #n ")" ::: "memory")
; #define PG8_BAR __builtin_amdgcn_s_barrier()
; #define PG8_SCHED __builtin_amdgcn_sched_barrier(0)
; template <class Epi, class Sched, bool ALIGN_EPI = false, bool SP2 = false>
; __device__ __forceinline__ void gemm_phase(PG8_LAS unsigned char* lds, const Gemm g, const Sched& S, const Epi& E) {
;     ...
;             PG8_LDB(B0, 0, 0); PG8_LDB(B1, 0, 1); PG8_SCHED; PG8_LDA(At, 0, 0); PG8_STAGE(PG8_SA(1, 1), a1 + hstep, voffA);
;             PG8_WAIT_V(8); PG8_WAIT_L(0); PG8_BAR; PG8_MMA(0, 0, At, B0); PG8_MMA(0, 1, At, B1); PG8_BAR; PG8_SCHED;
;             PG8_LDA(At, 0, 1); PG8_STAGE(PG8_SB(0, 0), b2, voffB); PG8_STAGE(PG8_SB(0, 1), b2 + hstep, voffB); PG8_STAGE(PG8_SA(0, 0), a2, voffA);
;             PG8_WAIT_V(8); PG8_WAIT_L(0); PG8_BAR; PG8_MMA(1, 0, At, B0); PG8_MMA(1, 1, At, B1); PG8_BAR; PG8_SCHED;
.LBB0_969:
	ds_read_b128 v[128:131], v191
	ds_read_b128 v[132:135], v191 offset:1024
	ds_read_b128 v[136:139], v191 offset:2048
	ds_read_b128 v[140:143], v191 offset:3072
	ds_read_b128 v[144:147], v192
	ds_read_b128 v[148:151], v192 offset:1024
	ds_read_b128 v[172:175], v192 offset:2048
	ds_read_b128 v[176:179], v192 offset:3072
	s_add_u32 s26, s24, 0xfffc0080
	s_addc_u32 s27, s25, -1
	s_cmp_eq_u32 s57, 12
	s_cselect_b32 s29, s17, s27
	s_cselect_b32 s28, s51, s26
	s_cselect_b32 s27, s15, s56
	s_cselect_b32 s26, s54, s55
	s_add_i32 m0, s39, 0xc000
	ds_read_b128 v[180:183], v193
	ds_read_b128 v[184:187], v193 offset:1024
	ds_read_b128 v[196:199], v193 offset:2048
	ds_read_b128 v[200:203], v193 offset:3072
	ds_read_b128 v[204:207], v193 offset:4096
	ds_read_b128 v[208:211], v193 offset:5120
	ds_read_b128 v[212:215], v193 offset:6144
	ds_read_b128 v[216:219], v193 offset:7168
	global_load_lds_dwordx4 v164, s[24:25]
	s_add_i32 m0, s39, 0xe000
	s_nop 0
	global_load_lds_dwordx4 v166, s[24:25]
	s_waitcnt vmcnt(8) lgkmcnt(0)
	s_barrier
	s_setprio 1
	v_mfma_f32_16x16x32_bf16 v[124:127], v[128:131], v[180:183], v[124:127]
	v_mfma_f32_16x16x32_bf16 v[120:123], v[136:139], v[180:183], v[120:123]
	v_mfma_f32_16x16x32_bf16 v[108:111], v[128:131], v[196:199], v[108:111]
	v_mfma_f32_16x16x32_bf16 v[104:107], v[136:139], v[196:199], v[104:107]
	v_mfma_f32_16x16x32_bf16 v[92:95], v[128:131], v[204:207], v[92:95]
	v_mfma_f32_16x16x32_bf16 v[84:87], v[136:139], v[204:207], v[84:87]
	v_mfma_f32_16x16x32_bf16 v[76:79], v[128:131], v[212:215], v[76:79]
	v_mfma_f32_16x16x32_bf16 v[72:75], v[136:139], v[212:215], v[72:75]
	v_mfma_f32_16x16x32_bf16 v[124:127], v[132:135], v[184:187], v[124:127]
	v_mfma_f32_16x16x32_bf16 v[120:123], v[140:143], v[184:187], v[120:123]
	v_mfma_f32_16x16x32_bf16 v[108:111], v[132:135], v[200:203], v[108:111]
	v_mfma_f32_16x16x32_bf16 v[104:107], v[140:143], v[200:203], v[104:107]
	v_mfma_f32_16x16x32_bf16 v[92:95], v[132:135], v[208:211], v[92:95]
	v_mfma_f32_16x16x32_bf16 v[84:87], v[140:143], v[208:211], v[84:87]
	v_mfma_f32_16x16x32_bf16 v[76:79], v[132:135], v[216:219], v[76:79]
	v_mfma_f32_16x16x32_bf16 v[72:75], v[140:143], v[216:219], v[72:75]
	v_mfma_f32_16x16x32_bf16 v[116:119], v[144:147], v[180:183], v[116:119]
	v_mfma_f32_16x16x32_bf16 v[112:115], v[172:175], v[180:183], v[112:115]
	v_mfma_f32_16x16x32_bf16 v[100:103], v[144:147], v[196:199], v[100:103]
	v_mfma_f32_16x16x32_bf16 v[96:99], v[172:175], v[196:199], v[96:99]
	v_mfma_f32_16x16x32_bf16 v[88:91], v[144:147], v[204:207], v[88:91]
	v_mfma_f32_16x16x32_bf16 v[80:83], v[172:175], v[204:207], v[80:83]
	v_mfma_f32_16x16x32_bf16 v[68:71], v[144:147], v[212:215], v[68:71]
	v_mfma_f32_16x16x32_bf16 v[64:67], v[172:175], v[212:215], v[64:67]
	v_mfma_f32_16x16x32_bf16 v[116:119], v[148:151], v[184:187], v[116:119]
	v_mfma_f32_16x16x32_bf16 v[112:115], v[176:179], v[184:187], v[112:115]
	v_mfma_f32_16x16x32_bf16 v[100:103], v[148:151], v[200:203], v[100:103]
	v_mfma_f32_16x16x32_bf16 v[96:99], v[176:179], v[200:203], v[96:99]
	v_mfma_f32_16x16x32_bf16 v[88:91], v[148:151], v[208:211], v[88:91]
	v_mfma_f32_16x16x32_bf16 v[80:83], v[176:179], v[208:211], v[80:83]
	v_mfma_f32_16x16x32_bf16 v[68:71], v[148:151], v[216:219], v[68:71]
	v_mfma_f32_16x16x32_bf16 v[64:67], v[176:179], v[216:219], v[64:67]
	s_setprio 0
	s_barrier
	s_add_i32 s58, s47, s36
	v_lshl_add_u64 v[220:221], s[26:27], 0, v[156:157]
	s_mov_b32 m0, s58
	ds_read_b128 v[180:183], v193 offset:16384
	ds_read_b128 v[184:187], v193 offset:17408
	ds_read_b128 v[196:199], v193 offset:18432
	ds_read_b128 v[200:203], v193 offset:19456
	ds_read_b128 v[204:207], v193 offset:20480
	ds_read_b128 v[208:211], v193 offset:21504
	ds_read_b128 v[212:215], v193 offset:22528
	ds_read_b128 v[216:219], v193 offset:23552
	global_load_lds_dwordx4 v[220:221], off
	s_add_i32 m0, s58, 0x2000
	s_add_u32 s58, s26, 0x40000
	v_lshl_add_u64 v[222:223], s[26:27], 0, v[152:153]
	s_addc_u32 s59, s27, 0
	s_add_i32 s60, s48, s36
	global_load_lds_dwordx4 v[222:223], off
	s_mov_b32 m0, s60
	v_lshl_add_u64 v[226:227], s[28:29], 0, v[154:155]
	global_load_lds_dwordx4 v156, s[58:59]
	s_add_i32 m0, s60, 0x2000
	s_nop 0
	global_load_lds_dwordx4 v152, s[58:59]
	v_lshl_add_u64 v[224:225], s[28:29], 0, v[158:159]
	s_mov_b32 m0, s39
	s_nop 0
	global_load_lds_dwordx4 v[224:225], off
	s_mov_b32 m0, s40
	s_nop 0
	global_load_lds_dwordx4 v[226:227], off
	s_waitcnt vmcnt(8) lgkmcnt(0)
	s_barrier
	s_setprio 1
	v_mfma_f32_16x16x32_bf16 v[60:63], v[128:131], v[180:183], v[60:63]
	v_mfma_f32_16x16x32_bf16 v[52:55], v[136:139], v[180:183], v[52:55]
	v_mfma_f32_16x16x32_bf16 v[44:47], v[128:131], v[196:199], v[44:47]
	v_mfma_f32_16x16x32_bf16 v[40:43], v[136:139], v[196:199], v[40:43]
	v_mfma_f32_16x16x32_bf16 v[28:31], v[128:131], v[204:207], v[28:31]
	v_mfma_f32_16x16x32_bf16 v[20:23], v[136:139], v[204:207], v[20:23]
	v_mfma_f32_16x16x32_bf16 v[12:15], v[128:131], v[212:215], v[12:15]
	v_mfma_f32_16x16x32_bf16 v[8:11], v[136:139], v[212:215], v[8:11]
	v_mfma_f32_16x16x32_bf16 v[60:63], v[132:135], v[184:187], v[60:63]
	v_mfma_f32_16x16x32_bf16 v[52:55], v[140:143], v[184:187], v[52:55]
	v_mfma_f32_16x16x32_bf16 v[44:47], v[132:135], v[200:203], v[44:47]
	v_mfma_f32_16x16x32_bf16 v[40:43], v[140:143], v[200:203], v[40:43]
	v_mfma_f32_16x16x32_bf16 v[28:31], v[132:135], v[208:211], v[28:31]
	v_mfma_f32_16x16x32_bf16 v[20:23], v[140:143], v[208:211], v[20:23]
	v_mfma_f32_16x16x32_bf16 v[12:15], v[132:135], v[216:219], v[12:15]
	v_mfma_f32_16x16x32_bf16 v[8:11], v[140:143], v[216:219], v[8:11]
	v_mfma_f32_16x16x32_bf16 v[56:59], v[144:147], v[180:183], v[56:59]
	v_mfma_f32_16x16x32_bf16 v[48:51], v[172:175], v[180:183], v[48:51]
	v_mfma_f32_16x16x32_bf16 v[36:39], v[144:147], v[196:199], v[36:39]
	v_mfma_f32_16x16x32_bf16 v[32:35], v[172:175], v[196:199], v[32:35]
	v_mfma_f32_16x16x32_bf16 v[24:27], v[144:147], v[204:207], v[24:27]
	v_mfma_f32_16x16x32_bf16 v[16:19], v[172:175], v[204:207], v[16:19]
	v_mfma_f32_16x16x32_bf16 v[4:7], v[144:147], v[212:215], v[4:7]
	v_mfma_f32_16x16x32_bf16 v[0:3], v[172:175], v[212:215], v[0:3]
	v_mfma_f32_16x16x32_bf16 v[56:59], v[148:151], v[184:187], v[56:59]
	v_mfma_f32_16x16x32_bf16 v[48:51], v[176:179], v[184:187], v[48:51]
	v_mfma_f32_16x16x32_bf16 v[36:39], v[148:151], v[200:203], v[36:39]
	v_mfma_f32_16x16x32_bf16 v[32:35], v[176:179], v[200:203], v[32:35]
	v_mfma_f32_16x16x32_bf16 v[24:27], v[148:151], v[208:211], v[24:27]
	v_mfma_f32_16x16x32_bf16 v[16:19], v[176:179], v[208:211], v[16:19]
	v_mfma_f32_16x16x32_bf16 v[4:7], v[148:151], v[216:219], v[4:7]
	v_mfma_f32_16x16x32_bf16 v[0:3], v[176:179], v[216:219], v[0:3]
	s_setprio 0
	s_barrier
; #define PG8_STAGE(bufoff, gbase, voff) do { _Pragma("unroll") for (int _i = 0; _i < 2; ++_i) \
;         __builtin_amdgcn_global_load_lds((const unsigned*)((const char*)(gbase) + (voff)[_i]), (PG8_LAS unsigned*)(lds + (bufoff) + ldsw + _i * 8192), 16, 0, 0); } while (0)
; #define PG8_LDA(dst, b, h) do { _Pragma("unroll") for (int m = 0; m < 4; ++m) _Pragma("unroll") for (int k = 0; k < 2; ++k) dst[m][k] = *(const PG8_LAS bf16x8*)(lds + PG8_SA(b, h) + aoff + m * 2048 + k * 1024); } while (0)
; #define PG8_LDB(dst, b, h) do { _Pragma("unroll") for (int n = 0; n < 2; ++n) _Pragma("unroll") for (int k = 0; k < 2; ++k) dst[n][k] = *(const PG8_LAS bf16x8*)(lds + PG8_SB(b, h) + boff + n * 2048 + k * 1024); } while (0)
; #define PG8_MMA(ai, bj, At, Bt) do { __builtin_amdgcn_s_setprio(1); _Pragma("unroll") for (int m = 0; m < 4; ++m) _Pragma("unroll") for (int n = 0; n < 2; ++n) _Pragma("unroll") for (int k = 0; k < 2; ++k) \
;         acc[ai][bj][m][n] = __builtin_amdgcn_mfma_f32_16x16x32_bf16(Bt[n][k], At[m][k], acc[ai][bj][m][n], 0, 0, 0); __builtin_amdgcn_s_setprio(0); } while (0)
; #define PG8_WAIT_V(n) asm volatile("s_waitcnt vmcnt(" #n ")" ::: "memory")
; #define PG8_WAIT_L(n) asm volatile("s_waitcnt lgkmcnt(" #n ")" ::: "memory")
; #define PG8_BAR __builtin_amdgcn_s_barrier()
; #define PG8_SCHED __builtin_amdgcn_sched_barrier(0)
; template <class Epi, class Sched, bool ALIGN_EPI = false, bool SP2 = false>
; __device__ __forceinline__ void gemm_phase(PG8_LAS unsigned char* lds, const Gemm g, const Sched& S, const Epi& E) {
;     ...
;             PG8_LDB(B0, 1, 0); PG8_LDB(B1, 1, 1); PG8_SCHED; PG8_LDA(At, 1, 0); PG8_STAGE(PG8_SA(0, 1), a2 + hstep, voffA);
;             PG8_WAIT_V(8); PG8_WAIT_L(0); PG8_BAR; PG8_MMA(0, 0, At, B0); PG8_MMA(0, 1, At, B1); PG8_BAR; PG8_SCHED;
;             PG8_LDA(At, 1, 1); PG8_STAGE(PG8_SB(1, 0), b3, voffB); PG8_STAGE(PG8_SB(1, 1), b3 + hstep, voffB); PG8_STAGE(PG8_SA(1, 0), a3, voffA);
;             PG8_WAIT_V(8); PG8_WAIT_L(0); PG8_BAR; PG8_MMA(1, 0, At, B0); PG8_MMA(1, 1, At, B1); PG8_BAR; PG8_SCHED;
;     ...
;         if constexpr (ALIGN_EPI) { if (wr == 0) PG8_BAR; }
	s_add_i32 s58, 0, 0x18000
	s_add_i32 s59, 0, 0x1c000
	v_add_u32_e32 v140, s58, v190
	v_add_u32_e32 v176, s59, v190
	ds_read_b128 v[128:131], v140
	ds_read_b128 v[132:135], v140 offset:1024
	ds_read_b128 v[136:139], v140 offset:2048
	ds_read_b128 v[140:143], v140 offset:3072
	ds_read_b128 v[144:147], v176
	ds_read_b128 v[148:151], v176 offset:1024
	ds_read_b128 v[172:175], v176 offset:2048
	ds_read_b128 v[176:179], v176 offset:3072
	s_add_u32 s28, s28, 0x40000
	s_addc_u32 s29, s29, 0
	s_mov_b32 m0, s41
	ds_read_b128 v[180:183], v193 offset:32768
	ds_read_b128 v[184:187], v193 offset:33792
	ds_read_b128 v[196:199], v193 offset:34816
	ds_read_b128 v[200:203], v193 offset:35840
	ds_read_b128 v[204:207], v193 offset:36864
	ds_read_b128 v[208:211], v193 offset:37888
	ds_read_b128 v[212:215], v193 offset:38912
	ds_read_b128 v[216:219], v193 offset:39936
	global_load_lds_dwordx4 v158, s[28:29]
	s_mov_b32 m0, s42
	s_nop 0
	global_load_lds_dwordx4 v154, s[28:29]
	s_waitcnt vmcnt(8) lgkmcnt(0)
	s_barrier
	s_setprio 1
	v_mfma_f32_16x16x32_bf16 v[124:127], v[128:131], v[180:183], v[124:127]
	v_mfma_f32_16x16x32_bf16 v[120:123], v[136:139], v[180:183], v[120:123]
	v_mfma_f32_16x16x32_bf16 v[108:111], v[128:131], v[196:199], v[108:111]
	v_mfma_f32_16x16x32_bf16 v[104:107], v[136:139], v[196:199], v[104:107]
	v_mfma_f32_16x16x32_bf16 v[92:95], v[128:131], v[204:207], v[92:95]
	v_mfma_f32_16x16x32_bf16 v[84:87], v[136:139], v[204:207], v[84:87]
	v_mfma_f32_16x16x32_bf16 v[76:79], v[128:131], v[212:215], v[76:79]
	v_mfma_f32_16x16x32_bf16 v[72:75], v[136:139], v[212:215], v[72:75]
	v_mfma_f32_16x16x32_bf16 v[124:127], v[132:135], v[184:187], v[124:127]
	v_mfma_f32_16x16x32_bf16 v[120:123], v[140:143], v[184:187], v[120:123]
	v_mfma_f32_16x16x32_bf16 v[108:111], v[132:135], v[200:203], v[108:111]
	v_mfma_f32_16x16x32_bf16 v[104:107], v[140:143], v[200:203], v[104:107]
	v_mfma_f32_16x16x32_bf16 v[92:95], v[132:135], v[208:211], v[92:95]
	v_mfma_f32_16x16x32_bf16 v[84:87], v[140:143], v[208:211], v[84:87]
	v_mfma_f32_16x16x32_bf16 v[76:79], v[132:135], v[216:219], v[76:79]
	v_mfma_f32_16x16x32_bf16 v[72:75], v[140:143], v[216:219], v[72:75]
	v_mfma_f32_16x16x32_bf16 v[116:119], v[144:147], v[180:183], v[116:119]
	v_mfma_f32_16x16x32_bf16 v[112:115], v[172:175], v[180:183], v[112:115]
	v_mfma_f32_16x16x32_bf16 v[100:103], v[144:147], v[196:199], v[100:103]
	v_mfma_f32_16x16x32_bf16 v[96:99], v[172:175], v[196:199], v[96:99]
	v_mfma_f32_16x16x32_bf16 v[88:91], v[144:147], v[204:207], v[88:91]
	v_mfma_f32_16x16x32_bf16 v[80:83], v[172:175], v[204:207], v[80:83]
	v_mfma_f32_16x16x32_bf16 v[68:71], v[144:147], v[212:215], v[68:71]
	v_mfma_f32_16x16x32_bf16 v[64:67], v[172:175], v[212:215], v[64:67]
	v_mfma_f32_16x16x32_bf16 v[116:119], v[148:151], v[184:187], v[116:119]
	v_mfma_f32_16x16x32_bf16 v[112:115], v[176:179], v[184:187], v[112:115]
	v_mfma_f32_16x16x32_bf16 v[100:103], v[148:151], v[200:203], v[100:103]
	v_mfma_f32_16x16x32_bf16 v[96:99], v[176:179], v[200:203], v[96:99]
	v_mfma_f32_16x16x32_bf16 v[88:91], v[148:151], v[208:211], v[88:91]
	v_mfma_f32_16x16x32_bf16 v[80:83], v[176:179], v[208:211], v[80:83]
	v_mfma_f32_16x16x32_bf16 v[68:71], v[148:151], v[216:219], v[68:71]
	v_mfma_f32_16x16x32_bf16 v[64:67], v[176:179], v[216:219], v[64:67]
	s_setprio 0
	s_barrier
	s_add_i32 s28, s58, s36
	v_lshl_add_u64 v[220:221], v[220:221], 0, s[10:11]
	s_mov_b32 m0, s28
	ds_read_b128 v[180:183], v193 offset:49152
	ds_read_b128 v[184:187], v193 offset:50176
	ds_read_b128 v[196:199], v193 offset:51200
	ds_read_b128 v[200:203], v193 offset:52224
	ds_read_b128 v[204:207], v193 offset:53248
	ds_read_b128 v[208:211], v193 offset:54272
	ds_read_b128 v[212:215], v193 offset:55296
	ds_read_b128 v[216:219], v193 offset:56320
	global_load_lds_dwordx4 v[220:221], off
	s_add_i32 m0, s28, 0x2000
	s_add_u32 s26, s26, 0x40080
	v_lshl_add_u64 v[220:221], v[222:223], 0, s[10:11]
	s_addc_u32 s27, s27, 0
	s_add_i32 s28, s59, s36
	global_load_lds_dwordx4 v[220:221], off
	s_mov_b32 m0, s28
	s_nop 0
	global_load_lds_dwordx4 v156, s[26:27]
	s_add_i32 m0, s28, 0x2000
	s_nop 0
	global_load_lds_dwordx4 v152, s[26:27]
	v_lshl_add_u64 v[220:221], v[224:225], 0, s[10:11]
	s_mov_b32 m0, s43
	s_nop 0
	global_load_lds_dwordx4 v[220:221], off
	v_lshl_add_u64 v[220:221], v[226:227], 0, s[10:11]
	s_mov_b32 m0, s44
	s_nop 0
	global_load_lds_dwordx4 v[220:221], off
	s_waitcnt vmcnt(8) lgkmcnt(0)
	s_barrier
	s_setprio 1
	v_mfma_f32_16x16x32_bf16 v[60:63], v[128:131], v[180:183], v[60:63]
	v_mfma_f32_16x16x32_bf16 v[52:55], v[136:139], v[180:183], v[52:55]
	v_mfma_f32_16x16x32_bf16 v[44:47], v[128:131], v[196:199], v[44:47]
	v_mfma_f32_16x16x32_bf16 v[40:43], v[136:139], v[196:199], v[40:43]
	v_mfma_f32_16x16x32_bf16 v[28:31], v[128:131], v[204:207], v[28:31]
	v_mfma_f32_16x16x32_bf16 v[20:23], v[136:139], v[204:207], v[20:23]
	v_mfma_f32_16x16x32_bf16 v[12:15], v[128:131], v[212:215], v[12:15]
	v_mfma_f32_16x16x32_bf16 v[8:11], v[136:139], v[212:215], v[8:11]
	v_mfma_f32_16x16x32_bf16 v[60:63], v[132:135], v[184:187], v[60:63]
	v_mfma_f32_16x16x32_bf16 v[52:55], v[140:143], v[184:187], v[52:55]
	v_mfma_f32_16x16x32_bf16 v[44:47], v[132:135], v[200:203], v[44:47]
	v_mfma_f32_16x16x32_bf16 v[40:43], v[140:143], v[200:203], v[40:43]
	v_mfma_f32_16x16x32_bf16 v[28:31], v[132:135], v[208:211], v[28:31]
	v_mfma_f32_16x16x32_bf16 v[20:23], v[140:143], v[208:211], v[20:23]
	v_mfma_f32_16x16x32_bf16 v[12:15], v[132:135], v[216:219], v[12:15]
	v_mfma_f32_16x16x32_bf16 v[8:11], v[140:143], v[216:219], v[8:11]
	v_mfma_f32_16x16x32_bf16 v[56:59], v[144:147], v[180:183], v[56:59]
	v_mfma_f32_16x16x32_bf16 v[48:51], v[172:175], v[180:183], v[48:51]
	v_mfma_f32_16x16x32_bf16 v[36:39], v[144:147], v[196:199], v[36:39]
	v_mfma_f32_16x16x32_bf16 v[32:35], v[172:175], v[196:199], v[32:35]
	v_mfma_f32_16x16x32_bf16 v[24:27], v[144:147], v[204:207], v[24:27]
	v_mfma_f32_16x16x32_bf16 v[16:19], v[172:175], v[204:207], v[16:19]
	v_mfma_f32_16x16x32_bf16 v[4:7], v[144:147], v[212:215], v[4:7]
	v_mfma_f32_16x16x32_bf16 v[0:3], v[172:175], v[212:215], v[0:3]
	v_mfma_f32_16x16x32_bf16 v[56:59], v[148:151], v[184:187], v[56:59]
	v_mfma_f32_16x16x32_bf16 v[48:51], v[176:179], v[184:187], v[48:51]
	v_mfma_f32_16x16x32_bf16 v[36:39], v[148:151], v[200:203], v[36:39]
	v_mfma_f32_16x16x32_bf16 v[32:35], v[176:179], v[200:203], v[32:35]
	v_mfma_f32_16x16x32_bf16 v[24:27], v[148:151], v[208:211], v[24:27]
	v_mfma_f32_16x16x32_bf16 v[16:19], v[176:179], v[208:211], v[16:19]
	v_mfma_f32_16x16x32_bf16 v[4:7], v[148:151], v[216:219], v[4:7]
	v_mfma_f32_16x16x32_bf16 v[0:3], v[176:179], v[216:219], v[0:3]
	s_setprio 0
	s_barrier
	s_add_i32 s57, s57, 2
	s_add_u32 s24, s24, 0x100
	s_addc_u32 s25, s25, 0
	s_add_u32 s55, s55, 0x100
	s_addc_u32 s56, s56, 0
	s_cmp_gt_u32 s57, 13
	s_cbranch_scc0 .LBB0_969
	s_and_b64 vcc, exec, s[12:13]
	s_cbranch_vccz .LBB0_972
	s_barrier

; #define PG8_STAGE(bufoff, gbase, voff) do { _Pragma("unroll") for (int _i = 0; _i < 2; ++_i) \
;         __builtin_amdgcn_global_load_lds((const unsigned*)((const char*)(gbase) + (voff)[_i]), (PG8_LAS unsigned*)(lds + (bufoff) + ldsw + _i * 8192), 16, 0, 0); } while (0)
; #define PG8_LDA(dst, b, h) do { _Pragma("unroll") for (int m = 0; m < 4; ++m) _Pragma("unroll") for (int k = 0; k < 2; ++k) dst[m][k] = *(const PG8_LAS bf16x8*)(lds + PG8_SA(b, h) + aoff + m * 2048 + k * 1024); } while (0)
; #define PG8_LDB(dst, b, h) do { _Pragma("unroll") for (int n = 0; n < 2; ++n) _Pragma("unroll") for (int k = 0; k < 2; ++k) dst[n][k] = *(const PG8_LAS bf16x8*)(lds + PG8_SB(b, h) + boff + n * 2048 + k * 1024); } while (0)
; #define PG8_MMA(ai, bj, At, Bt) do { __builtin_amdgcn_s_setprio(1); _Pragma("unroll") for (int m = 0; m < 4; ++m) _Pragma("unroll") for (int n = 0; n < 2; ++n) _Pragma("unroll") for (int k = 0; k < 2; ++k) \
;         acc[ai][bj][m][n] = __builtin_amdgcn_mfma_f32_16x16x32_bf16(Bt[n][k], At[m][k], acc[ai][bj][m][n], 0, 0, 0); __builtin_amdgcn_s_setprio(0); } while (0)
; #define PG8_WAIT_V(n) asm volatile("s_waitcnt vmcnt(" #n ")" ::: "memory")
; #define PG8_WAIT_L(n) asm volatile("s_waitcnt lgkmcnt(" #n ")" ::: "memory")
; #define PG8_BAR __builtin_amdgcn_s_barrier()
; #define PG8_SCHED __builtin_amdgcn_sched_barrier(0)
; template <class Epi, class Sched, bool ALIGN_EPI = false, bool SP2 = false>
; __device__ __forceinline__ void gemm_phase(PG8_LAS unsigned char* lds, const Gemm g, const Sched& S, const Epi& E) {
;     ...
;             PG8_LDB(B0, 0, 0); PG8_LDB(B1, 0, 1); PG8_SCHED; PG8_LDA(At, 0, 0); PG8_STAGE(PG8_SA(1, 1), a1 + hstep, voffA);
;             PG8_WAIT_V(8); PG8_WAIT_L(0); PG8_BAR; PG8_MMA(0, 0, At, B0); PG8_MMA(0, 1, At, B1); PG8_BAR; PG8_SCHED;
;             PG8_LDA(At, 0, 1); PG8_STAGE(PG8_SB(0, 0), b2, voffB); PG8_STAGE(PG8_SB(0, 1), b2 + hstep, voffB); PG8_STAGE(PG8_SA(0, 0), a2, voffA);
;             PG8_WAIT_V(8); PG8_WAIT_L(0); PG8_BAR; PG8_MMA(1, 0, At, B0); PG8_MMA(1, 1, At, B1); PG8_BAR; PG8_SCHED;
.LBB0_1052:
	ds_read_b128 v[146:149], v153
	ds_read_b128 v[156:159], v153 offset:1024
	ds_read_b128 v[160:163], v153 offset:2048
	ds_read_b128 v[164:167], v153 offset:3072
	ds_read_b128 v[168:171], v154
	ds_read_b128 v[172:175], v154 offset:1024
	ds_read_b128 v[176:179], v154 offset:2048
	ds_read_b128 v[180:183], v154 offset:3072
	s_add_u32 s24, s22, 0x100
	s_addc_u32 s25, s23, 0
	s_cmp_eq_u32 s56, 40
	s_cselect_b32 s29, s3, s25
	s_cselect_b32 s28, s2, s24
	s_cselect_b32 s27, s21, s55
	s_cselect_b32 s26, s20, s54
	s_add_i32 m0, s38, 0xc000
	ds_read_b128 v[184:187], v155
	ds_read_b128 v[188:191], v155 offset:1024
	ds_read_b128 v[192:195], v155 offset:2048
	ds_read_b128 v[196:199], v155 offset:3072
	ds_read_b128 v[200:203], v155 offset:4096
	ds_read_b128 v[204:207], v155 offset:5120
	ds_read_b128 v[208:211], v155 offset:6144
	ds_read_b128 v[212:215], v155 offset:7168
	global_load_lds_dwordx4 v138, s[22:23]
	s_add_i32 m0, s38, 0xe000
	s_nop 0
	global_load_lds_dwordx4 v140, s[22:23]
	s_waitcnt vmcnt(8) lgkmcnt(0)
	s_barrier
	s_setprio 1
	v_mfma_f32_16x16x32_bf16 v[124:127], v[146:149], v[184:187], v[124:127]
	v_mfma_f32_16x16x32_bf16 v[120:123], v[160:163], v[184:187], v[120:123]
	v_mfma_f32_16x16x32_bf16 v[116:119], v[146:149], v[192:195], v[116:119]
	v_mfma_f32_16x16x32_bf16 v[112:115], v[160:163], v[192:195], v[112:115]
	v_mfma_f32_16x16x32_bf16 v[92:95], v[146:149], v[200:203], v[92:95]
	v_mfma_f32_16x16x32_bf16 v[88:91], v[160:163], v[200:203], v[88:91]
	v_mfma_f32_16x16x32_bf16 v[76:79], v[146:149], v[208:211], v[76:79]
	v_mfma_f32_16x16x32_bf16 v[72:75], v[160:163], v[208:211], v[72:75]
	v_mfma_f32_16x16x32_bf16 v[124:127], v[156:159], v[188:191], v[124:127]
	v_mfma_f32_16x16x32_bf16 v[120:123], v[164:167], v[188:191], v[120:123]
	v_mfma_f32_16x16x32_bf16 v[116:119], v[156:159], v[196:199], v[116:119]
	v_mfma_f32_16x16x32_bf16 v[112:115], v[164:167], v[196:199], v[112:115]
	v_mfma_f32_16x16x32_bf16 v[92:95], v[156:159], v[204:207], v[92:95]
	v_mfma_f32_16x16x32_bf16 v[88:91], v[164:167], v[204:207], v[88:91]
	v_mfma_f32_16x16x32_bf16 v[76:79], v[156:159], v[212:215], v[76:79]
	v_mfma_f32_16x16x32_bf16 v[72:75], v[164:167], v[212:215], v[72:75]
	v_mfma_f32_16x16x32_bf16 v[108:111], v[168:171], v[184:187], v[108:111]
	v_mfma_f32_16x16x32_bf16 v[104:107], v[176:179], v[184:187], v[104:107]
	v_mfma_f32_16x16x32_bf16 v[100:103], v[168:171], v[192:195], v[100:103]
	v_mfma_f32_16x16x32_bf16 v[96:99], v[176:179], v[192:195], v[96:99]
	v_mfma_f32_16x16x32_bf16 v[84:87], v[168:171], v[200:203], v[84:87]
	v_mfma_f32_16x16x32_bf16 v[80:83], v[176:179], v[200:203], v[80:83]
	v_mfma_f32_16x16x32_bf16 v[68:71], v[168:171], v[208:211], v[68:71]
	v_mfma_f32_16x16x32_bf16 v[64:67], v[176:179], v[208:211], v[64:67]
	v_mfma_f32_16x16x32_bf16 v[108:111], v[172:175], v[188:191], v[108:111]
	v_mfma_f32_16x16x32_bf16 v[104:107], v[180:183], v[188:191], v[104:107]
	v_mfma_f32_16x16x32_bf16 v[100:103], v[172:175], v[196:199], v[100:103]
	v_mfma_f32_16x16x32_bf16 v[96:99], v[180:183], v[196:199], v[96:99]
	v_mfma_f32_16x16x32_bf16 v[84:87], v[172:175], v[204:207], v[84:87]
	v_mfma_f32_16x16x32_bf16 v[80:83], v[180:183], v[204:207], v[80:83]
	v_mfma_f32_16x16x32_bf16 v[68:71], v[172:175], v[212:215], v[68:71]
	v_mfma_f32_16x16x32_bf16 v[64:67], v[180:183], v[212:215], v[64:67]
	s_setprio 0
	s_barrier
	s_add_i32 s22, s46, s37
	v_lshl_add_u64 v[150:151], s[26:27], 0, v[130:131]
	s_mov_b32 m0, s22
	ds_read_b128 v[184:187], v155 offset:16384
	ds_read_b128 v[188:191], v155 offset:17408
	ds_read_b128 v[192:195], v155 offset:18432
	ds_read_b128 v[196:199], v155 offset:19456
	ds_read_b128 v[200:203], v155 offset:20480
	ds_read_b128 v[204:207], v155 offset:21504
	ds_read_b128 v[208:211], v155 offset:22528
	ds_read_b128 v[212:215], v155 offset:23552
	global_load_lds_dwordx4 v[150:151], off
	s_add_i32 m0, s22, 0x2000
	s_add_u32 s22, s26, 0xb0000
	v_lshl_add_u64 v[216:217], s[26:27], 0, v[134:135]
	s_addc_u32 s23, s27, 0
	s_add_i32 s57, s47, s37
	global_load_lds_dwordx4 v[216:217], off
	s_mov_b32 m0, s57
	v_lshl_add_u64 v[220:221], s[28:29], 0, v[132:133]
	global_load_lds_dwordx4 v130, s[22:23]
	s_add_i32 m0, s57, 0x2000
	s_nop 0
	global_load_lds_dwordx4 v134, s[22:23]
	v_lshl_add_u64 v[218:219], s[28:29], 0, v[128:129]
	s_mov_b32 m0, s38
	s_nop 0
	global_load_lds_dwordx4 v[218:219], off
	s_mov_b32 m0, s39
	s_nop 0
	global_load_lds_dwordx4 v[220:221], off
	s_waitcnt vmcnt(8) lgkmcnt(0)
	s_barrier
	s_setprio 1
	v_mfma_f32_16x16x32_bf16 v[60:63], v[146:149], v[184:187], v[60:63]
	v_mfma_f32_16x16x32_bf16 v[56:59], v[160:163], v[184:187], v[56:59]
	v_mfma_f32_16x16x32_bf16 v[44:47], v[146:149], v[192:195], v[44:47]
	v_mfma_f32_16x16x32_bf16 v[40:43], v[160:163], v[192:195], v[40:43]
	v_mfma_f32_16x16x32_bf16 v[28:31], v[146:149], v[200:203], v[28:31]
	v_mfma_f32_16x16x32_bf16 v[24:27], v[160:163], v[200:203], v[24:27]
	v_mfma_f32_16x16x32_bf16 v[12:15], v[146:149], v[208:211], v[12:15]
	v_mfma_f32_16x16x32_bf16 v[8:11], v[160:163], v[208:211], v[8:11]
	v_mfma_f32_16x16x32_bf16 v[60:63], v[156:159], v[188:191], v[60:63]
	v_mfma_f32_16x16x32_bf16 v[56:59], v[164:167], v[188:191], v[56:59]
	v_mfma_f32_16x16x32_bf16 v[44:47], v[156:159], v[196:199], v[44:47]
	v_mfma_f32_16x16x32_bf16 v[40:43], v[164:167], v[196:199], v[40:43]
	v_mfma_f32_16x16x32_bf16 v[28:31], v[156:159], v[204:207], v[28:31]
	v_mfma_f32_16x16x32_bf16 v[24:27], v[164:167], v[204:207], v[24:27]
	v_mfma_f32_16x16x32_bf16 v[12:15], v[156:159], v[212:215], v[12:15]
	v_mfma_f32_16x16x32_bf16 v[8:11], v[164:167], v[212:215], v[8:11]
	v_mfma_f32_16x16x32_bf16 v[52:55], v[168:171], v[184:187], v[52:55]
	v_mfma_f32_16x16x32_bf16 v[48:51], v[176:179], v[184:187], v[48:51]
	v_mfma_f32_16x16x32_bf16 v[36:39], v[168:171], v[192:195], v[36:39]
	v_mfma_f32_16x16x32_bf16 v[32:35], v[176:179], v[192:195], v[32:35]
	v_mfma_f32_16x16x32_bf16 v[20:23], v[168:171], v[200:203], v[20:23]
	v_mfma_f32_16x16x32_bf16 v[16:19], v[176:179], v[200:203], v[16:19]
	v_mfma_f32_16x16x32_bf16 v[4:7], v[168:171], v[208:211], v[4:7]
	v_mfma_f32_16x16x32_bf16 v[0:3], v[176:179], v[208:211], v[0:3]
	v_mfma_f32_16x16x32_bf16 v[52:55], v[172:175], v[188:191], v[52:55]
	v_mfma_f32_16x16x32_bf16 v[48:51], v[180:183], v[188:191], v[48:51]
	v_mfma_f32_16x16x32_bf16 v[36:39], v[172:175], v[196:199], v[36:39]
	v_mfma_f32_16x16x32_bf16 v[32:35], v[180:183], v[196:199], v[32:35]
	v_mfma_f32_16x16x32_bf16 v[20:23], v[172:175], v[204:207], v[20:23]
	v_mfma_f32_16x16x32_bf16 v[16:19], v[180:183], v[204:207], v[16:19]
	v_mfma_f32_16x16x32_bf16 v[4:7], v[172:175], v[212:215], v[4:7]
	v_mfma_f32_16x16x32_bf16 v[0:3], v[180:183], v[212:215], v[0:3]
	s_setprio 0
	s_barrier
; #define PG8_STAGE(bufoff, gbase, voff) do { _Pragma("unroll") for (int _i = 0; _i < 2; ++_i) \
;         __builtin_amdgcn_global_load_lds((const unsigned*)((const char*)(gbase) + (voff)[_i]), (PG8_LAS unsigned*)(lds + (bufoff) + ldsw + _i * 8192), 16, 0, 0); } while (0)
; #define PG8_LDA(dst, b, h) do { _Pragma("unroll") for (int m = 0; m < 4; ++m) _Pragma("unroll") for (int k = 0; k < 2; ++k) dst[m][k] = *(const PG8_LAS bf16x8*)(lds + PG8_SA(b, h) + aoff + m * 2048 + k * 1024); } while (0)
; #define PG8_LDB(dst, b, h) do { _Pragma("unroll") for (int n = 0; n < 2; ++n) _Pragma("unroll") for (int k = 0; k < 2; ++k) dst[n][k] = *(const PG8_LAS bf16x8*)(lds + PG8_SB(b, h) + boff + n * 2048 + k * 1024); } while (0)
; #define PG8_MMA(ai, bj, At, Bt) do { __builtin_amdgcn_s_setprio(1); _Pragma("unroll") for (int m = 0; m < 4; ++m) _Pragma("unroll") for (int n = 0; n < 2; ++n) _Pragma("unroll") for (int k = 0; k < 2; ++k) \
;         acc[ai][bj][m][n] = __builtin_amdgcn_mfma_f32_16x16x32_bf16(Bt[n][k], At[m][k], acc[ai][bj][m][n], 0, 0, 0); __builtin_amdgcn_s_setprio(0); } while (0)
; #define PG8_WAIT_V(n) asm volatile("s_waitcnt vmcnt(" #n ")" ::: "memory")
; #define PG8_WAIT_L(n) asm volatile("s_waitcnt lgkmcnt(" #n ")" ::: "memory")
; #define PG8_BAR __builtin_amdgcn_s_barrier()
; #define PG8_SCHED __builtin_amdgcn_sched_barrier(0)
; template <class Epi, class Sched, bool ALIGN_EPI = false, bool SP2 = false>
; __device__ __forceinline__ void gemm_phase(PG8_LAS unsigned char* lds, const Gemm g, const Sched& S, const Epi& E) {
;     ...
;             PG8_LDB(B0, 1, 0); PG8_LDB(B1, 1, 1); PG8_SCHED; PG8_LDA(At, 1, 0); PG8_STAGE(PG8_SA(0, 1), a2 + hstep, voffA);
;             PG8_WAIT_V(8); PG8_WAIT_L(0); PG8_BAR; PG8_MMA(0, 0, At, B0); PG8_MMA(0, 1, At, B1); PG8_BAR; PG8_SCHED;
;             PG8_LDA(At, 1, 1); PG8_STAGE(PG8_SB(1, 0), b3, voffB); PG8_STAGE(PG8_SB(1, 1), b3 + hstep, voffB); PG8_STAGE(PG8_SA(1, 0), a3, voffA);
;             PG8_WAIT_V(8); PG8_WAIT_L(0); PG8_BAR; PG8_MMA(1, 0, At, B0); PG8_MMA(1, 1, At, B1); PG8_BAR; PG8_SCHED;
;     ...
;         if constexpr (ALIGN_EPI) { if (wr == 0) PG8_BAR; }
	s_add_i32 s57, 0, 0x18000
	s_add_i32 s58, 0, 0x1c000
	v_add_u32_e32 v164, s57, v152
	v_add_u32_e32 v180, s58, v152
	ds_read_b128 v[146:149], v164
	ds_read_b128 v[156:159], v164 offset:1024
	ds_read_b128 v[160:163], v164 offset:2048
	ds_read_b128 v[164:167], v164 offset:3072
	ds_read_b128 v[168:171], v180
	ds_read_b128 v[172:175], v180 offset:1024
	ds_read_b128 v[176:179], v180 offset:2048
	ds_read_b128 v[180:183], v180 offset:3072
	s_add_u32 s22, s28, 0xb0000
	s_addc_u32 s23, s29, 0
	s_mov_b32 m0, s40
	ds_read_b128 v[184:187], v155 offset:32768
	ds_read_b128 v[188:191], v155 offset:33792
	ds_read_b128 v[192:195], v155 offset:34816
	ds_read_b128 v[196:199], v155 offset:35840
	ds_read_b128 v[200:203], v155 offset:36864
	ds_read_b128 v[204:207], v155 offset:37888
	ds_read_b128 v[208:211], v155 offset:38912
	ds_read_b128 v[212:215], v155 offset:39936
	global_load_lds_dwordx4 v128, s[22:23]
	s_mov_b32 m0, s41
	s_nop 0
	global_load_lds_dwordx4 v132, s[22:23]
	s_waitcnt vmcnt(8) lgkmcnt(0)
	s_barrier
	s_setprio 1
	v_mfma_f32_16x16x32_bf16 v[124:127], v[146:149], v[184:187], v[124:127]
	v_mfma_f32_16x16x32_bf16 v[120:123], v[160:163], v[184:187], v[120:123]
	v_mfma_f32_16x16x32_bf16 v[116:119], v[146:149], v[192:195], v[116:119]
	v_mfma_f32_16x16x32_bf16 v[112:115], v[160:163], v[192:195], v[112:115]
	v_mfma_f32_16x16x32_bf16 v[92:95], v[146:149], v[200:203], v[92:95]
	v_mfma_f32_16x16x32_bf16 v[88:91], v[160:163], v[200:203], v[88:91]
	v_mfma_f32_16x16x32_bf16 v[76:79], v[146:149], v[208:211], v[76:79]
	v_mfma_f32_16x16x32_bf16 v[72:75], v[160:163], v[208:211], v[72:75]
	v_mfma_f32_16x16x32_bf16 v[124:127], v[156:159], v[188:191], v[124:127]
	v_mfma_f32_16x16x32_bf16 v[120:123], v[164:167], v[188:191], v[120:123]
	v_mfma_f32_16x16x32_bf16 v[116:119], v[156:159], v[196:199], v[116:119]
	v_mfma_f32_16x16x32_bf16 v[112:115], v[164:167], v[196:199], v[112:115]
	v_mfma_f32_16x16x32_bf16 v[92:95], v[156:159], v[204:207], v[92:95]
	v_mfma_f32_16x16x32_bf16 v[88:91], v[164:167], v[204:207], v[88:91]
	v_mfma_f32_16x16x32_bf16 v[76:79], v[156:159], v[212:215], v[76:79]
	v_mfma_f32_16x16x32_bf16 v[72:75], v[164:167], v[212:215], v[72:75]
	v_mfma_f32_16x16x32_bf16 v[108:111], v[168:171], v[184:187], v[108:111]
	v_mfma_f32_16x16x32_bf16 v[104:107], v[176:179], v[184:187], v[104:107]
	v_mfma_f32_16x16x32_bf16 v[100:103], v[168:171], v[192:195], v[100:103]
	v_mfma_f32_16x16x32_bf16 v[96:99], v[176:179], v[192:195], v[96:99]
	v_mfma_f32_16x16x32_bf16 v[84:87], v[168:171], v[200:203], v[84:87]
	v_mfma_f32_16x16x32_bf16 v[80:83], v[176:179], v[200:203], v[80:83]
	v_mfma_f32_16x16x32_bf16 v[68:71], v[168:171], v[208:211], v[68:71]
	v_mfma_f32_16x16x32_bf16 v[64:67], v[176:179], v[208:211], v[64:67]
	v_mfma_f32_16x16x32_bf16 v[108:111], v[172:175], v[188:191], v[108:111]
	v_mfma_f32_16x16x32_bf16 v[104:107], v[180:183], v[188:191], v[104:107]
	v_mfma_f32_16x16x32_bf16 v[100:103], v[172:175], v[196:199], v[100:103]
	v_mfma_f32_16x16x32_bf16 v[96:99], v[180:183], v[196:199], v[96:99]
	v_mfma_f32_16x16x32_bf16 v[84:87], v[172:175], v[204:207], v[84:87]
	v_mfma_f32_16x16x32_bf16 v[80:83], v[180:183], v[204:207], v[80:83]
	v_mfma_f32_16x16x32_bf16 v[68:71], v[172:175], v[212:215], v[68:71]
	v_mfma_f32_16x16x32_bf16 v[64:67], v[180:183], v[212:215], v[64:67]
	s_setprio 0
	s_barrier
	s_add_i32 s22, s57, s37
	v_lshl_add_u64 v[150:151], v[150:151], 0, s[8:9]
	s_mov_b32 m0, s22
	ds_read_b128 v[184:187], v155 offset:49152
	ds_read_b128 v[188:191], v155 offset:50176
	ds_read_b128 v[192:195], v155 offset:51200
	ds_read_b128 v[196:199], v155 offset:52224
	ds_read_b128 v[200:203], v155 offset:53248
	ds_read_b128 v[204:207], v155 offset:54272
	ds_read_b128 v[208:211], v155 offset:55296
	ds_read_b128 v[212:215], v155 offset:56320
	global_load_lds_dwordx4 v[150:151], off
	s_add_i32 m0, s22, 0x2000
	s_add_u32 s22, s26, 0xb0080
	v_lshl_add_u64 v[150:151], v[216:217], 0, s[8:9]
	s_addc_u32 s23, s27, 0
	s_add_i32 s26, s58, s37
	global_load_lds_dwordx4 v[150:151], off
	s_mov_b32 m0, s26
	s_nop 0
	global_load_lds_dwordx4 v130, s[22:23]
	s_add_i32 m0, s26, 0x2000
	s_nop 0
	global_load_lds_dwordx4 v134, s[22:23]
	v_lshl_add_u64 v[150:151], v[218:219], 0, s[8:9]
	s_mov_b32 m0, s43
	s_nop 0
	global_load_lds_dwordx4 v[150:151], off
	v_lshl_add_u64 v[150:151], v[220:221], 0, s[8:9]
	s_mov_b32 m0, s44
	s_nop 0
	global_load_lds_dwordx4 v[150:151], off
	s_waitcnt vmcnt(8) lgkmcnt(0)
	s_barrier
	s_setprio 1
	v_mfma_f32_16x16x32_bf16 v[60:63], v[146:149], v[184:187], v[60:63]
	v_mfma_f32_16x16x32_bf16 v[56:59], v[160:163], v[184:187], v[56:59]
	v_mfma_f32_16x16x32_bf16 v[44:47], v[146:149], v[192:195], v[44:47]
	v_mfma_f32_16x16x32_bf16 v[40:43], v[160:163], v[192:195], v[40:43]
	v_mfma_f32_16x16x32_bf16 v[28:31], v[146:149], v[200:203], v[28:31]
	v_mfma_f32_16x16x32_bf16 v[24:27], v[160:163], v[200:203], v[24:27]
	v_mfma_f32_16x16x32_bf16 v[12:15], v[146:149], v[208:211], v[12:15]
	v_mfma_f32_16x16x32_bf16 v[8:11], v[160:163], v[208:211], v[8:11]
	v_mfma_f32_16x16x32_bf16 v[60:63], v[156:159], v[188:191], v[60:63]
	v_mfma_f32_16x16x32_bf16 v[56:59], v[164:167], v[188:191], v[56:59]
	v_mfma_f32_16x16x32_bf16 v[44:47], v[156:159], v[196:199], v[44:47]
	v_mfma_f32_16x16x32_bf16 v[40:43], v[164:167], v[196:199], v[40:43]
	v_mfma_f32_16x16x32_bf16 v[28:31], v[156:159], v[204:207], v[28:31]
	v_mfma_f32_16x16x32_bf16 v[24:27], v[164:167], v[204:207], v[24:27]
	v_mfma_f32_16x16x32_bf16 v[12:15], v[156:159], v[212:215], v[12:15]
	v_mfma_f32_16x16x32_bf16 v[8:11], v[164:167], v[212:215], v[8:11]
	v_mfma_f32_16x16x32_bf16 v[52:55], v[168:171], v[184:187], v[52:55]
	v_mfma_f32_16x16x32_bf16 v[48:51], v[176:179], v[184:187], v[48:51]
	v_mfma_f32_16x16x32_bf16 v[36:39], v[168:171], v[192:195], v[36:39]
	v_mfma_f32_16x16x32_bf16 v[32:35], v[176:179], v[192:195], v[32:35]
	v_mfma_f32_16x16x32_bf16 v[20:23], v[168:171], v[200:203], v[20:23]
	v_mfma_f32_16x16x32_bf16 v[16:19], v[176:179], v[200:203], v[16:19]
	v_mfma_f32_16x16x32_bf16 v[4:7], v[168:171], v[208:211], v[4:7]
	v_mfma_f32_16x16x32_bf16 v[0:3], v[176:179], v[208:211], v[0:3]
	v_mfma_f32_16x16x32_bf16 v[52:55], v[172:175], v[188:191], v[52:55]
	v_mfma_f32_16x16x32_bf16 v[48:51], v[180:183], v[188:191], v[48:51]
	v_mfma_f32_16x16x32_bf16 v[36:39], v[172:175], v[196:199], v[36:39]
	v_mfma_f32_16x16x32_bf16 v[32:35], v[180:183], v[196:199], v[32:35]
	v_mfma_f32_16x16x32_bf16 v[20:23], v[172:175], v[204:207], v[20:23]
	v_mfma_f32_16x16x32_bf16 v[16:19], v[180:183], v[204:207], v[16:19]
	v_mfma_f32_16x16x32_bf16 v[4:7], v[172:175], v[212:215], v[4:7]
	v_mfma_f32_16x16x32_bf16 v[0:3], v[180:183], v[212:215], v[0:3]
	s_setprio 0
	s_barrier
	s_add_i32 s56, s56, 2
	s_add_u32 s54, s54, 0x100
	s_addc_u32 s55, s55, 0
	s_cmp_gt_u32 s56, 41
	s_mov_b64 s[22:23], s[24:25]
	s_cbranch_scc0 .LBB0_1052
	s_and_b64 vcc, exec, s[10:11]
	s_cbranch_vccz .LBB0_1055
	s_barrier
